# plus: conv v_fma_mix lo/hi pairs fused into v_pk_fma_f32 on cached f32 conversions; FFN gate/up K-loop: first two vmcnt waits after a tile epilogue relaxed by the 8 epilogue stores so they drain under
# speedup vs baseline: 1.1045x; 1.0055x over previous
; #define CONV_LOAD(cc) do { _Pragma("unroll") for (int r = 0; r < 8; ++r) { const int rr = 8 * (cc) + r; if (rr < 38) { const int d = rr - 30; const bool ok = (tl + d >= 0); \
;             const h8 x = *(const GAS h8*)(GLU + (size_t)(tok0 + (ok ? d : -tl)) * 512 + 8 * lane); buf[(cc) & 1][r] = ok ? x : zero8; } } } while (0)
; __device__ __forceinline__ void conv_phase(KP P, LAS unsigned char* lds, int gw, int NGW, int tid, int lane) {
;     ...
;     for (int ch = gw; ch < TT / 8; ch += NGW) {
;         const int tok0 = 8 * ch, tl = tok0 & (SEQ - 1);
;         float acc[8][8];
; #pragma unroll
;         for (int i = 0; i < 8; ++i)
; #pragma unroll
;             for (int c = 0; c < 8; ++c) acc[i][c] = 0.f;
;         h8 buf[2][8];
;     ...
;         CONV_LOAD(0);
; #pragma unroll
;         for (int c = 0; c < 5; ++c) {
;             __builtin_amdgcn_sched_barrier(0);
;             if (c + 1 < 5) CONV_LOAD(c + 1);
.LBB0_351:
	s_add_i32 s26, s24, -7
	s_and_b32 s4, s26, 0x1ff8
	s_cmp_gt_u32 s4, 29
	v_sub_co_u32_e64 v48, vcc, 0, s4
	s_cselect_b64 s[6:7], -1, 0
	s_and_b64 s[8:9], s[6:7], exec
	v_readfirstlane_b32 s5, v48
	s_cselect_b32 s8, 0xffffffe2, s5
	s_add_i32 s8, s26, s8
	s_ashr_i32 s9, s8, 31
	s_lshl_b64 s[8:9], s[8:9], 10
	s_cmp_gt_u32 s4, 28
	v_lshl_add_u64 v[8:9], v[96:97], 0, s[8:9]
	s_cselect_b64 s[8:9], -1, 0
	s_and_b64 s[10:11], s[8:9], exec
	s_cselect_b32 s10, 0xffffffe3, s5
	s_add_i32 s10, s26, s10
	s_ashr_i32 s11, s10, 31
	s_lshl_b64 s[10:11], s[10:11], 10
	s_cmp_gt_u32 s4, 27
	v_lshl_add_u64 v[10:11], v[96:97], 0, s[10:11]
	s_cselect_b64 s[10:11], -1, 0
	s_and_b64 s[12:13], s[10:11], exec
	s_cselect_b32 s12, 0xffffffe4, s5
	s_add_i32 s12, s26, s12
	s_ashr_i32 s13, s12, 31
	s_lshl_b64 s[12:13], s[12:13], 10
	s_cmp_gt_u32 s4, 26
	v_lshl_add_u64 v[16:17], v[96:97], 0, s[12:13]
	s_cselect_b64 s[12:13], -1, 0
	s_and_b64 s[14:15], s[12:13], exec
	s_cselect_b32 s14, 0xffffffe5, s5
	s_add_i32 s14, s26, s14
	s_ashr_i32 s15, s14, 31
	s_lshl_b64 s[14:15], s[14:15], 10
	s_cmp_gt_u32 s4, 25
	v_lshl_add_u64 v[18:19], v[96:97], 0, s[14:15]
	s_cselect_b64 s[14:15], -1, 0
	s_and_b64 s[16:17], s[14:15], exec
	s_cselect_b32 s16, 0xffffffe6, s5
	s_add_i32 s16, s26, s16
	s_ashr_i32 s17, s16, 31
	s_lshl_b64 s[16:17], s[16:17], 10
	s_cmp_gt_u32 s4, 24
	global_load_dwordx4 v[0:3], v[8:9], off
	global_load_dwordx4 v[4:7], v[10:11], off
	s_nop 0
	global_load_dwordx4 v[8:11], v[16:17], off
	global_load_dwordx4 v[12:15], v[18:19], off
	v_lshl_add_u64 v[16:17], v[96:97], 0, s[16:17]
	s_cselect_b64 s[16:17], -1, 0
	s_and_b64 s[18:19], s[16:17], exec
	s_cselect_b32 s18, 0xffffffe7, s5
	s_add_i32 s18, s26, s18
	s_ashr_i32 s19, s18, 31
	s_lshl_b64 s[18:19], s[18:19], 10
	s_cmp_gt_u32 s4, 23
	v_lshl_add_u64 v[20:21], v[96:97], 0, s[18:19]
	s_cselect_b64 s[18:19], -1, 0
	s_and_b64 s[20:21], s[18:19], exec
	s_cselect_b32 s20, 0xffffffe8, s5
	s_add_i32 s20, s26, s20
	s_ashr_i32 s21, s20, 31
	s_lshl_b64 s[20:21], s[20:21], 10
	s_cmp_gt_u32 s4, 22
	v_lshl_add_u64 v[24:25], v[96:97], 0, s[20:21]
	s_cselect_b64 s[20:21], -1, 0
	s_and_b64 s[38:39], s[20:21], exec
	s_cselect_b32 s25, 0xffffffe9, s5
	s_add_i32 s38, s26, s25
	s_ashr_i32 s39, s38, 31
	s_lshl_b64 s[38:39], s[38:39], 10
	v_lshl_add_u64 v[28:29], v[96:97], 0, s[38:39]
	global_load_dwordx4 v[16:19], v[16:17], off
	s_nop 0
	global_load_dwordx4 v[20:23], v[20:21], off
	s_waitcnt vmcnt(5)
	v_cndmask_b32_e64 v32, 0, v3, s[6:7]
	global_load_dwordx4 v[24:27], v[24:25], off
	v_cndmask_b32_e64 v33, 0, v2, s[6:7]
	global_load_dwordx4 v[28:31], v[28:29], off
	v_cndmask_b32_e64 v34, 0, v1, s[6:7]
	v_cndmask_b32_e64 v35, 0, v0, s[6:7]
	s_waitcnt vmcnt(6)
	v_cndmask_b32_e64 v36, 0, v7, s[8:9]
	v_cndmask_b32_e64 v37, 0, v6, s[8:9]
	v_cndmask_b32_e64 v38, 0, v5, s[8:9]
	v_cndmask_b32_e64 v39, 0, v4, s[8:9]
	s_waitcnt vmcnt(5)
	v_cndmask_b32_e64 v44, 0, v11, s[10:11]
	v_cndmask_b32_e64 v45, 0, v10, s[10:11]
	v_cndmask_b32_e64 v46, 0, v9, s[10:11]
	v_cndmask_b32_e64 v47, 0, v8, s[10:11]
	s_waitcnt vmcnt(4)
	v_cndmask_b32_e64 v61, 0, v15, s[12:13]
	v_cndmask_b32_e64 v62, 0, v14, s[12:13]
	v_cndmask_b32_e64 v63, 0, v13, s[12:13]
	v_cndmask_b32_e64 v72, 0, v12, s[12:13]
	s_waitcnt vmcnt(3)
	v_cndmask_b32_e64 v40, 0, v19, s[14:15]
	v_cndmask_b32_e64 v41, 0, v18, s[14:15]
	v_cndmask_b32_e64 v42, 0, v17, s[14:15]
	v_cndmask_b32_e64 v43, 0, v16, s[14:15]
	s_waitcnt vmcnt(2)
	v_cndmask_b32_e64 v57, 0, v23, s[16:17]
	v_cndmask_b32_e64 v58, 0, v22, s[16:17]
	v_cndmask_b32_e64 v59, 0, v21, s[16:17]
	v_cndmask_b32_e64 v60, 0, v20, s[16:17]
	s_waitcnt vmcnt(1)
	v_cndmask_b32_e64 v53, 0, v27, s[18:19]
	v_cndmask_b32_e64 v54, 0, v26, s[18:19]
	v_cndmask_b32_e64 v55, 0, v25, s[18:19]
	v_cndmask_b32_e64 v56, 0, v24, s[18:19]
	s_waitcnt vmcnt(0)
	v_cndmask_b32_e64 v49, 0, v31, s[20:21]
	v_cndmask_b32_e64 v50, 0, v30, s[20:21]
	v_cndmask_b32_e64 v51, 0, v29, s[20:21]
	v_cndmask_b32_e64 v52, 0, v28, s[20:21]
	s_cmp_gt_u32 s4, 21
	s_cselect_b64 s[6:7], -1, 0
	s_and_b64 s[8:9], s[6:7], exec
	s_cselect_b32 s8, 0xffffffea, s5
	s_add_i32 s8, s26, s8
	s_ashr_i32 s9, s8, 31
	s_lshl_b64 s[8:9], s[8:9], 10
	s_cmp_gt_u32 s4, 20
	v_lshl_add_u64 v[0:1], v[96:97], 0, s[8:9]
	s_cselect_b64 s[8:9], -1, 0
	s_and_b64 s[10:11], s[8:9], exec
	s_cselect_b32 s10, 0xffffffeb, s5
	s_add_i32 s10, s26, s10
	s_ashr_i32 s11, s10, 31
	s_lshl_b64 s[10:11], s[10:11], 10
	s_cmp_gt_u32 s4, 19
	v_lshl_add_u64 v[4:5], v[96:97], 0, s[10:11]
	s_cselect_b64 s[10:11], -1, 0
	s_and_b64 s[12:13], s[10:11], exec
	s_cselect_b32 s12, 0xffffffec, s5
	s_add_i32 s12, s26, s12
	s_ashr_i32 s13, s12, 31
	s_lshl_b64 s[12:13], s[12:13], 10
	s_cmp_gt_u32 s4, 18
	v_lshl_add_u64 v[16:17], v[96:97], 0, s[12:13]
	s_cselect_b64 s[12:13], -1, 0
	s_and_b64 s[14:15], s[12:13], exec
	s_cselect_b32 s14, 0xffffffed, s5
	s_add_i32 s14, s26, s14
	s_ashr_i32 s15, s14, 31
	s_lshl_b64 s[14:15], s[14:15], 10
	s_cmp_gt_u32 s4, 17
	v_lshl_add_u64 v[18:19], v[96:97], 0, s[14:15]
	s_cselect_b64 s[14:15], -1, 0
	s_and_b64 s[16:17], s[14:15], exec
	s_cselect_b32 s16, 0xffffffee, s5
	s_add_i32 s16, s26, s16
	s_ashr_i32 s17, s16, 31
	s_lshl_b64 s[16:17], s[16:17], 10
	s_cmp_gt_u32 s4, 16
	global_load_dwordx4 v[0:3], v[0:1], off
	s_nop 0
	global_load_dwordx4 v[4:7], v[4:5], off
	s_nop 0
	global_load_dwordx4 v[8:11], v[16:17], off
	global_load_dwordx4 v[12:15], v[18:19], off
	v_lshl_add_u64 v[16:17], v[96:97], 0, s[16:17]
	s_cselect_b64 s[16:17], -1, 0
	s_and_b64 s[18:19], s[16:17], exec
	s_cselect_b32 s18, 0xffffffef, s5
	s_add_i32 s18, s26, s18
	s_ashr_i32 s19, s18, 31
	s_lshl_b64 s[18:19], s[18:19], 10
	s_cmp_gt_u32 s4, 15
	v_lshl_add_u64 v[20:21], v[96:97], 0, s[18:19]
	s_cselect_b64 s[18:19], -1, 0
	s_and_b64 s[20:21], s[18:19], exec
	s_cselect_b32 s20, -16, s5
	s_add_i32 s20, s26, s20
	s_ashr_i32 s21, s20, 31
	s_lshl_b64 s[20:21], s[20:21], 10
	s_cmp_gt_u32 s4, 14
	v_lshl_add_u64 v[24:25], v[96:97], 0, s[20:21]
	s_cselect_b64 s[20:21], -1, 0
	s_and_b64 s[38:39], s[20:21], exec
	s_cselect_b32 s5, -15, s5
	s_add_i32 s38, s26, s5
	s_ashr_i32 s39, s38, 31
	s_lshl_b64 s[38:39], s[38:39], 10
	v_lshl_add_u64 v[28:29], v[96:97], 0, s[38:39]
	global_load_dwordx4 v[16:19], v[16:17], off
	s_nop 0
	global_load_dwordx4 v[20:23], v[20:21], off
	s_waitcnt vmcnt(5)
; #define LAS __attribute__((address_space(3)))
; #define CONV_LOAD(cc) do { _Pragma("unroll") for (int r = 0; r < 8; ++r) { const int rr = 8 * (cc) + r; if (rr < 38) { const int d = rr - 30; const bool ok = (tl + d >= 0); \
;             const h8 x = *(const GAS h8*)(GLU + (size_t)(tok0 + (ok ? d : -tl)) * 512 + 8 * lane); buf[(cc) & 1][r] = ok ? x : zero8; } } } while (0)
; __device__ __forceinline__ void conv_phase(KP P, LAS unsigned char* lds, int gw, int NGW, int tid, int lane) {
;     ...
;         float acc[8][8];
; #pragma unroll
;         for (int i = 0; i < 8; ++i)
; #pragma unroll
;             for (int c = 0; c < 8; ++c) acc[i][c] = 0.f;
;         h8 buf[2][8];
;     ...
;         CONV_LOAD(0);
; #pragma unroll
;         for (int c = 0; c < 5; ++c) {
;             __builtin_amdgcn_sched_barrier(0);
;             if (c + 1 < 5) CONV_LOAD(c + 1);
;             __builtin_amdgcn_sched_barrier(0);
; #pragma unroll
;             for (int r = 0; r < 8; ++r) {
;                 const int rr = 8 * c + r;
;                 if (rr < 38) {
;                     const u32x4 xw = __builtin_bit_cast(u32x4, buf[c & 1][r]);
; #pragma unroll
;                     for (int i = 0; i < 8; ++i) {
;                         const int j = rr - i;
;                         if (j >= 0 && j <= 30) {
;                             const f32x4 w0 = *(const LAS f32x4*)(cw + j * 512 + 8 * lane), w1 = *(const LAS f32x4*)(cw + j * 512 + 8 * lane + 4);
; #pragma unroll
;                             for (int e = 0; e < 4; ++e) { const float wl = (e < 2) ? w0[2 * e] : w1[2 * e - 4], wh = (e < 2) ? w0[2 * e + 1] : w1[2 * e - 3];
;                                 asm("v_fma_mix_f32 %0, %1, %2, %0 op_sel_hi:[0,1,0]" : "+v"(acc[i][2 * e]) : "v"(wl), "v"(xw[e]));
;                                 asm("v_fma_mix_f32 %0, %1, %2, %0 op_sel:[0,1,0] op_sel_hi:[0,1,0]" : "+v"(acc[i][2 * e + 1]) : "v"(wh), "v"(xw[e])); }
;                         }
;                     }
;                 }
	v_cndmask_b32_e64 v206, 0, v3, s[6:7]
	global_load_dwordx4 v[24:27], v[24:25], off
	v_cndmask_b32_e64 v207, 0, v2, s[6:7]
	global_load_dwordx4 v[28:31], v[28:29], off
	v_cndmask_b32_e64 v208, 0, v1, s[6:7]
	v_cndmask_b32_e64 v209, 0, v0, s[6:7]
	s_waitcnt vmcnt(6)
	v_cndmask_b32_e64 v197, 0, v7, s[8:9]
	v_cndmask_b32_e64 v198, 0, v6, s[8:9]
	v_cndmask_b32_e64 v199, 0, v5, s[8:9]
	v_cndmask_b32_e64 v200, 0, v4, s[8:9]
	s_waitcnt vmcnt(5)
	v_cndmask_b32_e64 v188, 0, v11, s[10:11]
	v_cndmask_b32_e64 v189, 0, v10, s[10:11]
	v_cndmask_b32_e64 v190, 0, v9, s[10:11]
	v_cndmask_b32_e64 v191, 0, v8, s[10:11]
	s_waitcnt vmcnt(4)
	v_cndmask_b32_e64 v184, 0, v15, s[12:13]
	v_cndmask_b32_e64 v185, 0, v14, s[12:13]
	v_cndmask_b32_e64 v186, 0, v13, s[12:13]
	v_cndmask_b32_e64 v187, 0, v12, s[12:13]
	s_waitcnt vmcnt(3)
	v_cndmask_b32_e64 v180, 0, v19, s[14:15]
	v_cndmask_b32_e64 v181, 0, v18, s[14:15]
	v_cndmask_b32_e64 v182, 0, v17, s[14:15]
	v_cndmask_b32_e64 v183, 0, v16, s[14:15]
	s_waitcnt vmcnt(2)
	v_cndmask_b32_e64 v176, 0, v23, s[16:17]
	v_cndmask_b32_e64 v177, 0, v22, s[16:17]
	v_cndmask_b32_e64 v178, 0, v21, s[16:17]
	v_cndmask_b32_e64 v179, 0, v20, s[16:17]
	s_waitcnt vmcnt(1)
	v_cndmask_b32_e64 v68, 0, v27, s[18:19]
	v_cndmask_b32_e64 v69, 0, v26, s[18:19]
	v_cndmask_b32_e64 v70, 0, v25, s[18:19]
	v_cndmask_b32_e64 v71, 0, v24, s[18:19]
	s_waitcnt vmcnt(0)
	v_cndmask_b32_e64 v64, 0, v31, s[20:21]
	v_cndmask_b32_e64 v65, 0, v30, s[20:21]
	v_cndmask_b32_e64 v66, 0, v29, s[20:21]
	v_cndmask_b32_e64 v67, 0, v28, s[20:21]
	ds_read_b128 v[4:7], v166
	ds_read_b128 v[0:3], v166 offset:16
	v_mov_b32_e32 v158, 0
	v_mov_b32_e32 v159, 0
	v_mov_b32_e32 v162, 0
	v_mov_b32_e32 v163, 0
	v_mov_b32_e32 v160, 0
	v_mov_b32_e32 v161, 0
	v_mov_b32_e32 v164, 0
	v_mov_b32_e32 v165, 0
	s_waitcnt lgkmcnt(1)
	v_cvt_f32_f16_sdwa v215, v35 dst_sel:DWORD dst_unused:UNUSED_PAD src0_sel:WORD_1
	v_cvt_f32_f16_e32 v214, v35
	v_pk_fma_f32 v[158:159], v[4:5], v[214:215], v[158:159]
	v_cvt_f32_f16_sdwa v217, v34 dst_sel:DWORD dst_unused:UNUSED_PAD src0_sel:WORD_1
	v_cvt_f32_f16_e32 v216, v34
	v_pk_fma_f32 v[162:163], v[6:7], v[216:217], v[162:163]
	s_waitcnt lgkmcnt(0)
	v_cvt_f32_f16_sdwa v219, v33 dst_sel:DWORD dst_unused:UNUSED_PAD src0_sel:WORD_1
	v_cvt_f32_f16_e32 v218, v33
	v_pk_fma_f32 v[160:161], v[0:1], v[218:219], v[160:161]
	v_cvt_f32_f16_sdwa v221, v32 dst_sel:DWORD dst_unused:UNUSED_PAD src0_sel:WORD_1
	v_cvt_f32_f16_e32 v220, v32
	v_pk_fma_f32 v[164:165], v[2:3], v[220:221], v[164:165]
	v_mov_b32_e32 v150, 0
	v_mov_b32_e32 v151, 0
	v_mov_b32_e32 v154, 0
	v_mov_b32_e32 v155, 0
	v_mov_b32_e32 v152, 0
	v_mov_b32_e32 v153, 0
	v_mov_b32_e32 v156, 0
	v_mov_b32_e32 v157, 0
	ds_read_b128 v[12:15], v166 offset:2048
	ds_read_b128 v[8:11], v166 offset:2064
	s_waitcnt lgkmcnt(1)
	v_cvt_f32_f16_sdwa v223, v39 dst_sel:DWORD dst_unused:UNUSED_PAD src0_sel:WORD_1
	v_cvt_f32_f16_e32 v222, v39
	v_pk_fma_f32 v[158:159], v[12:13], v[222:223], v[158:159]
	v_cvt_f32_f16_sdwa v225, v38 dst_sel:DWORD dst_unused:UNUSED_PAD src0_sel:WORD_1
	v_cvt_f32_f16_e32 v224, v38
	v_pk_fma_f32 v[162:163], v[14:15], v[224:225], v[162:163]
	s_waitcnt lgkmcnt(0)
	v_cvt_f32_f16_sdwa v227, v37 dst_sel:DWORD dst_unused:UNUSED_PAD src0_sel:WORD_1
	v_cvt_f32_f16_e32 v226, v37
	v_pk_fma_f32 v[160:161], v[8:9], v[226:227], v[160:161]
	v_cvt_f32_f16_sdwa v229, v36 dst_sel:DWORD dst_unused:UNUSED_PAD src0_sel:WORD_1
	v_cvt_f32_f16_e32 v228, v36
	v_pk_fma_f32 v[164:165], v[10:11], v[228:229], v[164:165]
	v_pk_fma_f32 v[150:151], v[4:5], v[222:223], v[150:151]
	v_pk_fma_f32 v[154:155], v[6:7], v[224:225], v[154:155]
	v_pk_fma_f32 v[152:153], v[0:1], v[226:227], v[152:153]
	v_pk_fma_f32 v[156:157], v[2:3], v[228:229], v[156:157]
	v_mov_b32_e32 v142, 0
	v_mov_b32_e32 v143, 0
	v_mov_b32_e32 v146, 0
	v_mov_b32_e32 v147, 0
	v_mov_b32_e32 v144, 0
	v_mov_b32_e32 v145, 0
	v_mov_b32_e32 v148, 0
	v_mov_b32_e32 v149, 0
	ds_read_b128 v[20:23], v166 offset:4096
	ds_read_b128 v[16:19], v166 offset:4112
	s_waitcnt lgkmcnt(1)
	v_cvt_f32_f16_sdwa v231, v47 dst_sel:DWORD dst_unused:UNUSED_PAD src0_sel:WORD_1
	v_cvt_f32_f16_e32 v230, v47
	v_pk_fma_f32 v[158:159], v[20:21], v[230:231], v[158:159]
	v_cvt_f32_f16_sdwa v233, v46 dst_sel:DWORD dst_unused:UNUSED_PAD src0_sel:WORD_1
	v_cvt_f32_f16_e32 v232, v46
	v_pk_fma_f32 v[162:163], v[22:23], v[232:233], v[162:163]
	s_waitcnt lgkmcnt(0)
	v_cvt_f32_f16_sdwa v235, v45 dst_sel:DWORD dst_unused:UNUSED_PAD src0_sel:WORD_1
	v_cvt_f32_f16_e32 v234, v45
	v_pk_fma_f32 v[160:161], v[16:17], v[234:235], v[160:161]
	v_cvt_f32_f16_sdwa v237, v44 dst_sel:DWORD dst_unused:UNUSED_PAD src0_sel:WORD_1
	v_cvt_f32_f16_e32 v236, v44
	v_pk_fma_f32 v[164:165], v[18:19], v[236:237], v[164:165]
	v_pk_fma_f32 v[150:151], v[12:13], v[230:231], v[150:151]
	v_pk_fma_f32 v[154:155], v[14:15], v[232:233], v[154:155]
	v_pk_fma_f32 v[152:153], v[8:9], v[234:235], v[152:153]
	v_pk_fma_f32 v[156:157], v[10:11], v[236:237], v[156:157]
	v_pk_fma_f32 v[142:143], v[4:5], v[230:231], v[142:143]
	v_pk_fma_f32 v[146:147], v[6:7], v[232:233], v[146:147]
	v_pk_fma_f32 v[144:145], v[0:1], v[234:235], v[144:145]
	v_pk_fma_f32 v[148:149], v[2:3], v[236:237], v[148:149]
	v_mov_b32_e32 v134, 0
	v_mov_b32_e32 v135, 0
	v_mov_b32_e32 v138, 0
	v_mov_b32_e32 v139, 0
	v_mov_b32_e32 v136, 0
	v_mov_b32_e32 v137, 0
	v_mov_b32_e32 v140, 0
	v_mov_b32_e32 v141, 0
	ds_read_b128 v[28:31], v166 offset:6144
	ds_read_b128 v[24:27], v166 offset:6160
	s_waitcnt lgkmcnt(1)
; #define LAS __attribute__((address_space(3)))
; #define CONV_LOAD(cc) do { _Pragma("unroll") for (int r = 0; r < 8; ++r) { const int rr = 8 * (cc) + r; if (rr < 38) { const int d = rr - 30; const bool ok = (tl + d >= 0); \
;             const h8 x = *(const GAS h8*)(GLU + (size_t)(tok0 + (ok ? d : -tl)) * 512 + 8 * lane); buf[(cc) & 1][r] = ok ? x : zero8; } } } while (0)
; __device__ __forceinline__ void conv_phase(KP P, LAS unsigned char* lds, int gw, int NGW, int tid, int lane) {
;     ...
;         float acc[8][8];
; #pragma unroll
;         for (int i = 0; i < 8; ++i)
; #pragma unroll
;             for (int c = 0; c < 8; ++c) acc[i][c] = 0.f;
;         h8 buf[2][8];
;     ...
;         CONV_LOAD(0);
; #pragma unroll
;         for (int c = 0; c < 5; ++c) {
;             __builtin_amdgcn_sched_barrier(0);
;             if (c + 1 < 5) CONV_LOAD(c + 1);
;             __builtin_amdgcn_sched_barrier(0);
; #pragma unroll
;             for (int r = 0; r < 8; ++r) {
;                 const int rr = 8 * c + r;
;                 if (rr < 38) {
;                     const u32x4 xw = __builtin_bit_cast(u32x4, buf[c & 1][r]);
; #pragma unroll
;                     for (int i = 0; i < 8; ++i) {
;                         const int j = rr - i;
;                         if (j >= 0 && j <= 30) {
;                             const f32x4 w0 = *(const LAS f32x4*)(cw + j * 512 + 8 * lane), w1 = *(const LAS f32x4*)(cw + j * 512 + 8 * lane + 4);
; #pragma unroll
;                             for (int e = 0; e < 4; ++e) { const float wl = (e < 2) ? w0[2 * e] : w1[2 * e - 4], wh = (e < 2) ? w0[2 * e + 1] : w1[2 * e - 3];
;                                 asm("v_fma_mix_f32 %0, %1, %2, %0 op_sel_hi:[0,1,0]" : "+v"(acc[i][2 * e]) : "v"(wl), "v"(xw[e]));
;                                 asm("v_fma_mix_f32 %0, %1, %2, %0 op_sel:[0,1,0] op_sel_hi:[0,1,0]" : "+v"(acc[i][2 * e + 1]) : "v"(wh), "v"(xw[e])); }
;                         }
;                     }
;                 }
	v_cvt_f32_f16_sdwa v239, v72 dst_sel:DWORD dst_unused:UNUSED_PAD src0_sel:WORD_1
	v_cvt_f32_f16_e32 v238, v72
	v_pk_fma_f32 v[158:159], v[28:29], v[238:239], v[158:159]
	v_cvt_f32_f16_sdwa v241, v63 dst_sel:DWORD dst_unused:UNUSED_PAD src0_sel:WORD_1
	v_cvt_f32_f16_e32 v240, v63
	v_pk_fma_f32 v[162:163], v[30:31], v[240:241], v[162:163]
	s_waitcnt lgkmcnt(0)
	v_cvt_f32_f16_sdwa v243, v62 dst_sel:DWORD dst_unused:UNUSED_PAD src0_sel:WORD_1
	v_cvt_f32_f16_e32 v242, v62
	v_pk_fma_f32 v[160:161], v[24:25], v[242:243], v[160:161]
	v_cvt_f32_f16_sdwa v245, v61 dst_sel:DWORD dst_unused:UNUSED_PAD src0_sel:WORD_1
	v_cvt_f32_f16_e32 v244, v61
	v_pk_fma_f32 v[164:165], v[26:27], v[244:245], v[164:165]
	v_pk_fma_f32 v[150:151], v[20:21], v[238:239], v[150:151]
	v_pk_fma_f32 v[154:155], v[22:23], v[240:241], v[154:155]
	v_pk_fma_f32 v[152:153], v[16:17], v[242:243], v[152:153]
	v_pk_fma_f32 v[156:157], v[18:19], v[244:245], v[156:157]
	v_pk_fma_f32 v[142:143], v[12:13], v[238:239], v[142:143]
	v_pk_fma_f32 v[146:147], v[14:15], v[240:241], v[146:147]
	v_pk_fma_f32 v[144:145], v[8:9], v[242:243], v[144:145]
	v_pk_fma_f32 v[148:149], v[10:11], v[244:245], v[148:149]
	v_pk_fma_f32 v[134:135], v[4:5], v[238:239], v[134:135]
	v_pk_fma_f32 v[138:139], v[6:7], v[240:241], v[138:139]
	v_pk_fma_f32 v[136:137], v[0:1], v[242:243], v[136:137]
	v_pk_fma_f32 v[140:141], v[2:3], v[244:245], v[140:141]
	v_mov_b32_e32 v126, 0
	v_mov_b32_e32 v127, 0
	v_mov_b32_e32 v130, 0
	v_mov_b32_e32 v131, 0
	v_mov_b32_e32 v128, 0
	v_mov_b32_e32 v129, 0
	v_mov_b32_e32 v132, 0
	v_mov_b32_e32 v133, 0
	ds_read_b128 v[36:39], v166 offset:8192
	ds_read_b128 v[32:35], v166 offset:8208
	s_waitcnt lgkmcnt(1)
	v_cvt_f32_f16_sdwa v247, v43 dst_sel:DWORD dst_unused:UNUSED_PAD src0_sel:WORD_1
	v_cvt_f32_f16_e32 v246, v43
	v_pk_fma_f32 v[158:159], v[36:37], v[246:247], v[158:159]
	v_cvt_f32_f16_sdwa v229, v42 dst_sel:DWORD dst_unused:UNUSED_PAD src0_sel:WORD_1
	v_cvt_f32_f16_e32 v228, v42
	v_pk_fma_f32 v[162:163], v[38:39], v[228:229], v[162:163]
	s_waitcnt lgkmcnt(0)
	v_cvt_f32_f16_sdwa v227, v41 dst_sel:DWORD dst_unused:UNUSED_PAD src0_sel:WORD_1
	v_cvt_f32_f16_e32 v226, v41
	v_pk_fma_f32 v[160:161], v[32:33], v[226:227], v[160:161]
	v_cvt_f32_f16_sdwa v225, v40 dst_sel:DWORD dst_unused:UNUSED_PAD src0_sel:WORD_1
	v_cvt_f32_f16_e32 v224, v40
	v_pk_fma_f32 v[164:165], v[34:35], v[224:225], v[164:165]
	v_pk_fma_f32 v[150:151], v[28:29], v[246:247], v[150:151]
	v_pk_fma_f32 v[154:155], v[30:31], v[228:229], v[154:155]
	v_pk_fma_f32 v[152:153], v[24:25], v[226:227], v[152:153]
	v_pk_fma_f32 v[156:157], v[26:27], v[224:225], v[156:157]
	v_pk_fma_f32 v[142:143], v[20:21], v[246:247], v[142:143]
	v_pk_fma_f32 v[146:147], v[22:23], v[228:229], v[146:147]
	v_pk_fma_f32 v[144:145], v[16:17], v[226:227], v[144:145]
	v_pk_fma_f32 v[148:149], v[18:19], v[224:225], v[148:149]
	v_pk_fma_f32 v[134:135], v[12:13], v[246:247], v[134:135]
	v_pk_fma_f32 v[138:139], v[14:15], v[228:229], v[138:139]
	v_pk_fma_f32 v[136:137], v[8:9], v[226:227], v[136:137]
	v_pk_fma_f32 v[140:141], v[10:11], v[224:225], v[140:141]
	v_pk_fma_f32 v[126:127], v[4:5], v[246:247], v[126:127]
	v_pk_fma_f32 v[130:131], v[6:7], v[228:229], v[130:131]
	v_pk_fma_f32 v[128:129], v[0:1], v[226:227], v[128:129]
	v_pk_fma_f32 v[132:133], v[2:3], v[224:225], v[132:133]
	v_mov_b32_e32 v118, 0
	v_mov_b32_e32 v119, 0
	v_mov_b32_e32 v122, 0
	v_mov_b32_e32 v123, 0
	v_mov_b32_e32 v120, 0
	v_mov_b32_e32 v121, 0
	v_mov_b32_e32 v124, 0
	v_mov_b32_e32 v125, 0
	ds_read_b128 v[44:47], v166 offset:10240
	ds_read_b128 v[40:43], v166 offset:10256
	s_waitcnt lgkmcnt(1)
	v_cvt_f32_f16_sdwa v223, v60 dst_sel:DWORD dst_unused:UNUSED_PAD src0_sel:WORD_1
	v_cvt_f32_f16_e32 v222, v60
	v_pk_fma_f32 v[158:159], v[44:45], v[222:223], v[158:159]
	v_cvt_f32_f16_sdwa v221, v59 dst_sel:DWORD dst_unused:UNUSED_PAD src0_sel:WORD_1
	v_cvt_f32_f16_e32 v220, v59
	v_pk_fma_f32 v[162:163], v[46:47], v[220:221], v[162:163]
	s_waitcnt lgkmcnt(0)
	v_cvt_f32_f16_sdwa v219, v58 dst_sel:DWORD dst_unused:UNUSED_PAD src0_sel:WORD_1
	v_cvt_f32_f16_e32 v218, v58
	v_pk_fma_f32 v[160:161], v[40:41], v[218:219], v[160:161]
	v_cvt_f32_f16_sdwa v217, v57 dst_sel:DWORD dst_unused:UNUSED_PAD src0_sel:WORD_1
	v_cvt_f32_f16_e32 v216, v57
	v_pk_fma_f32 v[164:165], v[42:43], v[216:217], v[164:165]
	v_pk_fma_f32 v[150:151], v[36:37], v[222:223], v[150:151]
	v_pk_fma_f32 v[154:155], v[38:39], v[220:221], v[154:155]
	v_pk_fma_f32 v[152:153], v[32:33], v[218:219], v[152:153]
	v_pk_fma_f32 v[156:157], v[34:35], v[216:217], v[156:157]
	v_pk_fma_f32 v[142:143], v[28:29], v[222:223], v[142:143]
	v_pk_fma_f32 v[146:147], v[30:31], v[220:221], v[146:147]
	v_pk_fma_f32 v[144:145], v[24:25], v[218:219], v[144:145]
	v_pk_fma_f32 v[148:149], v[26:27], v[216:217], v[148:149]
	v_pk_fma_f32 v[134:135], v[20:21], v[222:223], v[134:135]
	v_pk_fma_f32 v[138:139], v[22:23], v[220:221], v[138:139]
	v_pk_fma_f32 v[136:137], v[16:17], v[218:219], v[136:137]
	v_pk_fma_f32 v[140:141], v[18:19], v[216:217], v[140:141]
	v_pk_fma_f32 v[126:127], v[12:13], v[222:223], v[126:127]
	v_pk_fma_f32 v[130:131], v[14:15], v[220:221], v[130:131]
	v_pk_fma_f32 v[128:129], v[8:9], v[218:219], v[128:129]
	v_pk_fma_f32 v[132:133], v[10:11], v[216:217], v[132:133]
	v_pk_fma_f32 v[118:119], v[4:5], v[222:223], v[118:119]
	v_pk_fma_f32 v[122:123], v[6:7], v[220:221], v[122:123]
	v_pk_fma_f32 v[120:121], v[0:1], v[218:219], v[120:121]
	v_pk_fma_f32 v[124:125], v[2:3], v[216:217], v[124:125]
	v_mov_b32_e32 v102, 0
	v_mov_b32_e32 v103, 0
	v_mov_b32_e32 v108, 0
	v_mov_b32_e32 v109, 0
	v_mov_b32_e32 v106, 0
	v_mov_b32_e32 v107, 0
	v_mov_b32_e32 v114, 0
	v_mov_b32_e32 v115, 0
	ds_read_b128 v[58:61], v166 offset:12288
	ds_read_b128 v[72:75], v166 offset:12304
	s_waitcnt lgkmcnt(1)
; #define LAS __attribute__((address_space(3)))
; #define CONV_LOAD(cc) do { _Pragma("unroll") for (int r = 0; r < 8; ++r) { const int rr = 8 * (cc) + r; if (rr < 38) { const int d = rr - 30; const bool ok = (tl + d >= 0); \
;             const h8 x = *(const GAS h8*)(GLU + (size_t)(tok0 + (ok ? d : -tl)) * 512 + 8 * lane); buf[(cc) & 1][r] = ok ? x : zero8; } } } while (0)
; __device__ __forceinline__ void conv_phase(KP P, LAS unsigned char* lds, int gw, int NGW, int tid, int lane) {
;     ...
;         CONV_LOAD(0);
; #pragma unroll
;         for (int c = 0; c < 5; ++c) {
;             __builtin_amdgcn_sched_barrier(0);
;             if (c + 1 < 5) CONV_LOAD(c + 1);
;             __builtin_amdgcn_sched_barrier(0);
; #pragma unroll
;             for (int r = 0; r < 8; ++r) {
;                 const int rr = 8 * c + r;
;                 if (rr < 38) {
;                     const u32x4 xw = __builtin_bit_cast(u32x4, buf[c & 1][r]);
; #pragma unroll
;                     for (int i = 0; i < 8; ++i) {
;                         const int j = rr - i;
;                         if (j >= 0 && j <= 30) {
;                             const f32x4 w0 = *(const LAS f32x4*)(cw + j * 512 + 8 * lane), w1 = *(const LAS f32x4*)(cw + j * 512 + 8 * lane + 4);
; #pragma unroll
;                             for (int e = 0; e < 4; ++e) { const float wl = (e < 2) ? w0[2 * e] : w1[2 * e - 4], wh = (e < 2) ? w0[2 * e + 1] : w1[2 * e - 3];
;                                 asm("v_fma_mix_f32 %0, %1, %2, %0 op_sel_hi:[0,1,0]" : "+v"(acc[i][2 * e]) : "v"(wl), "v"(xw[e]));
;                                 asm("v_fma_mix_f32 %0, %1, %2, %0 op_sel:[0,1,0] op_sel_hi:[0,1,0]" : "+v"(acc[i][2 * e + 1]) : "v"(wh), "v"(xw[e])); }
;                         }
;                     }
;                 }
	v_cvt_f32_f16_sdwa v215, v56 dst_sel:DWORD dst_unused:UNUSED_PAD src0_sel:WORD_1
	v_cvt_f32_f16_e32 v214, v56
	v_pk_fma_f32 v[158:159], v[58:59], v[214:215], v[158:159]
	v_cvt_f32_f16_sdwa v237, v55 dst_sel:DWORD dst_unused:UNUSED_PAD src0_sel:WORD_1
	v_cvt_f32_f16_e32 v236, v55
	v_pk_fma_f32 v[162:163], v[60:61], v[236:237], v[162:163]
	s_waitcnt lgkmcnt(0)
	v_cvt_f32_f16_sdwa v235, v54 dst_sel:DWORD dst_unused:UNUSED_PAD src0_sel:WORD_1
	v_cvt_f32_f16_e32 v234, v54
	v_pk_fma_f32 v[160:161], v[72:73], v[234:235], v[160:161]
	v_cvt_f32_f16_sdwa v233, v53 dst_sel:DWORD dst_unused:UNUSED_PAD src0_sel:WORD_1
	v_cvt_f32_f16_e32 v232, v53
	v_pk_fma_f32 v[164:165], v[74:75], v[232:233], v[164:165]
	v_pk_fma_f32 v[150:151], v[44:45], v[214:215], v[150:151]
	v_pk_fma_f32 v[154:155], v[46:47], v[236:237], v[154:155]
	v_pk_fma_f32 v[152:153], v[40:41], v[234:235], v[152:153]
	v_pk_fma_f32 v[156:157], v[42:43], v[232:233], v[156:157]
	v_pk_fma_f32 v[142:143], v[36:37], v[214:215], v[142:143]
	v_pk_fma_f32 v[146:147], v[38:39], v[236:237], v[146:147]
	v_pk_fma_f32 v[144:145], v[32:33], v[234:235], v[144:145]
	v_pk_fma_f32 v[148:149], v[34:35], v[232:233], v[148:149]
	v_pk_fma_f32 v[134:135], v[28:29], v[214:215], v[134:135]
	v_pk_fma_f32 v[138:139], v[30:31], v[236:237], v[138:139]
	v_pk_fma_f32 v[136:137], v[24:25], v[234:235], v[136:137]
	v_pk_fma_f32 v[140:141], v[26:27], v[232:233], v[140:141]
	v_pk_fma_f32 v[126:127], v[20:21], v[214:215], v[126:127]
	v_pk_fma_f32 v[130:131], v[22:23], v[236:237], v[130:131]
	v_pk_fma_f32 v[128:129], v[16:17], v[234:235], v[128:129]
	v_pk_fma_f32 v[132:133], v[18:19], v[232:233], v[132:133]
	v_pk_fma_f32 v[118:119], v[12:13], v[214:215], v[118:119]
	v_pk_fma_f32 v[122:123], v[14:15], v[236:237], v[122:123]
	v_pk_fma_f32 v[120:121], v[8:9], v[234:235], v[120:121]
	v_pk_fma_f32 v[124:125], v[10:11], v[232:233], v[124:125]
	v_pk_fma_f32 v[102:103], v[4:5], v[214:215], v[102:103]
	v_pk_fma_f32 v[108:109], v[6:7], v[236:237], v[108:109]
	v_pk_fma_f32 v[106:107], v[0:1], v[234:235], v[106:107]
	v_pk_fma_f32 v[114:115], v[2:3], v[232:233], v[114:115]
	v_mov_b32_e32 v104, 0
	v_mov_b32_e32 v105, 0
	v_mov_b32_e32 v112, 0
	v_mov_b32_e32 v113, 0
	v_mov_b32_e32 v110, 0
	v_mov_b32_e32 v111, 0
	v_mov_b32_e32 v116, 0
	v_mov_b32_e32 v117, 0
	ds_read_b128 v[54:57], v166 offset:14336
	ds_read_b128 v[76:79], v166 offset:14352
	s_waitcnt lgkmcnt(1)
	v_cvt_f32_f16_sdwa v231, v52 dst_sel:DWORD dst_unused:UNUSED_PAD src0_sel:WORD_1
	v_cvt_f32_f16_e32 v230, v52
	v_pk_fma_f32 v[158:159], v[54:55], v[230:231], v[158:159]
	v_cvt_f32_f16_sdwa v225, v51 dst_sel:DWORD dst_unused:UNUSED_PAD src0_sel:WORD_1
	v_cvt_f32_f16_e32 v224, v51
	v_pk_fma_f32 v[162:163], v[56:57], v[224:225], v[162:163]
	s_waitcnt lgkmcnt(0)
	v_cvt_f32_f16_sdwa v227, v50 dst_sel:DWORD dst_unused:UNUSED_PAD src0_sel:WORD_1
	v_cvt_f32_f16_e32 v226, v50
	v_pk_fma_f32 v[160:161], v[76:77], v[226:227], v[160:161]
	v_cvt_f32_f16_sdwa v229, v49 dst_sel:DWORD dst_unused:UNUSED_PAD src0_sel:WORD_1
	v_cvt_f32_f16_e32 v228, v49
	v_pk_fma_f32 v[164:165], v[78:79], v[228:229], v[164:165]
	v_pk_fma_f32 v[150:151], v[58:59], v[230:231], v[150:151]
	v_pk_fma_f32 v[154:155], v[60:61], v[224:225], v[154:155]
	v_pk_fma_f32 v[152:153], v[72:73], v[226:227], v[152:153]
	v_pk_fma_f32 v[156:157], v[74:75], v[228:229], v[156:157]
	v_pk_fma_f32 v[142:143], v[44:45], v[230:231], v[142:143]
	v_pk_fma_f32 v[146:147], v[46:47], v[224:225], v[146:147]
	v_pk_fma_f32 v[144:145], v[40:41], v[226:227], v[144:145]
	v_pk_fma_f32 v[148:149], v[42:43], v[228:229], v[148:149]
	v_pk_fma_f32 v[134:135], v[36:37], v[230:231], v[134:135]
	v_pk_fma_f32 v[138:139], v[38:39], v[224:225], v[138:139]
	v_pk_fma_f32 v[136:137], v[32:33], v[226:227], v[136:137]
	v_pk_fma_f32 v[140:141], v[34:35], v[228:229], v[140:141]
	v_pk_fma_f32 v[126:127], v[28:29], v[230:231], v[126:127]
	v_pk_fma_f32 v[130:131], v[30:31], v[224:225], v[130:131]
	v_pk_fma_f32 v[128:129], v[24:25], v[226:227], v[128:129]
	v_pk_fma_f32 v[132:133], v[26:27], v[228:229], v[132:133]
	v_pk_fma_f32 v[118:119], v[20:21], v[230:231], v[118:119]
	v_pk_fma_f32 v[122:123], v[22:23], v[224:225], v[122:123]
	v_pk_fma_f32 v[120:121], v[16:17], v[226:227], v[120:121]
	v_pk_fma_f32 v[124:125], v[18:19], v[228:229], v[124:125]
	v_pk_fma_f32 v[102:103], v[12:13], v[230:231], v[102:103]
	v_pk_fma_f32 v[108:109], v[14:15], v[224:225], v[108:109]
	v_pk_fma_f32 v[106:107], v[8:9], v[226:227], v[106:107]
	v_pk_fma_f32 v[114:115], v[10:11], v[228:229], v[114:115]
	v_pk_fma_f32 v[104:105], v[4:5], v[230:231], v[104:105]
	v_pk_fma_f32 v[112:113], v[6:7], v[224:225], v[112:113]
	v_pk_fma_f32 v[110:111], v[0:1], v[226:227], v[110:111]
	v_pk_fma_f32 v[116:117], v[2:3], v[228:229], v[116:117]
	s_cmp_gt_u32 s4, 13
	s_cselect_b64 s[6:7], -1, 0
	s_and_b64 s[8:9], s[6:7], exec
	v_readfirstlane_b32 s5, v48
	s_cselect_b32 s8, -14, s5
	s_add_i32 s8, s26, s8
	s_ashr_i32 s9, s8, 31
	s_lshl_b64 s[8:9], s[8:9], 10
	s_cmp_gt_u32 s4, 12
	v_lshl_add_u64 v[0:1], v[96:97], 0, s[8:9]
	s_cselect_b64 s[8:9], -1, 0
	s_and_b64 s[10:11], s[8:9], exec
	s_cselect_b32 s10, -13, s5
	s_add_i32 s10, s26, s10
	s_ashr_i32 s11, s10, 31
	s_lshl_b64 s[10:11], s[10:11], 10
	s_cmp_gt_u32 s4, 11
	v_lshl_add_u64 v[4:5], v[96:97], 0, s[10:11]
	s_cselect_b64 s[10:11], -1, 0
	s_and_b64 s[12:13], s[10:11], exec
	s_cselect_b32 s12, -12, s5
	s_add_i32 s12, s26, s12
	s_ashr_i32 s13, s12, 31
	s_lshl_b64 s[12:13], s[12:13], 10
	s_cmp_gt_u32 s4, 10
	v_lshl_add_u64 v[8:9], v[96:97], 0, s[12:13]
	s_cselect_b64 s[12:13], -1, 0
	s_and_b64 s[14:15], s[12:13], exec
	s_cselect_b32 s14, -11, s5
	s_add_i32 s14, s26, s14
; #define LAS __attribute__((address_space(3)))
; #define CONV_LOAD(cc) do { _Pragma("unroll") for (int r = 0; r < 8; ++r) { const int rr = 8 * (cc) + r; if (rr < 38) { const int d = rr - 30; const bool ok = (tl + d >= 0); \
;             const h8 x = *(const GAS h8*)(GLU + (size_t)(tok0 + (ok ? d : -tl)) * 512 + 8 * lane); buf[(cc) & 1][r] = ok ? x : zero8; } } } while (0)
; __device__ __forceinline__ void conv_phase(KP P, LAS unsigned char* lds, int gw, int NGW, int tid, int lane) {
;     ...
;         CONV_LOAD(0);
; #pragma unroll
;         for (int c = 0; c < 5; ++c) {
;             __builtin_amdgcn_sched_barrier(0);
;             if (c + 1 < 5) CONV_LOAD(c + 1);
;             __builtin_amdgcn_sched_barrier(0);
; #pragma unroll
;             for (int r = 0; r < 8; ++r) {
;                 const int rr = 8 * c + r;
;                 if (rr < 38) {
;                     const u32x4 xw = __builtin_bit_cast(u32x4, buf[c & 1][r]);
; #pragma unroll
;                     for (int i = 0; i < 8; ++i) {
;                         const int j = rr - i;
;                         if (j >= 0 && j <= 30) {
;                             const f32x4 w0 = *(const LAS f32x4*)(cw + j * 512 + 8 * lane), w1 = *(const LAS f32x4*)(cw + j * 512 + 8 * lane + 4);
; #pragma unroll
;                             for (int e = 0; e < 4; ++e) { const float wl = (e < 2) ? w0[2 * e] : w1[2 * e - 4], wh = (e < 2) ? w0[2 * e + 1] : w1[2 * e - 3];
;                                 asm("v_fma_mix_f32 %0, %1, %2, %0 op_sel_hi:[0,1,0]" : "+v"(acc[i][2 * e]) : "v"(wl), "v"(xw[e]));
;                                 asm("v_fma_mix_f32 %0, %1, %2, %0 op_sel:[0,1,0] op_sel_hi:[0,1,0]" : "+v"(acc[i][2 * e + 1]) : "v"(wh), "v"(xw[e])); }
;                         }
;                     }
;                 }
	s_ashr_i32 s15, s14, 31
	s_lshl_b64 s[14:15], s[14:15], 10
	s_cmp_gt_u32 s4, 9
	v_lshl_add_u64 v[12:13], v[96:97], 0, s[14:15]
	s_cselect_b64 s[14:15], -1, 0
	s_and_b64 s[16:17], s[14:15], exec
	s_cselect_b32 s16, -10, s5
	s_add_i32 s16, s26, s16
	s_ashr_i32 s17, s16, 31
	s_lshl_b64 s[16:17], s[16:17], 10
	s_cmp_gt_u32 s4, 8
	v_lshl_add_u64 v[16:17], v[96:97], 0, s[16:17]
	s_cselect_b64 s[16:17], -1, 0
	s_and_b64 s[18:19], s[16:17], exec
	s_cselect_b32 s5, -9, s5
	s_add_i32 s18, s26, s5
	s_ashr_i32 s19, s18, 31
	s_lshl_b64 s[18:19], s[18:19], 10
	s_cmp_eq_u32 s4, 0
	v_lshl_add_u64 v[20:21], v[96:97], 0, s[18:19]
	s_cselect_b64 s[18:19], -1, 0
	s_and_b64 s[4:5], s[18:19], exec
	s_cselect_b32 s27, 0, -8
	s_cselect_b32 s33, 0, -7
	s_cselect_b32 s25, 0, -6
	s_cselect_b32 s21, 0, -5
	s_cselect_b32 s20, 0, -4
	s_cselect_b32 s5, 0, -3
	s_cselect_b32 s4, 0, -2
	s_add_i32 s38, s26, s27
	s_ashr_i32 s39, s38, 31
	s_lshl_b64 s[38:39], s[38:39], 10
	v_lshl_add_u64 v[24:25], v[96:97], 0, s[38:39]
	s_add_i32 s38, s26, s33
	s_ashr_i32 s39, s38, 31
	s_lshl_b64 s[38:39], s[38:39], 10
	v_lshl_add_u64 v[28:29], v[96:97], 0, s[38:39]
	global_load_dwordx4 v[0:3], v[0:1], off
	s_nop 0
	global_load_dwordx4 v[4:7], v[4:5], off
	s_nop 0
	global_load_dwordx4 v[8:11], v[8:9], off
	s_nop 0
	global_load_dwordx4 v[12:15], v[12:13], off
	s_nop 0
	global_load_dwordx4 v[16:19], v[16:17], off
	s_nop 0
	global_load_dwordx4 v[20:23], v[20:21], off
	s_waitcnt vmcnt(5)
	v_cndmask_b32_e64 v201, 0, v3, s[6:7]
	global_load_dwordx4 v[24:27], v[24:25], off
	v_cndmask_b32_e64 v202, 0, v2, s[6:7]
	global_load_dwordx4 v[28:31], v[28:29], off
	v_cndmask_b32_e64 v203, 0, v1, s[6:7]
	v_cndmask_b32_e64 v205, 0, v0, s[6:7]
	s_waitcnt vmcnt(6)
	v_cndmask_b32_e64 v192, 0, v7, s[8:9]
	v_cndmask_b32_e64 v193, 0, v6, s[8:9]
	v_cndmask_b32_e64 v194, 0, v5, s[8:9]
	v_cndmask_b32_e64 v196, 0, v4, s[8:9]
	s_waitcnt vmcnt(5)
	v_cndmask_b32_e64 v92, 0, v11, s[10:11]
	v_cndmask_b32_e64 v93, 0, v10, s[10:11]
	v_cndmask_b32_e64 v94, 0, v9, s[10:11]
	v_cndmask_b32_e64 v95, 0, v8, s[10:11]
	s_waitcnt vmcnt(4)
	v_cndmask_b32_e64 v88, 0, v15, s[12:13]
	v_cndmask_b32_e64 v89, 0, v14, s[12:13]
	v_cndmask_b32_e64 v90, 0, v13, s[12:13]
	v_cndmask_b32_e64 v91, 0, v12, s[12:13]
	s_waitcnt vmcnt(3)
	v_cndmask_b32_e64 v84, 0, v19, s[14:15]
	v_cndmask_b32_e64 v85, 0, v18, s[14:15]
	v_cndmask_b32_e64 v86, 0, v17, s[14:15]
	v_cndmask_b32_e64 v87, 0, v16, s[14:15]
	s_waitcnt vmcnt(2)
	v_cndmask_b32_e64 v80, 0, v23, s[16:17]
	v_cndmask_b32_e64 v81, 0, v22, s[16:17]
	v_cndmask_b32_e64 v82, 0, v21, s[16:17]
	v_cndmask_b32_e64 v83, 0, v20, s[16:17]
	s_waitcnt vmcnt(1)
	v_cndmask_b32_e64 v76, v27, 0, s[18:19]
	v_cndmask_b32_e64 v77, v26, 0, s[18:19]
	v_cndmask_b32_e64 v78, v25, 0, s[18:19]
	v_cndmask_b32_e64 v79, v24, 0, s[18:19]
	s_waitcnt vmcnt(0)
	v_cndmask_b32_e64 v72, v31, 0, s[18:19]
	v_cndmask_b32_e64 v73, v30, 0, s[18:19]
	v_cndmask_b32_e64 v74, v29, 0, s[18:19]
	v_cndmask_b32_e64 v75, v28, 0, s[18:19]
	ds_read_b128 v[4:7], v166 offset:16384
	ds_read_b128 v[0:3], v166 offset:16400
	ds_read_b128 v[12:15], v166 offset:14336
	ds_read_b128 v[8:11], v166 offset:14352
	s_waitcnt lgkmcnt(1)
	v_fma_mix_f32 v150, v12, v209, v150 op_sel_hi:[0,1,0]
	v_cvt_f32_f16_sdwa v247, v209 dst_sel:DWORD dst_unused:UNUSED_PAD src0_sel:WORD_1
	v_cvt_f32_f16_e32 v246, v209
	v_pk_fma_f32 v[158:159], v[4:5], v[246:247], v[158:159]
	v_cvt_f32_f16_sdwa v219, v208 dst_sel:DWORD dst_unused:UNUSED_PAD src0_sel:WORD_1
	v_cvt_f32_f16_e32 v218, v208
	v_pk_fma_f32 v[162:163], v[6:7], v[218:219], v[162:163]
	v_cvt_f32_f16_sdwa v221, v207 dst_sel:DWORD dst_unused:UNUSED_PAD src0_sel:WORD_1
	v_cvt_f32_f16_e32 v220, v207
	v_pk_fma_f32 v[160:161], v[0:1], v[220:221], v[160:161]
	v_cvt_f32_f16_sdwa v223, v206 dst_sel:DWORD dst_unused:UNUSED_PAD src0_sel:WORD_1
	v_cvt_f32_f16_e32 v222, v206
	v_pk_fma_f32 v[164:165], v[2:3], v[222:223], v[164:165]
	v_fma_mix_f32 v151, v13, v209, v151 op_sel:[0,1,0] op_sel_hi:[0,1,0]
	v_pk_fma_f32 v[154:155], v[14:15], v[218:219], v[154:155]
	s_waitcnt lgkmcnt(0)
	v_fma_mix_f32 v152, v8, v207, v152 op_sel_hi:[0,1,0]
	ds_read_b128 v[28:31], v166 offset:12288
	ds_read_b128 v[24:27], v166 offset:12304
	v_fma_mix_f32 v153, v9, v207, v153 op_sel:[0,1,0] op_sel_hi:[0,1,0]
	v_pk_fma_f32 v[156:157], v[10:11], v[222:223], v[156:157]
	s_waitcnt lgkmcnt(1)
	v_pk_fma_f32 v[142:143], v[28:29], v[246:247], v[142:143]
	v_pk_fma_f32 v[146:147], v[30:31], v[218:219], v[146:147]
	s_waitcnt lgkmcnt(0)
	v_fma_mix_f32 v144, v24, v207, v144 op_sel_hi:[0,1,0]
	ds_read_b128 v[44:47], v166 offset:10240
	ds_read_b128 v[40:43], v166 offset:10256
	v_fma_mix_f32 v145, v25, v207, v145 op_sel:[0,1,0] op_sel_hi:[0,1,0]
	v_pk_fma_f32 v[148:149], v[26:27], v[222:223], v[148:149]
	s_waitcnt lgkmcnt(1)
	v_pk_fma_f32 v[134:135], v[44:45], v[246:247], v[134:135]
	v_pk_fma_f32 v[138:139], v[46:47], v[218:219], v[138:139]
	s_waitcnt lgkmcnt(0)
	v_fma_mix_f32 v136, v40, v207, v136 op_sel_hi:[0,1,0]
	ds_read_b128 v[60:63], v166 offset:8192
	ds_read_b128 v[56:59], v166 offset:8208
	v_fma_mix_f32 v137, v41, v207, v137 op_sel:[0,1,0] op_sel_hi:[0,1,0]
	v_pk_fma_f32 v[140:141], v[42:43], v[222:223], v[140:141]
	s_waitcnt lgkmcnt(1)
	v_pk_fma_f32 v[126:127], v[60:61], v[246:247], v[126:127]
	v_pk_fma_f32 v[130:131], v[62:63], v[218:219], v[130:131]
	s_waitcnt lgkmcnt(0)
	v_fma_mix_f32 v128, v56, v207, v128 op_sel_hi:[0,1,0]
	ds_read_b128 v[52:55], v166 offset:6144
	ds_read_b128 v[48:51], v166 offset:6160
	v_fma_mix_f32 v129, v57, v207, v129 op_sel:[0,1,0] op_sel_hi:[0,1,0]
	v_pk_fma_f32 v[132:133], v[58:59], v[222:223], v[132:133]
	s_waitcnt lgkmcnt(1)
; #define LAS __attribute__((address_space(3)))
; #define CONV_LOAD(cc) do { _Pragma("unroll") for (int r = 0; r < 8; ++r) { const int rr = 8 * (cc) + r; if (rr < 38) { const int d = rr - 30; const bool ok = (tl + d >= 0); \
;             const h8 x = *(const GAS h8*)(GLU + (size_t)(tok0 + (ok ? d : -tl)) * 512 + 8 * lane); buf[(cc) & 1][r] = ok ? x : zero8; } } } while (0)
; __device__ __forceinline__ void conv_phase(KP P, LAS unsigned char* lds, int gw, int NGW, int tid, int lane) {
;     ...
;         float acc[8][8];
; #pragma unroll
;         for (int i = 0; i < 8; ++i)
; #pragma unroll
;             for (int c = 0; c < 8; ++c) acc[i][c] = 0.f;
;         h8 buf[2][8];
;     ...
;         CONV_LOAD(0);
; #pragma unroll
;         for (int c = 0; c < 5; ++c) {
;             __builtin_amdgcn_sched_barrier(0);
;             if (c + 1 < 5) CONV_LOAD(c + 1);
;             __builtin_amdgcn_sched_barrier(0);
; #pragma unroll
;             for (int r = 0; r < 8; ++r) {
;                 const int rr = 8 * c + r;
;                 if (rr < 38) {
;                     const u32x4 xw = __builtin_bit_cast(u32x4, buf[c & 1][r]);
; #pragma unroll
;                     for (int i = 0; i < 8; ++i) {
;                         const int j = rr - i;
;                         if (j >= 0 && j <= 30) {
;                             const f32x4 w0 = *(const LAS f32x4*)(cw + j * 512 + 8 * lane), w1 = *(const LAS f32x4*)(cw + j * 512 + 8 * lane + 4);
; #pragma unroll
;                             for (int e = 0; e < 4; ++e) { const float wl = (e < 2) ? w0[2 * e] : w1[2 * e - 4], wh = (e < 2) ? w0[2 * e + 1] : w1[2 * e - 3];
;                                 asm("v_fma_mix_f32 %0, %1, %2, %0 op_sel_hi:[0,1,0]" : "+v"(acc[i][2 * e]) : "v"(wl), "v"(xw[e]));
;                                 asm("v_fma_mix_f32 %0, %1, %2, %0 op_sel:[0,1,0] op_sel_hi:[0,1,0]" : "+v"(acc[i][2 * e + 1]) : "v"(wh), "v"(xw[e])); }
;                         }
;                     }
;                 }
	v_pk_fma_f32 v[118:119], v[52:53], v[246:247], v[118:119]
	v_pk_fma_f32 v[122:123], v[54:55], v[218:219], v[122:123]
	s_waitcnt lgkmcnt(0)
	v_fma_mix_f32 v120, v48, v207, v120 op_sel_hi:[0,1,0]
	ds_read_b128 v[36:39], v166 offset:4096
	ds_read_b128 v[32:35], v166 offset:4112
	v_fma_mix_f32 v121, v49, v207, v121 op_sel:[0,1,0] op_sel_hi:[0,1,0]
	v_pk_fma_f32 v[124:125], v[50:51], v[222:223], v[124:125]
	s_waitcnt lgkmcnt(1)
	v_pk_fma_f32 v[102:103], v[36:37], v[246:247], v[102:103]
	v_pk_fma_f32 v[108:109], v[38:39], v[218:219], v[108:109]
	s_waitcnt lgkmcnt(0)
	v_fma_mix_f32 v106, v32, v207, v106 op_sel_hi:[0,1,0]
	ds_read_b128 v[16:19], v166 offset:2048
	ds_read_b128 v[210:213], v166 offset:2064
	v_fma_mix_f32 v107, v33, v207, v107 op_sel:[0,1,0] op_sel_hi:[0,1,0]
	v_pk_fma_f32 v[114:115], v[34:35], v[222:223], v[114:115]
	s_waitcnt lgkmcnt(1)
	v_pk_fma_f32 v[104:105], v[16:17], v[246:247], v[104:105]
	v_pk_fma_f32 v[112:113], v[18:19], v[218:219], v[112:113]
	s_waitcnt lgkmcnt(0)
	v_pk_fma_f32 v[110:111], v[210:211], v[220:221], v[110:111]
	v_pk_fma_f32 v[116:117], v[212:213], v[222:223], v[116:117]
	ds_read_b128 v[20:23], v166 offset:18432
	ds_read_b128 v[16:19], v166 offset:18448
	s_waitcnt lgkmcnt(1)
	v_cvt_f32_f16_sdwa v245, v200 dst_sel:DWORD dst_unused:UNUSED_PAD src0_sel:WORD_1
	v_cvt_f32_f16_e32 v244, v200
	v_pk_fma_f32 v[158:159], v[20:21], v[244:245], v[158:159]
	v_cvt_f32_f16_sdwa v239, v199 dst_sel:DWORD dst_unused:UNUSED_PAD src0_sel:WORD_1
	v_cvt_f32_f16_e32 v238, v199
	v_pk_fma_f32 v[162:163], v[22:23], v[238:239], v[162:163]
	s_waitcnt lgkmcnt(0)
	v_cvt_f32_f16_sdwa v235, v198 dst_sel:DWORD dst_unused:UNUSED_PAD src0_sel:WORD_1
	v_cvt_f32_f16_e32 v234, v198
	v_pk_fma_f32 v[160:161], v[16:17], v[234:235], v[160:161]
	v_cvt_f32_f16_sdwa v237, v197 dst_sel:DWORD dst_unused:UNUSED_PAD src0_sel:WORD_1
	v_cvt_f32_f16_e32 v236, v197
	v_pk_fma_f32 v[164:165], v[18:19], v[236:237], v[164:165]
	v_pk_fma_f32 v[150:151], v[4:5], v[244:245], v[150:151]
	v_pk_fma_f32 v[154:155], v[6:7], v[238:239], v[154:155]
	v_pk_fma_f32 v[152:153], v[0:1], v[234:235], v[152:153]
	v_pk_fma_f32 v[156:157], v[2:3], v[236:237], v[156:157]
	v_pk_fma_f32 v[142:143], v[12:13], v[244:245], v[142:143]
	v_pk_fma_f32 v[146:147], v[14:15], v[238:239], v[146:147]
	v_pk_fma_f32 v[144:145], v[8:9], v[234:235], v[144:145]
	v_pk_fma_f32 v[148:149], v[10:11], v[236:237], v[148:149]
	v_pk_fma_f32 v[134:135], v[28:29], v[244:245], v[134:135]
	v_pk_fma_f32 v[138:139], v[30:31], v[238:239], v[138:139]
	v_pk_fma_f32 v[136:137], v[24:25], v[234:235], v[136:137]
	v_pk_fma_f32 v[140:141], v[26:27], v[236:237], v[140:141]
	v_pk_fma_f32 v[126:127], v[44:45], v[244:245], v[126:127]
	v_pk_fma_f32 v[130:131], v[46:47], v[238:239], v[130:131]
	v_pk_fma_f32 v[128:129], v[40:41], v[234:235], v[128:129]
	v_pk_fma_f32 v[132:133], v[42:43], v[236:237], v[132:133]
	v_pk_fma_f32 v[118:119], v[60:61], v[244:245], v[118:119]
	v_pk_fma_f32 v[122:123], v[62:63], v[238:239], v[122:123]
	v_pk_fma_f32 v[120:121], v[56:57], v[234:235], v[120:121]
	v_pk_fma_f32 v[124:125], v[58:59], v[236:237], v[124:125]
	v_pk_fma_f32 v[102:103], v[52:53], v[244:245], v[102:103]
	v_pk_fma_f32 v[108:109], v[54:55], v[238:239], v[108:109]
	v_pk_fma_f32 v[106:107], v[48:49], v[234:235], v[106:107]
	v_pk_fma_f32 v[114:115], v[50:51], v[236:237], v[114:115]
	v_pk_fma_f32 v[104:105], v[36:37], v[244:245], v[104:105]
	v_pk_fma_f32 v[112:113], v[38:39], v[238:239], v[112:113]
	v_pk_fma_f32 v[110:111], v[32:33], v[234:235], v[110:111]
	v_pk_fma_f32 v[116:117], v[34:35], v[236:237], v[116:117]
	ds_read_b128 v[36:39], v166 offset:20480
	ds_read_b128 v[32:35], v166 offset:20496
	s_waitcnt lgkmcnt(1)
	v_cvt_f32_f16_sdwa v215, v191 dst_sel:DWORD dst_unused:UNUSED_PAD src0_sel:WORD_1
	v_cvt_f32_f16_e32 v214, v191
	v_pk_fma_f32 v[158:159], v[36:37], v[214:215], v[158:159]
	v_cvt_f32_f16_sdwa v217, v190 dst_sel:DWORD dst_unused:UNUSED_PAD src0_sel:WORD_1
	v_cvt_f32_f16_e32 v216, v190
	v_pk_fma_f32 v[162:163], v[38:39], v[216:217], v[162:163]
	s_waitcnt lgkmcnt(0)
	v_cvt_f32_f16_sdwa v243, v189 dst_sel:DWORD dst_unused:UNUSED_PAD src0_sel:WORD_1
	v_cvt_f32_f16_e32 v242, v189
	v_pk_fma_f32 v[160:161], v[32:33], v[242:243], v[160:161]
	v_cvt_f32_f16_sdwa v241, v188 dst_sel:DWORD dst_unused:UNUSED_PAD src0_sel:WORD_1
	v_cvt_f32_f16_e32 v240, v188
	v_pk_fma_f32 v[164:165], v[34:35], v[240:241], v[164:165]
	v_pk_fma_f32 v[150:151], v[20:21], v[214:215], v[150:151]
	v_pk_fma_f32 v[154:155], v[22:23], v[216:217], v[154:155]
	v_pk_fma_f32 v[152:153], v[16:17], v[242:243], v[152:153]
	v_pk_fma_f32 v[156:157], v[18:19], v[240:241], v[156:157]
	v_pk_fma_f32 v[142:143], v[4:5], v[214:215], v[142:143]
	v_pk_fma_f32 v[146:147], v[6:7], v[216:217], v[146:147]
	v_pk_fma_f32 v[144:145], v[0:1], v[242:243], v[144:145]
	v_pk_fma_f32 v[148:149], v[2:3], v[240:241], v[148:149]
	v_pk_fma_f32 v[134:135], v[12:13], v[214:215], v[134:135]
	v_pk_fma_f32 v[138:139], v[14:15], v[216:217], v[138:139]
	v_pk_fma_f32 v[136:137], v[8:9], v[242:243], v[136:137]
	v_pk_fma_f32 v[140:141], v[10:11], v[240:241], v[140:141]
	v_pk_fma_f32 v[126:127], v[28:29], v[214:215], v[126:127]
	v_pk_fma_f32 v[130:131], v[30:31], v[216:217], v[130:131]
	v_pk_fma_f32 v[128:129], v[24:25], v[242:243], v[128:129]
	v_pk_fma_f32 v[132:133], v[26:27], v[240:241], v[132:133]
	v_pk_fma_f32 v[118:119], v[44:45], v[214:215], v[118:119]
	v_pk_fma_f32 v[122:123], v[46:47], v[216:217], v[122:123]
	v_pk_fma_f32 v[120:121], v[40:41], v[242:243], v[120:121]
	v_pk_fma_f32 v[124:125], v[42:43], v[240:241], v[124:125]
	v_pk_fma_f32 v[102:103], v[60:61], v[214:215], v[102:103]
	v_pk_fma_f32 v[108:109], v[62:63], v[216:217], v[108:109]
	v_pk_fma_f32 v[106:107], v[56:57], v[242:243], v[106:107]
	v_pk_fma_f32 v[114:115], v[58:59], v[240:241], v[114:115]
	v_pk_fma_f32 v[104:105], v[52:53], v[214:215], v[104:105]
	v_pk_fma_f32 v[112:113], v[54:55], v[216:217], v[112:113]
	v_pk_fma_f32 v[110:111], v[48:49], v[242:243], v[110:111]
	v_pk_fma_f32 v[116:117], v[50:51], v[240:241], v[116:117]
	ds_read_b128 v[52:55], v166 offset:22528
	ds_read_b128 v[48:51], v166 offset:22544
	s_waitcnt lgkmcnt(1)
; #define LAS __attribute__((address_space(3)))
; #define CONV_LOAD(cc) do { _Pragma("unroll") for (int r = 0; r < 8; ++r) { const int rr = 8 * (cc) + r; if (rr < 38) { const int d = rr - 30; const bool ok = (tl + d >= 0); \
;             const h8 x = *(const GAS h8*)(GLU + (size_t)(tok0 + (ok ? d : -tl)) * 512 + 8 * lane); buf[(cc) & 1][r] = ok ? x : zero8; } } } while (0)
; __device__ __forceinline__ void conv_phase(KP P, LAS unsigned char* lds, int gw, int NGW, int tid, int lane) {
;     ...
;         float acc[8][8];
; #pragma unroll
;         for (int i = 0; i < 8; ++i)
; #pragma unroll
;             for (int c = 0; c < 8; ++c) acc[i][c] = 0.f;
;         h8 buf[2][8];
;     ...
;         CONV_LOAD(0);
; #pragma unroll
;         for (int c = 0; c < 5; ++c) {
;             __builtin_amdgcn_sched_barrier(0);
;             if (c + 1 < 5) CONV_LOAD(c + 1);
;             __builtin_amdgcn_sched_barrier(0);
; #pragma unroll
;             for (int r = 0; r < 8; ++r) {
;                 const int rr = 8 * c + r;
;                 if (rr < 38) {
;                     const u32x4 xw = __builtin_bit_cast(u32x4, buf[c & 1][r]);
; #pragma unroll
;                     for (int i = 0; i < 8; ++i) {
;                         const int j = rr - i;
;                         if (j >= 0 && j <= 30) {
;                             const f32x4 w0 = *(const LAS f32x4*)(cw + j * 512 + 8 * lane), w1 = *(const LAS f32x4*)(cw + j * 512 + 8 * lane + 4);
; #pragma unroll
;                             for (int e = 0; e < 4; ++e) { const float wl = (e < 2) ? w0[2 * e] : w1[2 * e - 4], wh = (e < 2) ? w0[2 * e + 1] : w1[2 * e - 3];
;                                 asm("v_fma_mix_f32 %0, %1, %2, %0 op_sel_hi:[0,1,0]" : "+v"(acc[i][2 * e]) : "v"(wl), "v"(xw[e]));
;                                 asm("v_fma_mix_f32 %0, %1, %2, %0 op_sel:[0,1,0] op_sel_hi:[0,1,0]" : "+v"(acc[i][2 * e + 1]) : "v"(wh), "v"(xw[e])); }
;                         }
;                     }
;                 }
	v_cvt_f32_f16_sdwa v231, v187 dst_sel:DWORD dst_unused:UNUSED_PAD src0_sel:WORD_1
	v_cvt_f32_f16_e32 v230, v187
	v_pk_fma_f32 v[158:159], v[52:53], v[230:231], v[158:159]
	v_cvt_f32_f16_sdwa v233, v186 dst_sel:DWORD dst_unused:UNUSED_PAD src0_sel:WORD_1
	v_cvt_f32_f16_e32 v232, v186
	v_pk_fma_f32 v[162:163], v[54:55], v[232:233], v[162:163]
	s_waitcnt lgkmcnt(0)
	v_cvt_f32_f16_sdwa v229, v185 dst_sel:DWORD dst_unused:UNUSED_PAD src0_sel:WORD_1
	v_cvt_f32_f16_e32 v228, v185
	v_pk_fma_f32 v[160:161], v[48:49], v[228:229], v[160:161]
	v_cvt_f32_f16_sdwa v227, v184 dst_sel:DWORD dst_unused:UNUSED_PAD src0_sel:WORD_1
	v_cvt_f32_f16_e32 v226, v184
	v_pk_fma_f32 v[164:165], v[50:51], v[226:227], v[164:165]
	v_pk_fma_f32 v[150:151], v[36:37], v[230:231], v[150:151]
	v_pk_fma_f32 v[154:155], v[38:39], v[232:233], v[154:155]
	v_pk_fma_f32 v[152:153], v[32:33], v[228:229], v[152:153]
	v_pk_fma_f32 v[156:157], v[34:35], v[226:227], v[156:157]
	v_pk_fma_f32 v[142:143], v[20:21], v[230:231], v[142:143]
	v_pk_fma_f32 v[146:147], v[22:23], v[232:233], v[146:147]
	v_pk_fma_f32 v[144:145], v[16:17], v[228:229], v[144:145]
	v_pk_fma_f32 v[148:149], v[18:19], v[226:227], v[148:149]
	v_pk_fma_f32 v[134:135], v[4:5], v[230:231], v[134:135]
	v_pk_fma_f32 v[138:139], v[6:7], v[232:233], v[138:139]
	v_pk_fma_f32 v[136:137], v[0:1], v[228:229], v[136:137]
	v_pk_fma_f32 v[140:141], v[2:3], v[226:227], v[140:141]
	v_pk_fma_f32 v[126:127], v[12:13], v[230:231], v[126:127]
	v_pk_fma_f32 v[130:131], v[14:15], v[232:233], v[130:131]
	v_pk_fma_f32 v[128:129], v[8:9], v[228:229], v[128:129]
	v_pk_fma_f32 v[132:133], v[10:11], v[226:227], v[132:133]
	v_pk_fma_f32 v[118:119], v[28:29], v[230:231], v[118:119]
	v_pk_fma_f32 v[122:123], v[30:31], v[232:233], v[122:123]
	v_pk_fma_f32 v[120:121], v[24:25], v[228:229], v[120:121]
	v_pk_fma_f32 v[124:125], v[26:27], v[226:227], v[124:125]
	v_pk_fma_f32 v[102:103], v[44:45], v[230:231], v[102:103]
	v_pk_fma_f32 v[108:109], v[46:47], v[232:233], v[108:109]
	v_pk_fma_f32 v[106:107], v[40:41], v[228:229], v[106:107]
	v_pk_fma_f32 v[114:115], v[42:43], v[226:227], v[114:115]
	v_pk_fma_f32 v[104:105], v[60:61], v[230:231], v[104:105]
	v_pk_fma_f32 v[112:113], v[62:63], v[232:233], v[112:113]
	v_pk_fma_f32 v[110:111], v[56:57], v[228:229], v[110:111]
	v_pk_fma_f32 v[116:117], v[58:59], v[226:227], v[116:117]
	ds_read_b128 v[60:63], v166 offset:24576
	ds_read_b128 v[56:59], v166 offset:24592
	s_waitcnt lgkmcnt(1)
	v_cvt_f32_f16_sdwa v225, v183 dst_sel:DWORD dst_unused:UNUSED_PAD src0_sel:WORD_1
	v_cvt_f32_f16_e32 v224, v183
	v_pk_fma_f32 v[158:159], v[60:61], v[224:225], v[158:159]
	v_cvt_f32_f16_sdwa v247, v182 dst_sel:DWORD dst_unused:UNUSED_PAD src0_sel:WORD_1
	v_cvt_f32_f16_e32 v246, v182
	v_pk_fma_f32 v[162:163], v[62:63], v[246:247], v[162:163]
	s_waitcnt lgkmcnt(0)
	v_cvt_f32_f16_sdwa v219, v181 dst_sel:DWORD dst_unused:UNUSED_PAD src0_sel:WORD_1
	v_cvt_f32_f16_e32 v218, v181
	v_pk_fma_f32 v[160:161], v[56:57], v[218:219], v[160:161]
	v_cvt_f32_f16_sdwa v221, v180 dst_sel:DWORD dst_unused:UNUSED_PAD src0_sel:WORD_1
	v_cvt_f32_f16_e32 v220, v180
	v_pk_fma_f32 v[164:165], v[58:59], v[220:221], v[164:165]
	v_pk_fma_f32 v[150:151], v[52:53], v[224:225], v[150:151]
	v_pk_fma_f32 v[154:155], v[54:55], v[246:247], v[154:155]
	v_pk_fma_f32 v[152:153], v[48:49], v[218:219], v[152:153]
	v_pk_fma_f32 v[156:157], v[50:51], v[220:221], v[156:157]
	v_pk_fma_f32 v[142:143], v[36:37], v[224:225], v[142:143]
	v_pk_fma_f32 v[146:147], v[38:39], v[246:247], v[146:147]
	v_pk_fma_f32 v[144:145], v[32:33], v[218:219], v[144:145]
	v_pk_fma_f32 v[148:149], v[34:35], v[220:221], v[148:149]
	v_pk_fma_f32 v[134:135], v[20:21], v[224:225], v[134:135]
	v_pk_fma_f32 v[138:139], v[22:23], v[246:247], v[138:139]
	v_pk_fma_f32 v[136:137], v[16:17], v[218:219], v[136:137]
	v_pk_fma_f32 v[140:141], v[18:19], v[220:221], v[140:141]
	v_pk_fma_f32 v[126:127], v[4:5], v[224:225], v[126:127]
	v_pk_fma_f32 v[130:131], v[6:7], v[246:247], v[130:131]
	v_pk_fma_f32 v[128:129], v[0:1], v[218:219], v[128:129]
	v_pk_fma_f32 v[132:133], v[2:3], v[220:221], v[132:133]
	v_pk_fma_f32 v[118:119], v[12:13], v[224:225], v[118:119]
	v_pk_fma_f32 v[122:123], v[14:15], v[246:247], v[122:123]
	v_pk_fma_f32 v[120:121], v[8:9], v[218:219], v[120:121]
	v_pk_fma_f32 v[124:125], v[10:11], v[220:221], v[124:125]
	v_pk_fma_f32 v[102:103], v[28:29], v[224:225], v[102:103]
	v_pk_fma_f32 v[108:109], v[30:31], v[246:247], v[108:109]
	v_pk_fma_f32 v[106:107], v[24:25], v[218:219], v[106:107]
	v_pk_fma_f32 v[114:115], v[26:27], v[220:221], v[114:115]
	v_pk_fma_f32 v[104:105], v[44:45], v[224:225], v[104:105]
	v_pk_fma_f32 v[112:113], v[46:47], v[246:247], v[112:113]
	v_pk_fma_f32 v[110:111], v[40:41], v[218:219], v[110:111]
	v_pk_fma_f32 v[116:117], v[42:43], v[220:221], v[116:117]
	ds_read_b128 v[44:47], v166 offset:26624
	ds_read_b128 v[40:43], v166 offset:26640
	s_waitcnt lgkmcnt(1)
	v_cvt_f32_f16_sdwa v223, v179 dst_sel:DWORD dst_unused:UNUSED_PAD src0_sel:WORD_1
	v_cvt_f32_f16_e32 v222, v179
	v_pk_fma_f32 v[158:159], v[44:45], v[222:223], v[158:159]
	v_cvt_f32_f16_sdwa v245, v178 dst_sel:DWORD dst_unused:UNUSED_PAD src0_sel:WORD_1
	v_cvt_f32_f16_e32 v244, v178
	v_pk_fma_f32 v[162:163], v[46:47], v[244:245], v[162:163]
	s_waitcnt lgkmcnt(0)
; #define LAS __attribute__((address_space(3)))
; #define CONV_LOAD(cc) do { _Pragma("unroll") for (int r = 0; r < 8; ++r) { const int rr = 8 * (cc) + r; if (rr < 38) { const int d = rr - 30; const bool ok = (tl + d >= 0); \
;             const h8 x = *(const GAS h8*)(GLU + (size_t)(tok0 + (ok ? d : -tl)) * 512 + 8 * lane); buf[(cc) & 1][r] = ok ? x : zero8; } } } while (0)
; __device__ __forceinline__ void conv_phase(KP P, LAS unsigned char* lds, int gw, int NGW, int tid, int lane) {
;     ...
;         float acc[8][8];
; #pragma unroll
;         for (int i = 0; i < 8; ++i)
; #pragma unroll
;             for (int c = 0; c < 8; ++c) acc[i][c] = 0.f;
;         h8 buf[2][8];
;     ...
;         CONV_LOAD(0);
; #pragma unroll
;         for (int c = 0; c < 5; ++c) {
;             __builtin_amdgcn_sched_barrier(0);
;             if (c + 1 < 5) CONV_LOAD(c + 1);
;             __builtin_amdgcn_sched_barrier(0);
; #pragma unroll
;             for (int r = 0; r < 8; ++r) {
;                 const int rr = 8 * c + r;
;                 if (rr < 38) {
;                     const u32x4 xw = __builtin_bit_cast(u32x4, buf[c & 1][r]);
; #pragma unroll
;                     for (int i = 0; i < 8; ++i) {
;                         const int j = rr - i;
;                         if (j >= 0 && j <= 30) {
;                             const f32x4 w0 = *(const LAS f32x4*)(cw + j * 512 + 8 * lane), w1 = *(const LAS f32x4*)(cw + j * 512 + 8 * lane + 4);
; #pragma unroll
;                             for (int e = 0; e < 4; ++e) { const float wl = (e < 2) ? w0[2 * e] : w1[2 * e - 4], wh = (e < 2) ? w0[2 * e + 1] : w1[2 * e - 3];
;                                 asm("v_fma_mix_f32 %0, %1, %2, %0 op_sel_hi:[0,1,0]" : "+v"(acc[i][2 * e]) : "v"(wl), "v"(xw[e]));
;                                 asm("v_fma_mix_f32 %0, %1, %2, %0 op_sel:[0,1,0] op_sel_hi:[0,1,0]" : "+v"(acc[i][2 * e + 1]) : "v"(wh), "v"(xw[e])); }
;                         }
;                     }
;                 }
	v_cvt_f32_f16_sdwa v239, v177 dst_sel:DWORD dst_unused:UNUSED_PAD src0_sel:WORD_1
	v_cvt_f32_f16_e32 v238, v177
	v_pk_fma_f32 v[160:161], v[40:41], v[238:239], v[160:161]
	v_cvt_f32_f16_sdwa v235, v176 dst_sel:DWORD dst_unused:UNUSED_PAD src0_sel:WORD_1
	v_cvt_f32_f16_e32 v234, v176
	v_pk_fma_f32 v[164:165], v[42:43], v[234:235], v[164:165]
	v_pk_fma_f32 v[150:151], v[60:61], v[222:223], v[150:151]
	v_pk_fma_f32 v[154:155], v[62:63], v[244:245], v[154:155]
	v_pk_fma_f32 v[152:153], v[56:57], v[238:239], v[152:153]
	v_pk_fma_f32 v[156:157], v[58:59], v[234:235], v[156:157]
	v_pk_fma_f32 v[142:143], v[52:53], v[222:223], v[142:143]
	v_pk_fma_f32 v[146:147], v[54:55], v[244:245], v[146:147]
	v_pk_fma_f32 v[144:145], v[48:49], v[238:239], v[144:145]
	v_pk_fma_f32 v[148:149], v[50:51], v[234:235], v[148:149]
	v_pk_fma_f32 v[134:135], v[36:37], v[222:223], v[134:135]
	v_pk_fma_f32 v[138:139], v[38:39], v[244:245], v[138:139]
	v_pk_fma_f32 v[136:137], v[32:33], v[238:239], v[136:137]
	v_pk_fma_f32 v[140:141], v[34:35], v[234:235], v[140:141]
	v_pk_fma_f32 v[126:127], v[20:21], v[222:223], v[126:127]
	v_pk_fma_f32 v[130:131], v[22:23], v[244:245], v[130:131]
	v_pk_fma_f32 v[128:129], v[16:17], v[238:239], v[128:129]
	v_pk_fma_f32 v[132:133], v[18:19], v[234:235], v[132:133]
	v_pk_fma_f32 v[118:119], v[4:5], v[222:223], v[118:119]
	v_pk_fma_f32 v[122:123], v[6:7], v[244:245], v[122:123]
	v_pk_fma_f32 v[120:121], v[0:1], v[238:239], v[120:121]
	v_pk_fma_f32 v[124:125], v[2:3], v[234:235], v[124:125]
	v_pk_fma_f32 v[102:103], v[12:13], v[222:223], v[102:103]
	v_pk_fma_f32 v[108:109], v[14:15], v[244:245], v[108:109]
	v_pk_fma_f32 v[106:107], v[8:9], v[238:239], v[106:107]
	v_pk_fma_f32 v[114:115], v[10:11], v[234:235], v[114:115]
	v_pk_fma_f32 v[104:105], v[28:29], v[222:223], v[104:105]
	v_pk_fma_f32 v[112:113], v[30:31], v[244:245], v[112:113]
	v_pk_fma_f32 v[110:111], v[24:25], v[238:239], v[110:111]
	v_pk_fma_f32 v[116:117], v[26:27], v[234:235], v[116:117]
	ds_read_b128 v[28:31], v166 offset:28672
	ds_read_b128 v[24:27], v166 offset:28688
	s_waitcnt lgkmcnt(1)
	v_cvt_f32_f16_sdwa v237, v71 dst_sel:DWORD dst_unused:UNUSED_PAD src0_sel:WORD_1
	v_cvt_f32_f16_e32 v236, v71
	v_pk_fma_f32 v[158:159], v[28:29], v[236:237], v[158:159]
	v_cvt_f32_f16_sdwa v215, v70 dst_sel:DWORD dst_unused:UNUSED_PAD src0_sel:WORD_1
	v_cvt_f32_f16_e32 v214, v70
	v_pk_fma_f32 v[162:163], v[30:31], v[214:215], v[162:163]
	s_waitcnt lgkmcnt(0)
	v_cvt_f32_f16_sdwa v217, v69 dst_sel:DWORD dst_unused:UNUSED_PAD src0_sel:WORD_1
	v_cvt_f32_f16_e32 v216, v69
	v_pk_fma_f32 v[160:161], v[24:25], v[216:217], v[160:161]
	v_cvt_f32_f16_sdwa v243, v68 dst_sel:DWORD dst_unused:UNUSED_PAD src0_sel:WORD_1
	v_cvt_f32_f16_e32 v242, v68
	v_pk_fma_f32 v[164:165], v[26:27], v[242:243], v[164:165]
	v_pk_fma_f32 v[150:151], v[44:45], v[236:237], v[150:151]
	v_pk_fma_f32 v[154:155], v[46:47], v[214:215], v[154:155]
	v_pk_fma_f32 v[152:153], v[40:41], v[216:217], v[152:153]
	v_pk_fma_f32 v[156:157], v[42:43], v[242:243], v[156:157]
	v_pk_fma_f32 v[142:143], v[60:61], v[236:237], v[142:143]
	v_pk_fma_f32 v[146:147], v[62:63], v[214:215], v[146:147]
	v_pk_fma_f32 v[144:145], v[56:57], v[216:217], v[144:145]
	v_pk_fma_f32 v[148:149], v[58:59], v[242:243], v[148:149]
	v_pk_fma_f32 v[134:135], v[52:53], v[236:237], v[134:135]
	v_pk_fma_f32 v[138:139], v[54:55], v[214:215], v[138:139]
	v_pk_fma_f32 v[136:137], v[48:49], v[216:217], v[136:137]
	v_pk_fma_f32 v[140:141], v[50:51], v[242:243], v[140:141]
	v_pk_fma_f32 v[126:127], v[36:37], v[236:237], v[126:127]
	v_pk_fma_f32 v[130:131], v[38:39], v[214:215], v[130:131]
	v_pk_fma_f32 v[128:129], v[32:33], v[216:217], v[128:129]
	v_pk_fma_f32 v[132:133], v[34:35], v[242:243], v[132:133]
	v_pk_fma_f32 v[118:119], v[20:21], v[236:237], v[118:119]
	v_pk_fma_f32 v[122:123], v[22:23], v[214:215], v[122:123]
	v_pk_fma_f32 v[120:121], v[16:17], v[216:217], v[120:121]
	v_pk_fma_f32 v[124:125], v[18:19], v[242:243], v[124:125]
	v_pk_fma_f32 v[102:103], v[4:5], v[236:237], v[102:103]
	v_pk_fma_f32 v[108:109], v[6:7], v[214:215], v[108:109]
	v_pk_fma_f32 v[106:107], v[0:1], v[216:217], v[106:107]
	v_pk_fma_f32 v[114:115], v[2:3], v[242:243], v[114:115]
	v_pk_fma_f32 v[104:105], v[12:13], v[236:237], v[104:105]
	v_pk_fma_f32 v[112:113], v[14:15], v[214:215], v[112:113]
	v_pk_fma_f32 v[110:111], v[8:9], v[216:217], v[110:111]
	v_pk_fma_f32 v[116:117], v[10:11], v[242:243], v[116:117]
	ds_read_b128 v[12:15], v166 offset:30720
	ds_read_b128 v[8:11], v166 offset:30736
	s_waitcnt lgkmcnt(1)
	v_cvt_f32_f16_sdwa v241, v67 dst_sel:DWORD dst_unused:UNUSED_PAD src0_sel:WORD_1
	v_cvt_f32_f16_e32 v240, v67
	v_pk_fma_f32 v[158:159], v[12:13], v[240:241], v[158:159]
	v_cvt_f32_f16_sdwa v231, v66 dst_sel:DWORD dst_unused:UNUSED_PAD src0_sel:WORD_1
	v_cvt_f32_f16_e32 v230, v66
	v_pk_fma_f32 v[162:163], v[14:15], v[230:231], v[162:163]
	s_waitcnt lgkmcnt(0)
; #define LAS __attribute__((address_space(3)))
; #define CONV_LOAD(cc) do { _Pragma("unroll") for (int r = 0; r < 8; ++r) { const int rr = 8 * (cc) + r; if (rr < 38) { const int d = rr - 30; const bool ok = (tl + d >= 0); \
;             const h8 x = *(const GAS h8*)(GLU + (size_t)(tok0 + (ok ? d : -tl)) * 512 + 8 * lane); buf[(cc) & 1][r] = ok ? x : zero8; } } } while (0)
; __device__ __forceinline__ void conv_phase(KP P, LAS unsigned char* lds, int gw, int NGW, int tid, int lane) {
;     ...
;         CONV_LOAD(0);
; #pragma unroll
;         for (int c = 0; c < 5; ++c) {
;             __builtin_amdgcn_sched_barrier(0);
;             if (c + 1 < 5) CONV_LOAD(c + 1);
;             __builtin_amdgcn_sched_barrier(0);
; #pragma unroll
;             for (int r = 0; r < 8; ++r) {
;                 const int rr = 8 * c + r;
;                 if (rr < 38) {
;                     const u32x4 xw = __builtin_bit_cast(u32x4, buf[c & 1][r]);
; #pragma unroll
;                     for (int i = 0; i < 8; ++i) {
;                         const int j = rr - i;
;                         if (j >= 0 && j <= 30) {
;                             const f32x4 w0 = *(const LAS f32x4*)(cw + j * 512 + 8 * lane), w1 = *(const LAS f32x4*)(cw + j * 512 + 8 * lane + 4);
; #pragma unroll
;                             for (int e = 0; e < 4; ++e) { const float wl = (e < 2) ? w0[2 * e] : w1[2 * e - 4], wh = (e < 2) ? w0[2 * e + 1] : w1[2 * e - 3];
;                                 asm("v_fma_mix_f32 %0, %1, %2, %0 op_sel_hi:[0,1,0]" : "+v"(acc[i][2 * e]) : "v"(wl), "v"(xw[e]));
;                                 asm("v_fma_mix_f32 %0, %1, %2, %0 op_sel:[0,1,0] op_sel_hi:[0,1,0]" : "+v"(acc[i][2 * e + 1]) : "v"(wh), "v"(xw[e])); }
;                         }
;                     }
;                 }
	v_cvt_f32_f16_sdwa v233, v65 dst_sel:DWORD dst_unused:UNUSED_PAD src0_sel:WORD_1
	v_cvt_f32_f16_e32 v232, v65
	v_pk_fma_f32 v[160:161], v[8:9], v[232:233], v[160:161]
	v_cvt_f32_f16_sdwa v229, v64 dst_sel:DWORD dst_unused:UNUSED_PAD src0_sel:WORD_1
	v_cvt_f32_f16_e32 v228, v64
	v_pk_fma_f32 v[164:165], v[10:11], v[228:229], v[164:165]
	v_pk_fma_f32 v[150:151], v[28:29], v[240:241], v[150:151]
	v_pk_fma_f32 v[154:155], v[30:31], v[230:231], v[154:155]
	v_pk_fma_f32 v[152:153], v[24:25], v[232:233], v[152:153]
	v_pk_fma_f32 v[156:157], v[26:27], v[228:229], v[156:157]
	v_pk_fma_f32 v[142:143], v[44:45], v[240:241], v[142:143]
	v_pk_fma_f32 v[146:147], v[46:47], v[230:231], v[146:147]
	v_pk_fma_f32 v[144:145], v[40:41], v[232:233], v[144:145]
	v_pk_fma_f32 v[148:149], v[42:43], v[228:229], v[148:149]
	v_pk_fma_f32 v[134:135], v[60:61], v[240:241], v[134:135]
	v_pk_fma_f32 v[138:139], v[62:63], v[230:231], v[138:139]
	v_pk_fma_f32 v[136:137], v[56:57], v[232:233], v[136:137]
	v_pk_fma_f32 v[140:141], v[58:59], v[228:229], v[140:141]
	v_pk_fma_f32 v[126:127], v[52:53], v[240:241], v[126:127]
	v_pk_fma_f32 v[130:131], v[54:55], v[230:231], v[130:131]
	v_pk_fma_f32 v[128:129], v[48:49], v[232:233], v[128:129]
	v_pk_fma_f32 v[132:133], v[50:51], v[228:229], v[132:133]
	v_pk_fma_f32 v[118:119], v[36:37], v[240:241], v[118:119]
	v_pk_fma_f32 v[122:123], v[38:39], v[230:231], v[122:123]
	v_pk_fma_f32 v[120:121], v[32:33], v[232:233], v[120:121]
	v_pk_fma_f32 v[124:125], v[34:35], v[228:229], v[124:125]
	v_pk_fma_f32 v[102:103], v[20:21], v[240:241], v[102:103]
	v_pk_fma_f32 v[108:109], v[22:23], v[230:231], v[108:109]
	v_pk_fma_f32 v[106:107], v[16:17], v[232:233], v[106:107]
	v_pk_fma_f32 v[114:115], v[18:19], v[228:229], v[114:115]
	v_pk_fma_f32 v[104:105], v[4:5], v[240:241], v[104:105]
	v_pk_fma_f32 v[112:113], v[6:7], v[230:231], v[112:113]
	v_pk_fma_f32 v[110:111], v[0:1], v[232:233], v[110:111]
	v_pk_fma_f32 v[116:117], v[2:3], v[228:229], v[116:117]
	s_add_i32 s6, s26, s25
	s_ashr_i32 s7, s6, 31
	s_lshl_b64 s[6:7], s[6:7], 10
	v_lshl_add_u64 v[0:1], v[96:97], 0, s[6:7]
	s_add_i32 s6, s26, s21
	s_ashr_i32 s7, s6, 31
	s_lshl_b64 s[6:7], s[6:7], 10
	v_lshl_add_u64 v[2:3], v[96:97], 0, s[6:7]
	s_add_i32 s6, s26, s20
	s_ashr_i32 s7, s6, 31
	s_lshl_b64 s[6:7], s[6:7], 10
	global_load_dwordx4 v[8:11], v[0:1], off
	global_load_dwordx4 v[12:15], v[2:3], off
	v_lshl_add_u64 v[0:1], v[96:97], 0, s[6:7]
	s_add_i32 s6, s26, s5
	s_add_i32 s4, s26, s4
	s_ashr_i32 s7, s6, 31
	s_ashr_i32 s5, s4, 31
	s_lshl_b64 s[6:7], s[6:7], 10
	s_lshl_b64 s[4:5], s[4:5], 10
	s_cmp_lg_u64 vcc, 0
	v_lshl_add_u64 v[2:3], v[96:97], 0, s[6:7]
	global_load_dwordx4 v[16:19], v[0:1], off
	global_load_dwordx4 v[20:23], v[2:3], off
	v_lshl_add_u64 v[0:1], v[96:97], 0, s[4:5]
	s_subb_u32 s4, s26, 0
	s_ashr_i32 s5, s4, 31
	s_lshl_b64 s[4:5], s[4:5], 10
	v_lshl_add_u64 v[2:3], v[96:97], 0, s[4:5]
	s_add_i32 s4, s24, -6
	s_ashr_i32 s27, s26, 31
	s_ashr_i32 s5, s4, 31
	s_lshl_b64 s[12:13], s[26:27], 10
	s_lshl_b64 s[6:7], s[4:5], 10
	global_load_dwordx4 v[24:27], v[0:1], off
	global_load_dwordx4 v[28:31], v[2:3], off
	v_lshl_add_u64 v[0:1], v[96:97], 0, s[12:13]
	v_lshl_add_u64 v[2:3], v[96:97], 0, s[6:7]
	global_load_dwordx4 v[4:7], v[0:1], off
	s_nop 0
	global_load_dwordx4 v[0:3], v[2:3], off
	s_waitcnt vmcnt(7)
	v_cndmask_b32_e64 v206, v11, 0, s[18:19]
	v_cndmask_b32_e64 v207, v10, 0, s[18:19]
	v_cndmask_b32_e64 v208, v9, 0, s[18:19]
	v_cndmask_b32_e64 v209, v8, 0, s[18:19]
	s_waitcnt vmcnt(6)
	v_cndmask_b32_e64 v197, v15, 0, s[18:19]
	v_cndmask_b32_e64 v198, v14, 0, s[18:19]
	v_cndmask_b32_e64 v199, v13, 0, s[18:19]
	v_cndmask_b32_e64 v200, v12, 0, s[18:19]
	s_waitcnt vmcnt(5)
	v_cndmask_b32_e64 v188, v19, 0, s[18:19]
	v_cndmask_b32_e64 v189, v18, 0, s[18:19]
	v_cndmask_b32_e64 v190, v17, 0, s[18:19]
	v_cndmask_b32_e64 v191, v16, 0, s[18:19]
	s_waitcnt vmcnt(4)
	v_cndmask_b32_e64 v184, v23, 0, s[18:19]
	v_cndmask_b32_e64 v185, v22, 0, s[18:19]
	v_cndmask_b32_e64 v186, v21, 0, s[18:19]
	v_cndmask_b32_e64 v187, v20, 0, s[18:19]
	s_waitcnt vmcnt(3)
	v_cndmask_b32_e64 v180, v27, 0, s[18:19]
	v_cndmask_b32_e64 v181, v26, 0, s[18:19]
	v_cndmask_b32_e64 v182, v25, 0, s[18:19]
	v_cndmask_b32_e64 v183, v24, 0, s[18:19]
	s_waitcnt vmcnt(2)
	v_cndmask_b32_e32 v176, 0, v31, vcc
	v_cndmask_b32_e32 v177, 0, v30, vcc
	v_cndmask_b32_e32 v178, 0, v29, vcc
	v_cndmask_b32_e32 v179, 0, v28, vcc
	ds_read_b128 v[12:15], v166 offset:32768
	ds_read_b128 v[8:11], v166 offset:32784
	ds_read_b128 v[20:23], v166 offset:30720
	ds_read_b128 v[16:19], v166 offset:30736
	s_waitcnt lgkmcnt(1)
	v_fma_mix_f32 v150, v20, v205, v150 op_sel_hi:[0,1,0]
	v_cvt_f32_f16_sdwa v227, v205 dst_sel:DWORD dst_unused:UNUSED_PAD src0_sel:WORD_1
	v_cvt_f32_f16_e32 v226, v205
	v_pk_fma_f32 v[158:159], v[12:13], v[226:227], v[158:159]
	v_cvt_f32_f16_sdwa v221, v203 dst_sel:DWORD dst_unused:UNUSED_PAD src0_sel:WORD_1
	v_cvt_f32_f16_e32 v220, v203
	v_pk_fma_f32 v[162:163], v[14:15], v[220:221], v[162:163]
	v_cvt_f32_f16_sdwa v219, v202 dst_sel:DWORD dst_unused:UNUSED_PAD src0_sel:WORD_1
	v_cvt_f32_f16_e32 v218, v202
	v_pk_fma_f32 v[160:161], v[8:9], v[218:219], v[160:161]
	v_cvt_f32_f16_sdwa v247, v201 dst_sel:DWORD dst_unused:UNUSED_PAD src0_sel:WORD_1
	v_cvt_f32_f16_e32 v246, v201
	v_pk_fma_f32 v[164:165], v[10:11], v[246:247], v[164:165]
	v_fma_mix_f32 v151, v21, v205, v151 op_sel:[0,1,0] op_sel_hi:[0,1,0]
	v_pk_fma_f32 v[154:155], v[22:23], v[220:221], v[154:155]
	s_waitcnt lgkmcnt(0)
	v_fma_mix_f32 v152, v16, v202, v152 op_sel_hi:[0,1,0]
	ds_read_b128 v[36:39], v166 offset:28672
	ds_read_b128 v[32:35], v166 offset:28688
	v_fma_mix_f32 v153, v17, v202, v153 op_sel:[0,1,0] op_sel_hi:[0,1,0]
	v_pk_fma_f32 v[156:157], v[18:19], v[246:247], v[156:157]
	s_waitcnt lgkmcnt(1)
; #define LAS __attribute__((address_space(3)))
; #define CONV_LOAD(cc) do { _Pragma("unroll") for (int r = 0; r < 8; ++r) { const int rr = 8 * (cc) + r; if (rr < 38) { const int d = rr - 30; const bool ok = (tl + d >= 0); \
;             const h8 x = *(const GAS h8*)(GLU + (size_t)(tok0 + (ok ? d : -tl)) * 512 + 8 * lane); buf[(cc) & 1][r] = ok ? x : zero8; } } } while (0)
; __device__ __forceinline__ void conv_phase(KP P, LAS unsigned char* lds, int gw, int NGW, int tid, int lane) {
;     ...
;         for (int c = 0; c < 5; ++c) {
;             __builtin_amdgcn_sched_barrier(0);
;             if (c + 1 < 5) CONV_LOAD(c + 1);
;             __builtin_amdgcn_sched_barrier(0);
; #pragma unroll
;             for (int r = 0; r < 8; ++r) {
;                 const int rr = 8 * c + r;
;                 if (rr < 38) {
;                     const u32x4 xw = __builtin_bit_cast(u32x4, buf[c & 1][r]);
; #pragma unroll
;                     for (int i = 0; i < 8; ++i) {
;                         const int j = rr - i;
;                         if (j >= 0 && j <= 30) {
;                             const f32x4 w0 = *(const LAS f32x4*)(cw + j * 512 + 8 * lane), w1 = *(const LAS f32x4*)(cw + j * 512 + 8 * lane + 4);
; #pragma unroll
;                             for (int e = 0; e < 4; ++e) { const float wl = (e < 2) ? w0[2 * e] : w1[2 * e - 4], wh = (e < 2) ? w0[2 * e + 1] : w1[2 * e - 3];
;                                 asm("v_fma_mix_f32 %0, %1, %2, %0 op_sel_hi:[0,1,0]" : "+v"(acc[i][2 * e]) : "v"(wl), "v"(xw[e]));
;                                 asm("v_fma_mix_f32 %0, %1, %2, %0 op_sel:[0,1,0] op_sel_hi:[0,1,0]" : "+v"(acc[i][2 * e + 1]) : "v"(wh), "v"(xw[e])); }
;                         }
;                     }
;                 }
;             }
	v_pk_fma_f32 v[142:143], v[36:37], v[226:227], v[142:143]
	v_pk_fma_f32 v[146:147], v[38:39], v[220:221], v[146:147]
	s_waitcnt lgkmcnt(0)
	v_fma_mix_f32 v144, v32, v202, v144 op_sel_hi:[0,1,0]
	ds_read_b128 v[52:55], v166 offset:26624
	ds_read_b128 v[48:51], v166 offset:26640
	v_fma_mix_f32 v145, v33, v202, v145 op_sel:[0,1,0] op_sel_hi:[0,1,0]
	v_pk_fma_f32 v[148:149], v[34:35], v[246:247], v[148:149]
	s_waitcnt lgkmcnt(1)
	v_pk_fma_f32 v[134:135], v[52:53], v[226:227], v[134:135]
	v_pk_fma_f32 v[138:139], v[54:55], v[220:221], v[138:139]
	s_waitcnt lgkmcnt(0)
	v_fma_mix_f32 v136, v48, v202, v136 op_sel_hi:[0,1,0]
	ds_read_b128 v[68:71], v166 offset:24576
	ds_read_b128 v[64:67], v166 offset:24592
	v_fma_mix_f32 v137, v49, v202, v137 op_sel:[0,1,0] op_sel_hi:[0,1,0]
	v_pk_fma_f32 v[140:141], v[50:51], v[246:247], v[140:141]
	s_waitcnt lgkmcnt(1)
	v_pk_fma_f32 v[126:127], v[68:69], v[226:227], v[126:127]
	v_pk_fma_f32 v[130:131], v[70:71], v[220:221], v[130:131]
	s_waitcnt lgkmcnt(0)
	v_fma_mix_f32 v128, v64, v202, v128 op_sel_hi:[0,1,0]
	ds_read_b128 v[60:63], v166 offset:22528
	ds_read_b128 v[56:59], v166 offset:22544
	v_fma_mix_f32 v129, v65, v202, v129 op_sel:[0,1,0] op_sel_hi:[0,1,0]
	v_pk_fma_f32 v[132:133], v[66:67], v[246:247], v[132:133]
	s_waitcnt lgkmcnt(1)
	v_pk_fma_f32 v[118:119], v[60:61], v[226:227], v[118:119]
	v_pk_fma_f32 v[122:123], v[62:63], v[220:221], v[122:123]
	s_waitcnt lgkmcnt(0)
	v_fma_mix_f32 v120, v56, v202, v120 op_sel_hi:[0,1,0]
	ds_read_b128 v[44:47], v166 offset:20480
	ds_read_b128 v[40:43], v166 offset:20496
	v_fma_mix_f32 v121, v57, v202, v121 op_sel:[0,1,0] op_sel_hi:[0,1,0]
	v_pk_fma_f32 v[124:125], v[58:59], v[246:247], v[124:125]
	s_waitcnt lgkmcnt(1)
	v_pk_fma_f32 v[102:103], v[44:45], v[226:227], v[102:103]
	v_pk_fma_f32 v[108:109], v[46:47], v[220:221], v[108:109]
	s_waitcnt lgkmcnt(0)
	v_fma_mix_f32 v106, v40, v202, v106 op_sel_hi:[0,1,0]
	ds_read_b128 v[24:27], v166 offset:18432
	ds_read_b128 v[210:213], v166 offset:18448
	v_fma_mix_f32 v107, v41, v202, v107 op_sel:[0,1,0] op_sel_hi:[0,1,0]
	v_pk_fma_f32 v[114:115], v[42:43], v[246:247], v[114:115]
	s_waitcnt lgkmcnt(1)
	v_pk_fma_f32 v[104:105], v[24:25], v[226:227], v[104:105]
	v_pk_fma_f32 v[112:113], v[26:27], v[220:221], v[112:113]
	s_waitcnt lgkmcnt(0)
	v_pk_fma_f32 v[110:111], v[210:211], v[218:219], v[110:111]
	v_pk_fma_f32 v[116:117], v[212:213], v[246:247], v[116:117]
	ds_read_b128 v[28:31], v166 offset:34816
	ds_read_b128 v[24:27], v166 offset:34832
	s_waitcnt lgkmcnt(1)
	v_cvt_f32_f16_sdwa v225, v196 dst_sel:DWORD dst_unused:UNUSED_PAD src0_sel:WORD_1
	v_cvt_f32_f16_e32 v224, v196
	v_pk_fma_f32 v[158:159], v[28:29], v[224:225], v[158:159]
	v_cvt_f32_f16_sdwa v235, v194 dst_sel:DWORD dst_unused:UNUSED_PAD src0_sel:WORD_1
	v_cvt_f32_f16_e32 v234, v194
	v_pk_fma_f32 v[162:163], v[30:31], v[234:235], v[162:163]
	s_waitcnt lgkmcnt(0)
	v_cvt_f32_f16_sdwa v239, v193 dst_sel:DWORD dst_unused:UNUSED_PAD src0_sel:WORD_1
	v_cvt_f32_f16_e32 v238, v193
	v_pk_fma_f32 v[160:161], v[24:25], v[238:239], v[160:161]
	v_cvt_f32_f16_sdwa v245, v192 dst_sel:DWORD dst_unused:UNUSED_PAD src0_sel:WORD_1
	v_cvt_f32_f16_e32 v244, v192
	v_pk_fma_f32 v[164:165], v[26:27], v[244:245], v[164:165]
	v_pk_fma_f32 v[150:151], v[12:13], v[224:225], v[150:151]
	v_pk_fma_f32 v[154:155], v[14:15], v[234:235], v[154:155]
	v_pk_fma_f32 v[152:153], v[8:9], v[238:239], v[152:153]
	v_pk_fma_f32 v[156:157], v[10:11], v[244:245], v[156:157]
	v_pk_fma_f32 v[142:143], v[20:21], v[224:225], v[142:143]
	v_pk_fma_f32 v[146:147], v[22:23], v[234:235], v[146:147]
	v_pk_fma_f32 v[144:145], v[16:17], v[238:239], v[144:145]
	v_pk_fma_f32 v[148:149], v[18:19], v[244:245], v[148:149]
	v_pk_fma_f32 v[134:135], v[36:37], v[224:225], v[134:135]
	v_pk_fma_f32 v[138:139], v[38:39], v[234:235], v[138:139]
	v_pk_fma_f32 v[136:137], v[32:33], v[238:239], v[136:137]
	v_pk_fma_f32 v[140:141], v[34:35], v[244:245], v[140:141]
	v_pk_fma_f32 v[126:127], v[52:53], v[224:225], v[126:127]
	v_pk_fma_f32 v[130:131], v[54:55], v[234:235], v[130:131]
	v_pk_fma_f32 v[128:129], v[48:49], v[238:239], v[128:129]
	v_pk_fma_f32 v[132:133], v[50:51], v[244:245], v[132:133]
	v_pk_fma_f32 v[118:119], v[68:69], v[224:225], v[118:119]
	v_pk_fma_f32 v[122:123], v[70:71], v[234:235], v[122:123]
	v_pk_fma_f32 v[120:121], v[64:65], v[238:239], v[120:121]
	v_pk_fma_f32 v[124:125], v[66:67], v[244:245], v[124:125]
	v_pk_fma_f32 v[102:103], v[60:61], v[224:225], v[102:103]
	v_pk_fma_f32 v[108:109], v[62:63], v[234:235], v[108:109]
	v_pk_fma_f32 v[106:107], v[56:57], v[238:239], v[106:107]
	v_pk_fma_f32 v[114:115], v[58:59], v[244:245], v[114:115]
	v_pk_fma_f32 v[104:105], v[44:45], v[224:225], v[104:105]
	v_pk_fma_f32 v[112:113], v[46:47], v[234:235], v[112:113]
	v_pk_fma_f32 v[110:111], v[40:41], v[238:239], v[110:111]
	v_pk_fma_f32 v[116:117], v[42:43], v[244:245], v[116:117]
	ds_read_b128 v[44:47], v166 offset:36864
	ds_read_b128 v[40:43], v166 offset:36880
	s_waitcnt lgkmcnt(1)
	v_cvt_f32_f16_sdwa v223, v95 dst_sel:DWORD dst_unused:UNUSED_PAD src0_sel:WORD_1
	v_cvt_f32_f16_e32 v222, v95
	v_pk_fma_f32 v[158:159], v[44:45], v[222:223], v[158:159]
	v_cvt_f32_f16_sdwa v243, v94 dst_sel:DWORD dst_unused:UNUSED_PAD src0_sel:WORD_1
	v_cvt_f32_f16_e32 v242, v94
	v_pk_fma_f32 v[162:163], v[46:47], v[242:243], v[162:163]
	s_waitcnt lgkmcnt(0)
; #define LAS __attribute__((address_space(3)))
; #define CONV_LOAD(cc) do { _Pragma("unroll") for (int r = 0; r < 8; ++r) { const int rr = 8 * (cc) + r; if (rr < 38) { const int d = rr - 30; const bool ok = (tl + d >= 0); \
;             const h8 x = *(const GAS h8*)(GLU + (size_t)(tok0 + (ok ? d : -tl)) * 512 + 8 * lane); buf[(cc) & 1][r] = ok ? x : zero8; } } } while (0)
; __device__ __forceinline__ void conv_phase(KP P, LAS unsigned char* lds, int gw, int NGW, int tid, int lane) {
;     ...
;         for (int c = 0; c < 5; ++c) {
;             __builtin_amdgcn_sched_barrier(0);
;             if (c + 1 < 5) CONV_LOAD(c + 1);
;             __builtin_amdgcn_sched_barrier(0);
; #pragma unroll
;             for (int r = 0; r < 8; ++r) {
;                 const int rr = 8 * c + r;
;                 if (rr < 38) {
;                     const u32x4 xw = __builtin_bit_cast(u32x4, buf[c & 1][r]);
; #pragma unroll
;                     for (int i = 0; i < 8; ++i) {
;                         const int j = rr - i;
;                         if (j >= 0 && j <= 30) {
;                             const f32x4 w0 = *(const LAS f32x4*)(cw + j * 512 + 8 * lane), w1 = *(const LAS f32x4*)(cw + j * 512 + 8 * lane + 4);
; #pragma unroll
;                             for (int e = 0; e < 4; ++e) { const float wl = (e < 2) ? w0[2 * e] : w1[2 * e - 4], wh = (e < 2) ? w0[2 * e + 1] : w1[2 * e - 3];
;                                 asm("v_fma_mix_f32 %0, %1, %2, %0 op_sel_hi:[0,1,0]" : "+v"(acc[i][2 * e]) : "v"(wl), "v"(xw[e]));
;                                 asm("v_fma_mix_f32 %0, %1, %2, %0 op_sel:[0,1,0] op_sel_hi:[0,1,0]" : "+v"(acc[i][2 * e + 1]) : "v"(wh), "v"(xw[e])); }
;                         }
;                     }
;                 }
;             }
	v_cvt_f32_f16_sdwa v217, v93 dst_sel:DWORD dst_unused:UNUSED_PAD src0_sel:WORD_1
	v_cvt_f32_f16_e32 v216, v93
	v_pk_fma_f32 v[160:161], v[40:41], v[216:217], v[160:161]
	v_cvt_f32_f16_sdwa v215, v92 dst_sel:DWORD dst_unused:UNUSED_PAD src0_sel:WORD_1
	v_cvt_f32_f16_e32 v214, v92
	v_pk_fma_f32 v[164:165], v[42:43], v[214:215], v[164:165]
	v_pk_fma_f32 v[150:151], v[28:29], v[222:223], v[150:151]
	v_pk_fma_f32 v[154:155], v[30:31], v[242:243], v[154:155]
	v_pk_fma_f32 v[152:153], v[24:25], v[216:217], v[152:153]
	v_pk_fma_f32 v[156:157], v[26:27], v[214:215], v[156:157]
	v_pk_fma_f32 v[142:143], v[12:13], v[222:223], v[142:143]
	v_pk_fma_f32 v[146:147], v[14:15], v[242:243], v[146:147]
	v_pk_fma_f32 v[144:145], v[8:9], v[216:217], v[144:145]
	v_pk_fma_f32 v[148:149], v[10:11], v[214:215], v[148:149]
	v_pk_fma_f32 v[134:135], v[20:21], v[222:223], v[134:135]
	v_pk_fma_f32 v[138:139], v[22:23], v[242:243], v[138:139]
	v_pk_fma_f32 v[136:137], v[16:17], v[216:217], v[136:137]
	v_pk_fma_f32 v[140:141], v[18:19], v[214:215], v[140:141]
	v_pk_fma_f32 v[126:127], v[36:37], v[222:223], v[126:127]
	v_pk_fma_f32 v[130:131], v[38:39], v[242:243], v[130:131]
	v_pk_fma_f32 v[128:129], v[32:33], v[216:217], v[128:129]
	v_pk_fma_f32 v[132:133], v[34:35], v[214:215], v[132:133]
	v_pk_fma_f32 v[118:119], v[52:53], v[222:223], v[118:119]
	v_pk_fma_f32 v[122:123], v[54:55], v[242:243], v[122:123]
	v_pk_fma_f32 v[120:121], v[48:49], v[216:217], v[120:121]
	v_pk_fma_f32 v[124:125], v[50:51], v[214:215], v[124:125]
	v_pk_fma_f32 v[102:103], v[68:69], v[222:223], v[102:103]
	v_pk_fma_f32 v[108:109], v[70:71], v[242:243], v[108:109]
	v_pk_fma_f32 v[106:107], v[64:65], v[216:217], v[106:107]
	v_pk_fma_f32 v[114:115], v[66:67], v[214:215], v[114:115]
	v_pk_fma_f32 v[104:105], v[60:61], v[222:223], v[104:105]
	v_pk_fma_f32 v[112:113], v[62:63], v[242:243], v[112:113]
	v_pk_fma_f32 v[110:111], v[56:57], v[216:217], v[110:111]
	v_pk_fma_f32 v[116:117], v[58:59], v[214:215], v[116:117]
	ds_read_b128 v[60:63], v166 offset:38912
	ds_read_b128 v[56:59], v166 offset:38928
	s_waitcnt lgkmcnt(1)
	v_cvt_f32_f16_sdwa v237, v91 dst_sel:DWORD dst_unused:UNUSED_PAD src0_sel:WORD_1
	v_cvt_f32_f16_e32 v236, v91
	v_pk_fma_f32 v[158:159], v[60:61], v[236:237], v[158:159]
	v_cvt_f32_f16_sdwa v229, v90 dst_sel:DWORD dst_unused:UNUSED_PAD src0_sel:WORD_1
	v_cvt_f32_f16_e32 v228, v90
	v_pk_fma_f32 v[162:163], v[62:63], v[228:229], v[162:163]
	s_waitcnt lgkmcnt(0)
	v_cvt_f32_f16_sdwa v233, v89 dst_sel:DWORD dst_unused:UNUSED_PAD src0_sel:WORD_1
	v_cvt_f32_f16_e32 v232, v89
	v_pk_fma_f32 v[160:161], v[56:57], v[232:233], v[160:161]
	v_cvt_f32_f16_sdwa v231, v88 dst_sel:DWORD dst_unused:UNUSED_PAD src0_sel:WORD_1
	v_cvt_f32_f16_e32 v230, v88
	v_pk_fma_f32 v[164:165], v[58:59], v[230:231], v[164:165]
	v_pk_fma_f32 v[150:151], v[44:45], v[236:237], v[150:151]
	v_pk_fma_f32 v[154:155], v[46:47], v[228:229], v[154:155]
	v_pk_fma_f32 v[152:153], v[40:41], v[232:233], v[152:153]
	v_pk_fma_f32 v[156:157], v[42:43], v[230:231], v[156:157]
	v_pk_fma_f32 v[142:143], v[28:29], v[236:237], v[142:143]
	v_pk_fma_f32 v[146:147], v[30:31], v[228:229], v[146:147]
	v_pk_fma_f32 v[144:145], v[24:25], v[232:233], v[144:145]
	v_pk_fma_f32 v[148:149], v[26:27], v[230:231], v[148:149]
	v_pk_fma_f32 v[134:135], v[12:13], v[236:237], v[134:135]
	v_pk_fma_f32 v[138:139], v[14:15], v[228:229], v[138:139]
	v_pk_fma_f32 v[136:137], v[8:9], v[232:233], v[136:137]
	v_pk_fma_f32 v[140:141], v[10:11], v[230:231], v[140:141]
	v_pk_fma_f32 v[126:127], v[20:21], v[236:237], v[126:127]
	v_pk_fma_f32 v[130:131], v[22:23], v[228:229], v[130:131]
	v_pk_fma_f32 v[128:129], v[16:17], v[232:233], v[128:129]
	v_pk_fma_f32 v[132:133], v[18:19], v[230:231], v[132:133]
	v_pk_fma_f32 v[118:119], v[36:37], v[236:237], v[118:119]
	v_pk_fma_f32 v[122:123], v[38:39], v[228:229], v[122:123]
	v_pk_fma_f32 v[120:121], v[32:33], v[232:233], v[120:121]
	v_pk_fma_f32 v[124:125], v[34:35], v[230:231], v[124:125]
	v_pk_fma_f32 v[102:103], v[52:53], v[236:237], v[102:103]
	v_pk_fma_f32 v[108:109], v[54:55], v[228:229], v[108:109]
	v_pk_fma_f32 v[106:107], v[48:49], v[232:233], v[106:107]
	v_pk_fma_f32 v[114:115], v[50:51], v[230:231], v[114:115]
	v_pk_fma_f32 v[104:105], v[68:69], v[236:237], v[104:105]
	v_pk_fma_f32 v[112:113], v[70:71], v[228:229], v[112:113]
	v_pk_fma_f32 v[110:111], v[64:65], v[232:233], v[110:111]
	v_pk_fma_f32 v[116:117], v[66:67], v[230:231], v[116:117]
	ds_read_b128 v[68:71], v166 offset:40960
	ds_read_b128 v[64:67], v166 offset:40976
	s_waitcnt lgkmcnt(1)
	v_cvt_f32_f16_sdwa v241, v87 dst_sel:DWORD dst_unused:UNUSED_PAD src0_sel:WORD_1
	v_cvt_f32_f16_e32 v240, v87
	v_pk_fma_f32 v[158:159], v[68:69], v[240:241], v[158:159]
	v_cvt_f32_f16_sdwa v227, v86 dst_sel:DWORD dst_unused:UNUSED_PAD src0_sel:WORD_1
	v_cvt_f32_f16_e32 v226, v86
	v_pk_fma_f32 v[162:163], v[70:71], v[226:227], v[162:163]
	s_waitcnt lgkmcnt(0)
; #define LAS __attribute__((address_space(3)))
; #define CONV_LOAD(cc) do { _Pragma("unroll") for (int r = 0; r < 8; ++r) { const int rr = 8 * (cc) + r; if (rr < 38) { const int d = rr - 30; const bool ok = (tl + d >= 0); \
;             const h8 x = *(const GAS h8*)(GLU + (size_t)(tok0 + (ok ? d : -tl)) * 512 + 8 * lane); buf[(cc) & 1][r] = ok ? x : zero8; } } } while (0)
; __device__ __forceinline__ void conv_phase(KP P, LAS unsigned char* lds, int gw, int NGW, int tid, int lane) {
;     ...
;         for (int c = 0; c < 5; ++c) {
;             __builtin_amdgcn_sched_barrier(0);
;             if (c + 1 < 5) CONV_LOAD(c + 1);
;             __builtin_amdgcn_sched_barrier(0);
; #pragma unroll
;             for (int r = 0; r < 8; ++r) {
;                 const int rr = 8 * c + r;
;                 if (rr < 38) {
;                     const u32x4 xw = __builtin_bit_cast(u32x4, buf[c & 1][r]);
; #pragma unroll
;                     for (int i = 0; i < 8; ++i) {
;                         const int j = rr - i;
;                         if (j >= 0 && j <= 30) {
;                             const f32x4 w0 = *(const LAS f32x4*)(cw + j * 512 + 8 * lane), w1 = *(const LAS f32x4*)(cw + j * 512 + 8 * lane + 4);
; #pragma unroll
;                             for (int e = 0; e < 4; ++e) { const float wl = (e < 2) ? w0[2 * e] : w1[2 * e - 4], wh = (e < 2) ? w0[2 * e + 1] : w1[2 * e - 3];
;                                 asm("v_fma_mix_f32 %0, %1, %2, %0 op_sel_hi:[0,1,0]" : "+v"(acc[i][2 * e]) : "v"(wl), "v"(xw[e]));
;                                 asm("v_fma_mix_f32 %0, %1, %2, %0 op_sel:[0,1,0] op_sel_hi:[0,1,0]" : "+v"(acc[i][2 * e + 1]) : "v"(wh), "v"(xw[e])); }
;                         }
;                     }
;                 }
;             }
	v_cvt_f32_f16_sdwa v221, v85 dst_sel:DWORD dst_unused:UNUSED_PAD src0_sel:WORD_1
	v_cvt_f32_f16_e32 v220, v85
	v_pk_fma_f32 v[160:161], v[64:65], v[220:221], v[160:161]
	v_cvt_f32_f16_sdwa v219, v84 dst_sel:DWORD dst_unused:UNUSED_PAD src0_sel:WORD_1
	v_cvt_f32_f16_e32 v218, v84
	v_pk_fma_f32 v[164:165], v[66:67], v[218:219], v[164:165]
	v_pk_fma_f32 v[150:151], v[60:61], v[240:241], v[150:151]
	v_pk_fma_f32 v[154:155], v[62:63], v[226:227], v[154:155]
	v_pk_fma_f32 v[152:153], v[56:57], v[220:221], v[152:153]
	v_pk_fma_f32 v[156:157], v[58:59], v[218:219], v[156:157]
	v_pk_fma_f32 v[142:143], v[44:45], v[240:241], v[142:143]
	v_pk_fma_f32 v[146:147], v[46:47], v[226:227], v[146:147]
	v_pk_fma_f32 v[144:145], v[40:41], v[220:221], v[144:145]
	v_pk_fma_f32 v[148:149], v[42:43], v[218:219], v[148:149]
	v_pk_fma_f32 v[134:135], v[28:29], v[240:241], v[134:135]
	v_pk_fma_f32 v[138:139], v[30:31], v[226:227], v[138:139]
	v_pk_fma_f32 v[136:137], v[24:25], v[220:221], v[136:137]
	v_pk_fma_f32 v[140:141], v[26:27], v[218:219], v[140:141]
	v_pk_fma_f32 v[126:127], v[12:13], v[240:241], v[126:127]
	v_pk_fma_f32 v[130:131], v[14:15], v[226:227], v[130:131]
	v_pk_fma_f32 v[128:129], v[8:9], v[220:221], v[128:129]
	v_pk_fma_f32 v[132:133], v[10:11], v[218:219], v[132:133]
	v_pk_fma_f32 v[118:119], v[20:21], v[240:241], v[118:119]
	v_pk_fma_f32 v[122:123], v[22:23], v[226:227], v[122:123]
	v_pk_fma_f32 v[120:121], v[16:17], v[220:221], v[120:121]
	v_pk_fma_f32 v[124:125], v[18:19], v[218:219], v[124:125]
	v_pk_fma_f32 v[102:103], v[36:37], v[240:241], v[102:103]
	v_pk_fma_f32 v[108:109], v[38:39], v[226:227], v[108:109]
	v_pk_fma_f32 v[106:107], v[32:33], v[220:221], v[106:107]
	v_pk_fma_f32 v[114:115], v[34:35], v[218:219], v[114:115]
	v_pk_fma_f32 v[104:105], v[52:53], v[240:241], v[104:105]
	v_pk_fma_f32 v[112:113], v[54:55], v[226:227], v[112:113]
	v_pk_fma_f32 v[110:111], v[48:49], v[220:221], v[110:111]
	v_pk_fma_f32 v[116:117], v[50:51], v[218:219], v[116:117]
	ds_read_b128 v[52:55], v166 offset:43008
	ds_read_b128 v[48:51], v166 offset:43024
	s_waitcnt lgkmcnt(1)
	v_cvt_f32_f16_sdwa v247, v83 dst_sel:DWORD dst_unused:UNUSED_PAD src0_sel:WORD_1
	v_cvt_f32_f16_e32 v246, v83
	v_pk_fma_f32 v[158:159], v[52:53], v[246:247], v[158:159]
	v_cvt_f32_f16_sdwa v225, v82 dst_sel:DWORD dst_unused:UNUSED_PAD src0_sel:WORD_1
	v_cvt_f32_f16_e32 v224, v82
	v_pk_fma_f32 v[162:163], v[54:55], v[224:225], v[162:163]
	s_waitcnt lgkmcnt(0)
	v_cvt_f32_f16_sdwa v235, v81 dst_sel:DWORD dst_unused:UNUSED_PAD src0_sel:WORD_1
	v_cvt_f32_f16_e32 v234, v81
	v_pk_fma_f32 v[160:161], v[48:49], v[234:235], v[160:161]
	v_cvt_f32_f16_sdwa v239, v80 dst_sel:DWORD dst_unused:UNUSED_PAD src0_sel:WORD_1
	v_cvt_f32_f16_e32 v238, v80
	v_pk_fma_f32 v[164:165], v[50:51], v[238:239], v[164:165]
	v_pk_fma_f32 v[150:151], v[68:69], v[246:247], v[150:151]
	v_pk_fma_f32 v[154:155], v[70:71], v[224:225], v[154:155]
	v_pk_fma_f32 v[152:153], v[64:65], v[234:235], v[152:153]
	v_pk_fma_f32 v[156:157], v[66:67], v[238:239], v[156:157]
	v_pk_fma_f32 v[142:143], v[60:61], v[246:247], v[142:143]
	v_pk_fma_f32 v[146:147], v[62:63], v[224:225], v[146:147]
	v_pk_fma_f32 v[144:145], v[56:57], v[234:235], v[144:145]
	v_pk_fma_f32 v[148:149], v[58:59], v[238:239], v[148:149]
	v_pk_fma_f32 v[134:135], v[44:45], v[246:247], v[134:135]
	v_pk_fma_f32 v[138:139], v[46:47], v[224:225], v[138:139]
	v_pk_fma_f32 v[136:137], v[40:41], v[234:235], v[136:137]
	v_pk_fma_f32 v[140:141], v[42:43], v[238:239], v[140:141]
	v_pk_fma_f32 v[126:127], v[28:29], v[246:247], v[126:127]
	v_pk_fma_f32 v[130:131], v[30:31], v[224:225], v[130:131]
	v_pk_fma_f32 v[128:129], v[24:25], v[234:235], v[128:129]
	v_pk_fma_f32 v[132:133], v[26:27], v[238:239], v[132:133]
	v_pk_fma_f32 v[118:119], v[12:13], v[246:247], v[118:119]
	v_pk_fma_f32 v[122:123], v[14:15], v[224:225], v[122:123]
	v_pk_fma_f32 v[120:121], v[8:9], v[234:235], v[120:121]
	v_pk_fma_f32 v[124:125], v[10:11], v[238:239], v[124:125]
	v_pk_fma_f32 v[102:103], v[20:21], v[246:247], v[102:103]
	v_pk_fma_f32 v[108:109], v[22:23], v[224:225], v[108:109]
	v_pk_fma_f32 v[106:107], v[16:17], v[234:235], v[106:107]
	v_pk_fma_f32 v[114:115], v[18:19], v[238:239], v[114:115]
	v_pk_fma_f32 v[104:105], v[36:37], v[246:247], v[104:105]
	v_pk_fma_f32 v[112:113], v[38:39], v[224:225], v[112:113]
	v_pk_fma_f32 v[110:111], v[32:33], v[234:235], v[110:111]
	v_pk_fma_f32 v[116:117], v[34:35], v[238:239], v[116:117]
	ds_read_b128 v[36:39], v166 offset:45056
	ds_read_b128 v[32:35], v166 offset:45072
	s_waitcnt lgkmcnt(1)
	v_cvt_f32_f16_sdwa v245, v79 dst_sel:DWORD dst_unused:UNUSED_PAD src0_sel:WORD_1
	v_cvt_f32_f16_e32 v244, v79
	v_pk_fma_f32 v[158:159], v[36:37], v[244:245], v[158:159]
	v_cvt_f32_f16_sdwa v223, v78 dst_sel:DWORD dst_unused:UNUSED_PAD src0_sel:WORD_1
	v_cvt_f32_f16_e32 v222, v78
	v_pk_fma_f32 v[162:163], v[38:39], v[222:223], v[162:163]
	s_waitcnt lgkmcnt(0)
; #define LAS __attribute__((address_space(3)))
; #define CONV_LOAD(cc) do { _Pragma("unroll") for (int r = 0; r < 8; ++r) { const int rr = 8 * (cc) + r; if (rr < 38) { const int d = rr - 30; const bool ok = (tl + d >= 0); \
;             const h8 x = *(const GAS h8*)(GLU + (size_t)(tok0 + (ok ? d : -tl)) * 512 + 8 * lane); buf[(cc) & 1][r] = ok ? x : zero8; } } } while (0)
; __device__ __forceinline__ void conv_phase(KP P, LAS unsigned char* lds, int gw, int NGW, int tid, int lane) {
;     ...
;         for (int c = 0; c < 5; ++c) {
;             __builtin_amdgcn_sched_barrier(0);
;             if (c + 1 < 5) CONV_LOAD(c + 1);
;             __builtin_amdgcn_sched_barrier(0);
; #pragma unroll
;             for (int r = 0; r < 8; ++r) {
;                 const int rr = 8 * c + r;
;                 if (rr < 38) {
;                     const u32x4 xw = __builtin_bit_cast(u32x4, buf[c & 1][r]);
; #pragma unroll
;                     for (int i = 0; i < 8; ++i) {
;                         const int j = rr - i;
;                         if (j >= 0 && j <= 30) {
;                             const f32x4 w0 = *(const LAS f32x4*)(cw + j * 512 + 8 * lane), w1 = *(const LAS f32x4*)(cw + j * 512 + 8 * lane + 4);
; #pragma unroll
;                             for (int e = 0; e < 4; ++e) { const float wl = (e < 2) ? w0[2 * e] : w1[2 * e - 4], wh = (e < 2) ? w0[2 * e + 1] : w1[2 * e - 3];
;                                 asm("v_fma_mix_f32 %0, %1, %2, %0 op_sel_hi:[0,1,0]" : "+v"(acc[i][2 * e]) : "v"(wl), "v"(xw[e]));
;                                 asm("v_fma_mix_f32 %0, %1, %2, %0 op_sel:[0,1,0] op_sel_hi:[0,1,0]" : "+v"(acc[i][2 * e + 1]) : "v"(wh), "v"(xw[e])); }
;                         }
;                     }
;                 }
;             }
	v_cvt_f32_f16_sdwa v243, v77 dst_sel:DWORD dst_unused:UNUSED_PAD src0_sel:WORD_1
	v_cvt_f32_f16_e32 v242, v77
	v_pk_fma_f32 v[160:161], v[32:33], v[242:243], v[160:161]
	v_cvt_f32_f16_sdwa v217, v76 dst_sel:DWORD dst_unused:UNUSED_PAD src0_sel:WORD_1
	v_cvt_f32_f16_e32 v216, v76
	v_pk_fma_f32 v[164:165], v[34:35], v[216:217], v[164:165]
	v_pk_fma_f32 v[150:151], v[52:53], v[244:245], v[150:151]
	v_pk_fma_f32 v[154:155], v[54:55], v[222:223], v[154:155]
	v_pk_fma_f32 v[152:153], v[48:49], v[242:243], v[152:153]
	v_pk_fma_f32 v[156:157], v[50:51], v[216:217], v[156:157]
	v_pk_fma_f32 v[142:143], v[68:69], v[244:245], v[142:143]
	v_pk_fma_f32 v[146:147], v[70:71], v[222:223], v[146:147]
	v_pk_fma_f32 v[144:145], v[64:65], v[242:243], v[144:145]
	v_pk_fma_f32 v[148:149], v[66:67], v[216:217], v[148:149]
	v_pk_fma_f32 v[134:135], v[60:61], v[244:245], v[134:135]
	v_pk_fma_f32 v[138:139], v[62:63], v[222:223], v[138:139]
	v_pk_fma_f32 v[136:137], v[56:57], v[242:243], v[136:137]
	v_pk_fma_f32 v[140:141], v[58:59], v[216:217], v[140:141]
	v_pk_fma_f32 v[126:127], v[44:45], v[244:245], v[126:127]
	v_pk_fma_f32 v[130:131], v[46:47], v[222:223], v[130:131]
	v_pk_fma_f32 v[128:129], v[40:41], v[242:243], v[128:129]
	v_pk_fma_f32 v[132:133], v[42:43], v[216:217], v[132:133]
	v_pk_fma_f32 v[118:119], v[28:29], v[244:245], v[118:119]
	v_pk_fma_f32 v[122:123], v[30:31], v[222:223], v[122:123]
	v_pk_fma_f32 v[120:121], v[24:25], v[242:243], v[120:121]
	v_pk_fma_f32 v[124:125], v[26:27], v[216:217], v[124:125]
	v_pk_fma_f32 v[102:103], v[12:13], v[244:245], v[102:103]
	v_pk_fma_f32 v[108:109], v[14:15], v[222:223], v[108:109]
	v_pk_fma_f32 v[106:107], v[8:9], v[242:243], v[106:107]
	v_pk_fma_f32 v[114:115], v[10:11], v[216:217], v[114:115]
	v_pk_fma_f32 v[104:105], v[20:21], v[244:245], v[104:105]
	v_pk_fma_f32 v[112:113], v[22:23], v[222:223], v[112:113]
	v_pk_fma_f32 v[110:111], v[16:17], v[242:243], v[110:111]
	v_pk_fma_f32 v[116:117], v[18:19], v[216:217], v[116:117]
	ds_read_b128 v[20:23], v166 offset:47104
	ds_read_b128 v[16:19], v166 offset:47120
	s_waitcnt lgkmcnt(1)
	v_cvt_f32_f16_sdwa v215, v75 dst_sel:DWORD dst_unused:UNUSED_PAD src0_sel:WORD_1
	v_cvt_f32_f16_e32 v214, v75
	v_pk_fma_f32 v[158:159], v[20:21], v[214:215], v[158:159]
	v_cvt_f32_f16_sdwa v237, v74 dst_sel:DWORD dst_unused:UNUSED_PAD src0_sel:WORD_1
	v_cvt_f32_f16_e32 v236, v74
	v_pk_fma_f32 v[162:163], v[22:23], v[236:237], v[162:163]
	s_waitcnt lgkmcnt(0)
	v_cvt_f32_f16_sdwa v229, v73 dst_sel:DWORD dst_unused:UNUSED_PAD src0_sel:WORD_1
	v_cvt_f32_f16_e32 v228, v73
	v_pk_fma_f32 v[160:161], v[16:17], v[228:229], v[160:161]
	v_cvt_f32_f16_sdwa v233, v72 dst_sel:DWORD dst_unused:UNUSED_PAD src0_sel:WORD_1
	v_cvt_f32_f16_e32 v232, v72
	v_pk_fma_f32 v[164:165], v[18:19], v[232:233], v[164:165]
	v_pk_fma_f32 v[150:151], v[36:37], v[214:215], v[150:151]
	v_pk_fma_f32 v[154:155], v[38:39], v[236:237], v[154:155]
	v_pk_fma_f32 v[152:153], v[32:33], v[228:229], v[152:153]
	v_pk_fma_f32 v[156:157], v[34:35], v[232:233], v[156:157]
	v_pk_fma_f32 v[142:143], v[52:53], v[214:215], v[142:143]
	v_pk_fma_f32 v[146:147], v[54:55], v[236:237], v[146:147]
	v_pk_fma_f32 v[144:145], v[48:49], v[228:229], v[144:145]
	v_pk_fma_f32 v[148:149], v[50:51], v[232:233], v[148:149]
	v_pk_fma_f32 v[134:135], v[68:69], v[214:215], v[134:135]
	v_pk_fma_f32 v[138:139], v[70:71], v[236:237], v[138:139]
	v_pk_fma_f32 v[136:137], v[64:65], v[228:229], v[136:137]
	v_pk_fma_f32 v[140:141], v[66:67], v[232:233], v[140:141]
	v_pk_fma_f32 v[126:127], v[60:61], v[214:215], v[126:127]
	v_pk_fma_f32 v[130:131], v[62:63], v[236:237], v[130:131]
	v_pk_fma_f32 v[128:129], v[56:57], v[228:229], v[128:129]
	v_pk_fma_f32 v[132:133], v[58:59], v[232:233], v[132:133]
	v_pk_fma_f32 v[118:119], v[44:45], v[214:215], v[118:119]
	v_pk_fma_f32 v[122:123], v[46:47], v[236:237], v[122:123]
	v_pk_fma_f32 v[120:121], v[40:41], v[228:229], v[120:121]
	v_pk_fma_f32 v[124:125], v[42:43], v[232:233], v[124:125]
	v_pk_fma_f32 v[102:103], v[28:29], v[214:215], v[102:103]
	v_pk_fma_f32 v[108:109], v[30:31], v[236:237], v[108:109]
	v_pk_fma_f32 v[106:107], v[24:25], v[228:229], v[106:107]
	v_pk_fma_f32 v[114:115], v[26:27], v[232:233], v[114:115]
	v_pk_fma_f32 v[104:105], v[12:13], v[214:215], v[104:105]
	v_pk_fma_f32 v[112:113], v[14:15], v[236:237], v[112:113]
	v_pk_fma_f32 v[110:111], v[8:9], v[228:229], v[110:111]
	v_pk_fma_f32 v[116:117], v[10:11], v[232:233], v[116:117]
	s_add_i32 s4, s24, -5
	s_ashr_i32 s5, s4, 31
	s_lshl_b64 s[38:39], s[4:5], 10
	s_add_i32 s4, s24, -4
	s_ashr_i32 s5, s4, 31
	s_lshl_b64 s[26:27], s[4:5], 10
	s_add_i32 s4, s24, -3
	s_ashr_i32 s5, s4, 31
	s_lshl_b64 s[20:21], s[4:5], 10
	s_add_i32 s4, s24, -2
	s_ashr_i32 s5, s4, 31
	s_lshl_b64 s[18:19], s[4:5], 10
	s_add_i32 s4, s24, -1
	v_lshl_add_u64 v[8:9], v[96:97], 0, s[38:39]
	v_lshl_add_u64 v[10:11], v[96:97], 0, s[26:27]
	s_ashr_i32 s5, s4, 31
	s_ashr_i32 s25, s24, 31
	global_load_dwordx4 v[28:31], v[8:9], off
	global_load_dwordx4 v[24:27], v[10:11], off
	v_lshl_add_u64 v[8:9], v[96:97], 0, s[20:21]
	v_lshl_add_u64 v[10:11], v[96:97], 0, s[18:19]
	s_lshl_b64 s[16:17], s[4:5], 10
	s_lshl_b64 s[14:15], s[24:25], 10
	global_load_dwordx4 v[20:23], v[8:9], off
	global_load_dwordx4 v[16:19], v[10:11], off
	v_lshl_add_u64 v[8:9], v[96:97], 0, s[16:17]
	v_lshl_add_u64 v[10:11], v[96:97], 0, s[14:15]
	global_load_dwordx4 v[12:15], v[8:9], off
	s_nop 0
	global_load_dwordx4 v[8:11], v[10:11], off
	ds_read_b128 v[36:39], v166 offset:49152
	ds_read_b128 v[32:35], v166 offset:49168
	ds_read_b128 v[48:51], v166 offset:47104
	ds_read_b128 v[40:43], v166 offset:47120
	s_waitcnt lgkmcnt(1)
; #define LAS __attribute__((address_space(3)))
; #define CONV_LOAD(cc) do { _Pragma("unroll") for (int r = 0; r < 8; ++r) { const int rr = 8 * (cc) + r; if (rr < 38) { const int d = rr - 30; const bool ok = (tl + d >= 0); \
;             const h8 x = *(const GAS h8*)(GLU + (size_t)(tok0 + (ok ? d : -tl)) * 512 + 8 * lane); buf[(cc) & 1][r] = ok ? x : zero8; } } } while (0)
; __device__ __forceinline__ void conv_phase(KP P, LAS unsigned char* lds, int gw, int NGW, int tid, int lane) {
;     ...
;         for (int c = 0; c < 5; ++c) {
;             __builtin_amdgcn_sched_barrier(0);
;             if (c + 1 < 5) CONV_LOAD(c + 1);
;             __builtin_amdgcn_sched_barrier(0);
; #pragma unroll
;             for (int r = 0; r < 8; ++r) {
;                 const int rr = 8 * c + r;
;                 if (rr < 38) {
;                     const u32x4 xw = __builtin_bit_cast(u32x4, buf[c & 1][r]);
; #pragma unroll
;                     for (int i = 0; i < 8; ++i) {
;                         const int j = rr - i;
;                         if (j >= 0 && j <= 30) {
;                             const f32x4 w0 = *(const LAS f32x4*)(cw + j * 512 + 8 * lane), w1 = *(const LAS f32x4*)(cw + j * 512 + 8 * lane + 4);
; #pragma unroll
;                             for (int e = 0; e < 4; ++e) { const float wl = (e < 2) ? w0[2 * e] : w1[2 * e - 4], wh = (e < 2) ? w0[2 * e + 1] : w1[2 * e - 3];
;                                 asm("v_fma_mix_f32 %0, %1, %2, %0 op_sel_hi:[0,1,0]" : "+v"(acc[i][2 * e]) : "v"(wl), "v"(xw[e]));
;                                 asm("v_fma_mix_f32 %0, %1, %2, %0 op_sel:[0,1,0] op_sel_hi:[0,1,0]" : "+v"(acc[i][2 * e + 1]) : "v"(wh), "v"(xw[e])); }
;                         }
;                     }
;                 }
;             }
	v_cvt_f32_f16_sdwa v231, v209 dst_sel:DWORD dst_unused:UNUSED_PAD src0_sel:WORD_1
	v_cvt_f32_f16_e32 v230, v209
	v_pk_fma_f32 v[150:151], v[48:49], v[230:231], v[150:151]
	v_cvt_f32_f16_sdwa v241, v208 dst_sel:DWORD dst_unused:UNUSED_PAD src0_sel:WORD_1
	v_cvt_f32_f16_e32 v240, v208
	v_pk_fma_f32 v[154:155], v[50:51], v[240:241], v[154:155]
	s_waitcnt lgkmcnt(0)
	v_fma_mix_f32 v152, v40, v207, v152 op_sel_hi:[0,1,0]
	ds_read_b128 v[68:71], v166 offset:45056
	ds_read_b128 v[64:67], v166 offset:45072
	v_fma_mix_f32 v153, v41, v207, v153 op_sel:[0,1,0] op_sel_hi:[0,1,0]
	v_cvt_f32_f16_sdwa v227, v206 dst_sel:DWORD dst_unused:UNUSED_PAD src0_sel:WORD_1
	v_cvt_f32_f16_e32 v226, v206
	v_pk_fma_f32 v[156:157], v[42:43], v[226:227], v[156:157]
	s_waitcnt lgkmcnt(1)
	v_pk_fma_f32 v[142:143], v[68:69], v[230:231], v[142:143]
	v_pk_fma_f32 v[146:147], v[70:71], v[240:241], v[146:147]
	s_waitcnt lgkmcnt(0)
	v_fma_mix_f32 v144, v64, v207, v144 op_sel_hi:[0,1,0]
	ds_read_b128 v[84:87], v166 offset:43008
	ds_read_b128 v[80:83], v166 offset:43024
	v_fma_mix_f32 v145, v65, v207, v145 op_sel:[0,1,0] op_sel_hi:[0,1,0]
	v_pk_fma_f32 v[148:149], v[66:67], v[226:227], v[148:149]
	s_waitcnt lgkmcnt(1)
	v_pk_fma_f32 v[134:135], v[84:85], v[230:231], v[134:135]
	v_pk_fma_f32 v[138:139], v[86:87], v[240:241], v[138:139]
	s_waitcnt lgkmcnt(0)
	v_fma_mix_f32 v136, v80, v207, v136 op_sel_hi:[0,1,0]
	ds_read_b128 v[92:95], v166 offset:40960
	ds_read_b128 v[88:91], v166 offset:40976
	v_fma_mix_f32 v137, v81, v207, v137 op_sel:[0,1,0] op_sel_hi:[0,1,0]
	v_pk_fma_f32 v[140:141], v[82:83], v[226:227], v[140:141]
	s_waitcnt lgkmcnt(1)
	v_pk_fma_f32 v[126:127], v[92:93], v[230:231], v[126:127]
	v_pk_fma_f32 v[130:131], v[94:95], v[240:241], v[130:131]
	s_waitcnt lgkmcnt(0)
	v_fma_mix_f32 v128, v88, v207, v128 op_sel_hi:[0,1,0]
	ds_read_b128 v[76:79], v166 offset:38912
	ds_read_b128 v[72:75], v166 offset:38928
	v_fma_mix_f32 v129, v89, v207, v129 op_sel:[0,1,0] op_sel_hi:[0,1,0]
	v_pk_fma_f32 v[132:133], v[90:91], v[226:227], v[132:133]
	s_waitcnt lgkmcnt(1)
	v_pk_fma_f32 v[118:119], v[76:77], v[230:231], v[118:119]
	v_pk_fma_f32 v[122:123], v[78:79], v[240:241], v[122:123]
	s_waitcnt lgkmcnt(0)
	v_fma_mix_f32 v120, v72, v207, v120 op_sel_hi:[0,1,0]
	ds_read_b128 v[60:63], v166 offset:36864
	ds_read_b128 v[56:59], v166 offset:36880
	v_fma_mix_f32 v121, v73, v207, v121 op_sel:[0,1,0] op_sel_hi:[0,1,0]
	v_pk_fma_f32 v[124:125], v[74:75], v[226:227], v[124:125]
	s_waitcnt lgkmcnt(1)
	v_pk_fma_f32 v[102:103], v[60:61], v[230:231], v[102:103]
	v_pk_fma_f32 v[108:109], v[62:63], v[240:241], v[108:109]
	s_waitcnt lgkmcnt(0)
	v_fma_mix_f32 v106, v56, v207, v106 op_sel_hi:[0,1,0]
	ds_read_b128 v[44:47], v166 offset:34816
	ds_read_b128 v[210:213], v166 offset:34832
	v_fma_mix_f32 v107, v57, v207, v107 op_sel:[0,1,0] op_sel_hi:[0,1,0]
	v_pk_fma_f32 v[114:115], v[58:59], v[226:227], v[114:115]
	s_waitcnt lgkmcnt(1)
	v_pk_fma_f32 v[104:105], v[44:45], v[230:231], v[104:105]
	v_pk_fma_f32 v[112:113], v[46:47], v[240:241], v[112:113]
	s_waitcnt lgkmcnt(0)
	v_cvt_f32_f16_sdwa v219, v207 dst_sel:DWORD dst_unused:UNUSED_PAD src0_sel:WORD_1
	v_cvt_f32_f16_e32 v218, v207
	v_pk_fma_f32 v[110:111], v[210:211], v[218:219], v[110:111]
	v_pk_fma_f32 v[116:117], v[212:213], v[226:227], v[116:117]
	v_pk_fma_f32 v[158:159], v[36:37], v[230:231], v[158:159]
	v_pk_fma_f32 v[162:163], v[38:39], v[240:241], v[162:163]
	v_pk_fma_f32 v[160:161], v[32:33], v[218:219], v[160:161]
	v_pk_fma_f32 v[164:165], v[34:35], v[226:227], v[164:165]
	v_cvt_f32_f16_sdwa v221, v200 dst_sel:DWORD dst_unused:UNUSED_PAD src0_sel:WORD_1
	v_cvt_f32_f16_e32 v220, v200
	v_pk_fma_f32 v[150:151], v[36:37], v[220:221], v[150:151]
	v_cvt_f32_f16_sdwa v239, v199 dst_sel:DWORD dst_unused:UNUSED_PAD src0_sel:WORD_1
	v_cvt_f32_f16_e32 v238, v199
	v_pk_fma_f32 v[154:155], v[38:39], v[238:239], v[154:155]
	v_cvt_f32_f16_sdwa v235, v198 dst_sel:DWORD dst_unused:UNUSED_PAD src0_sel:WORD_1
	v_cvt_f32_f16_e32 v234, v198
	v_pk_fma_f32 v[152:153], v[32:33], v[234:235], v[152:153]
	v_cvt_f32_f16_sdwa v225, v197 dst_sel:DWORD dst_unused:UNUSED_PAD src0_sel:WORD_1
	v_cvt_f32_f16_e32 v224, v197
	v_pk_fma_f32 v[156:157], v[34:35], v[224:225], v[156:157]
	v_pk_fma_f32 v[142:143], v[48:49], v[220:221], v[142:143]
	v_pk_fma_f32 v[146:147], v[50:51], v[238:239], v[146:147]
	v_pk_fma_f32 v[144:145], v[40:41], v[234:235], v[144:145]
	v_pk_fma_f32 v[148:149], v[42:43], v[224:225], v[148:149]
	v_pk_fma_f32 v[134:135], v[68:69], v[220:221], v[134:135]
	v_pk_fma_f32 v[138:139], v[70:71], v[238:239], v[138:139]
	v_pk_fma_f32 v[136:137], v[64:65], v[234:235], v[136:137]
	v_pk_fma_f32 v[140:141], v[66:67], v[224:225], v[140:141]
	v_pk_fma_f32 v[126:127], v[84:85], v[220:221], v[126:127]
	v_pk_fma_f32 v[130:131], v[86:87], v[238:239], v[130:131]
	v_pk_fma_f32 v[128:129], v[80:81], v[234:235], v[128:129]
	v_pk_fma_f32 v[132:133], v[82:83], v[224:225], v[132:133]
	v_pk_fma_f32 v[118:119], v[92:93], v[220:221], v[118:119]
	v_pk_fma_f32 v[122:123], v[94:95], v[238:239], v[122:123]
	v_pk_fma_f32 v[120:121], v[88:89], v[234:235], v[120:121]
	v_pk_fma_f32 v[124:125], v[90:91], v[224:225], v[124:125]
	v_pk_fma_f32 v[102:103], v[76:77], v[220:221], v[102:103]
	v_pk_fma_f32 v[108:109], v[78:79], v[238:239], v[108:109]
	v_pk_fma_f32 v[106:107], v[72:73], v[234:235], v[106:107]
	v_pk_fma_f32 v[114:115], v[74:75], v[224:225], v[114:115]
	v_pk_fma_f32 v[104:105], v[60:61], v[220:221], v[104:105]
	v_pk_fma_f32 v[112:113], v[62:63], v[238:239], v[112:113]
	s_nop 0
	v_pk_fma_f32 v[110:111], v[56:57], v[234:235], v[110:111]
	v_pk_fma_f32 v[116:117], v[58:59], v[224:225], v[116:117]
	ds_read_b128 v[52:55], v166 offset:51200
	ds_read_b128 v[44:47], v166 offset:51216
	s_waitcnt lgkmcnt(1)
; #define LAS __attribute__((address_space(3)))
; #define CONV_LOAD(cc) do { _Pragma("unroll") for (int r = 0; r < 8; ++r) { const int rr = 8 * (cc) + r; if (rr < 38) { const int d = rr - 30; const bool ok = (tl + d >= 0); \
;             const h8 x = *(const GAS h8*)(GLU + (size_t)(tok0 + (ok ? d : -tl)) * 512 + 8 * lane); buf[(cc) & 1][r] = ok ? x : zero8; } } } while (0)
; __device__ __forceinline__ void conv_phase(KP P, LAS unsigned char* lds, int gw, int NGW, int tid, int lane) {
;     ...
;         for (int c = 0; c < 5; ++c) {
;             __builtin_amdgcn_sched_barrier(0);
;             if (c + 1 < 5) CONV_LOAD(c + 1);
;             __builtin_amdgcn_sched_barrier(0);
; #pragma unroll
;             for (int r = 0; r < 8; ++r) {
;                 const int rr = 8 * c + r;
;                 if (rr < 38) {
;                     const u32x4 xw = __builtin_bit_cast(u32x4, buf[c & 1][r]);
; #pragma unroll
;                     for (int i = 0; i < 8; ++i) {
;                         const int j = rr - i;
;                         if (j >= 0 && j <= 30) {
;                             const f32x4 w0 = *(const LAS f32x4*)(cw + j * 512 + 8 * lane), w1 = *(const LAS f32x4*)(cw + j * 512 + 8 * lane + 4);
; #pragma unroll
;                             for (int e = 0; e < 4; ++e) { const float wl = (e < 2) ? w0[2 * e] : w1[2 * e - 4], wh = (e < 2) ? w0[2 * e + 1] : w1[2 * e - 3];
;                                 asm("v_fma_mix_f32 %0, %1, %2, %0 op_sel_hi:[0,1,0]" : "+v"(acc[i][2 * e]) : "v"(wl), "v"(xw[e]));
;                                 asm("v_fma_mix_f32 %0, %1, %2, %0 op_sel:[0,1,0] op_sel_hi:[0,1,0]" : "+v"(acc[i][2 * e + 1]) : "v"(wh), "v"(xw[e])); }
;                         }
;                     }
;                 }
;             }
	v_pk_fma_f32 v[158:159], v[52:53], v[220:221], v[158:159]
	v_pk_fma_f32 v[162:163], v[54:55], v[238:239], v[162:163]
	s_waitcnt lgkmcnt(0)
	v_pk_fma_f32 v[160:161], v[44:45], v[234:235], v[160:161]
	v_pk_fma_f32 v[164:165], v[46:47], v[224:225], v[164:165]
	v_cvt_f32_f16_sdwa v247, v191 dst_sel:DWORD dst_unused:UNUSED_PAD src0_sel:WORD_1
	v_cvt_f32_f16_e32 v246, v191
	v_pk_fma_f32 v[150:151], v[52:53], v[246:247], v[150:151]
	v_cvt_f32_f16_sdwa v217, v190 dst_sel:DWORD dst_unused:UNUSED_PAD src0_sel:WORD_1
	v_cvt_f32_f16_e32 v216, v190
	v_pk_fma_f32 v[154:155], v[54:55], v[216:217], v[154:155]
	v_cvt_f32_f16_sdwa v243, v189 dst_sel:DWORD dst_unused:UNUSED_PAD src0_sel:WORD_1
	v_cvt_f32_f16_e32 v242, v189
	v_pk_fma_f32 v[152:153], v[44:45], v[242:243], v[152:153]
	v_cvt_f32_f16_sdwa v223, v188 dst_sel:DWORD dst_unused:UNUSED_PAD src0_sel:WORD_1
	v_cvt_f32_f16_e32 v222, v188
	v_pk_fma_f32 v[156:157], v[46:47], v[222:223], v[156:157]
	v_pk_fma_f32 v[142:143], v[36:37], v[246:247], v[142:143]
	v_pk_fma_f32 v[146:147], v[38:39], v[216:217], v[146:147]
	v_pk_fma_f32 v[144:145], v[32:33], v[242:243], v[144:145]
	v_pk_fma_f32 v[148:149], v[34:35], v[222:223], v[148:149]
	v_pk_fma_f32 v[134:135], v[48:49], v[246:247], v[134:135]
	v_pk_fma_f32 v[138:139], v[50:51], v[216:217], v[138:139]
	v_pk_fma_f32 v[136:137], v[40:41], v[242:243], v[136:137]
	v_pk_fma_f32 v[140:141], v[42:43], v[222:223], v[140:141]
	v_pk_fma_f32 v[126:127], v[68:69], v[246:247], v[126:127]
	v_pk_fma_f32 v[130:131], v[70:71], v[216:217], v[130:131]
	v_pk_fma_f32 v[128:129], v[64:65], v[242:243], v[128:129]
	v_pk_fma_f32 v[132:133], v[66:67], v[222:223], v[132:133]
	v_pk_fma_f32 v[118:119], v[84:85], v[246:247], v[118:119]
	v_pk_fma_f32 v[122:123], v[86:87], v[216:217], v[122:123]
	v_pk_fma_f32 v[120:121], v[80:81], v[242:243], v[120:121]
	v_pk_fma_f32 v[124:125], v[82:83], v[222:223], v[124:125]
	v_pk_fma_f32 v[102:103], v[92:93], v[246:247], v[102:103]
	v_pk_fma_f32 v[108:109], v[94:95], v[216:217], v[108:109]
	v_pk_fma_f32 v[106:107], v[88:89], v[242:243], v[106:107]
	v_pk_fma_f32 v[114:115], v[90:91], v[222:223], v[114:115]
	v_pk_fma_f32 v[104:105], v[76:77], v[246:247], v[104:105]
	v_pk_fma_f32 v[112:113], v[78:79], v[216:217], v[112:113]
	v_pk_fma_f32 v[110:111], v[72:73], v[242:243], v[110:111]
	v_pk_fma_f32 v[116:117], v[74:75], v[222:223], v[116:117]
	ds_read_b128 v[60:63], v166 offset:53248
	ds_read_b128 v[56:59], v166 offset:53264
	s_waitcnt lgkmcnt(1)
	v_pk_fma_f32 v[158:159], v[60:61], v[246:247], v[158:159]
	v_pk_fma_f32 v[162:163], v[62:63], v[216:217], v[162:163]
	s_waitcnt lgkmcnt(0)
	v_pk_fma_f32 v[160:161], v[56:57], v[242:243], v[160:161]
	v_pk_fma_f32 v[164:165], v[58:59], v[222:223], v[164:165]
	v_cvt_f32_f16_sdwa v245, v187 dst_sel:DWORD dst_unused:UNUSED_PAD src0_sel:WORD_1
	v_cvt_f32_f16_e32 v244, v187
	v_pk_fma_f32 v[150:151], v[60:61], v[244:245], v[150:151]
	v_cvt_f32_f16_sdwa v233, v186 dst_sel:DWORD dst_unused:UNUSED_PAD src0_sel:WORD_1
	v_cvt_f32_f16_e32 v232, v186
	v_pk_fma_f32 v[154:155], v[62:63], v[232:233], v[154:155]
	v_cvt_f32_f16_sdwa v229, v185 dst_sel:DWORD dst_unused:UNUSED_PAD src0_sel:WORD_1
	v_cvt_f32_f16_e32 v228, v185
	v_pk_fma_f32 v[152:153], v[56:57], v[228:229], v[152:153]
	v_cvt_f32_f16_sdwa v237, v184 dst_sel:DWORD dst_unused:UNUSED_PAD src0_sel:WORD_1
	v_cvt_f32_f16_e32 v236, v184
	v_pk_fma_f32 v[156:157], v[58:59], v[236:237], v[156:157]
	v_pk_fma_f32 v[142:143], v[52:53], v[244:245], v[142:143]
	v_pk_fma_f32 v[146:147], v[54:55], v[232:233], v[146:147]
	v_pk_fma_f32 v[144:145], v[44:45], v[228:229], v[144:145]
	v_pk_fma_f32 v[148:149], v[46:47], v[236:237], v[148:149]
	v_pk_fma_f32 v[134:135], v[36:37], v[244:245], v[134:135]
	v_pk_fma_f32 v[138:139], v[38:39], v[232:233], v[138:139]
	v_pk_fma_f32 v[136:137], v[32:33], v[228:229], v[136:137]
	v_pk_fma_f32 v[140:141], v[34:35], v[236:237], v[140:141]
	v_pk_fma_f32 v[126:127], v[48:49], v[244:245], v[126:127]
	v_pk_fma_f32 v[130:131], v[50:51], v[232:233], v[130:131]
	v_pk_fma_f32 v[128:129], v[40:41], v[228:229], v[128:129]
	v_pk_fma_f32 v[132:133], v[42:43], v[236:237], v[132:133]
	v_pk_fma_f32 v[118:119], v[68:69], v[244:245], v[118:119]
	v_pk_fma_f32 v[122:123], v[70:71], v[232:233], v[122:123]
	v_pk_fma_f32 v[120:121], v[64:65], v[228:229], v[120:121]
	v_pk_fma_f32 v[124:125], v[66:67], v[236:237], v[124:125]
	v_pk_fma_f32 v[102:103], v[84:85], v[244:245], v[102:103]
	v_pk_fma_f32 v[108:109], v[86:87], v[232:233], v[108:109]
	v_pk_fma_f32 v[106:107], v[80:81], v[228:229], v[106:107]
	v_pk_fma_f32 v[114:115], v[82:83], v[236:237], v[114:115]
	v_pk_fma_f32 v[104:105], v[92:93], v[244:245], v[104:105]
	v_pk_fma_f32 v[112:113], v[94:95], v[232:233], v[112:113]
	v_pk_fma_f32 v[110:111], v[88:89], v[228:229], v[110:111]
	v_pk_fma_f32 v[116:117], v[90:91], v[236:237], v[116:117]
	ds_read_b128 v[76:79], v166 offset:55296
	ds_read_b128 v[72:75], v166 offset:55312
	s_waitcnt lgkmcnt(1)
	v_pk_fma_f32 v[158:159], v[76:77], v[244:245], v[158:159]
	v_pk_fma_f32 v[162:163], v[78:79], v[232:233], v[162:163]
	s_waitcnt lgkmcnt(0)
; #define LAS __attribute__((address_space(3)))
; #define CONV_LOAD(cc) do { _Pragma("unroll") for (int r = 0; r < 8; ++r) { const int rr = 8 * (cc) + r; if (rr < 38) { const int d = rr - 30; const bool ok = (tl + d >= 0); \
;             const h8 x = *(const GAS h8*)(GLU + (size_t)(tok0 + (ok ? d : -tl)) * 512 + 8 * lane); buf[(cc) & 1][r] = ok ? x : zero8; } } } while (0)
; __device__ __forceinline__ void conv_phase(KP P, LAS unsigned char* lds, int gw, int NGW, int tid, int lane) {
;     ...
;         for (int c = 0; c < 5; ++c) {
;             __builtin_amdgcn_sched_barrier(0);
;             if (c + 1 < 5) CONV_LOAD(c + 1);
;             __builtin_amdgcn_sched_barrier(0);
; #pragma unroll
;             for (int r = 0; r < 8; ++r) {
;                 const int rr = 8 * c + r;
;                 if (rr < 38) {
;                     const u32x4 xw = __builtin_bit_cast(u32x4, buf[c & 1][r]);
; #pragma unroll
;                     for (int i = 0; i < 8; ++i) {
;                         const int j = rr - i;
;                         if (j >= 0 && j <= 30) {
;                             const f32x4 w0 = *(const LAS f32x4*)(cw + j * 512 + 8 * lane), w1 = *(const LAS f32x4*)(cw + j * 512 + 8 * lane + 4);
; #pragma unroll
;                             for (int e = 0; e < 4; ++e) { const float wl = (e < 2) ? w0[2 * e] : w1[2 * e - 4], wh = (e < 2) ? w0[2 * e + 1] : w1[2 * e - 3];
;                                 asm("v_fma_mix_f32 %0, %1, %2, %0 op_sel_hi:[0,1,0]" : "+v"(acc[i][2 * e]) : "v"(wl), "v"(xw[e]));
;                                 asm("v_fma_mix_f32 %0, %1, %2, %0 op_sel:[0,1,0] op_sel_hi:[0,1,0]" : "+v"(acc[i][2 * e + 1]) : "v"(wh), "v"(xw[e])); }
;                         }
;                     }
;                 }
;             }
	v_pk_fma_f32 v[160:161], v[72:73], v[228:229], v[160:161]
	v_pk_fma_f32 v[164:165], v[74:75], v[236:237], v[164:165]
	v_cvt_f32_f16_sdwa v215, v183 dst_sel:DWORD dst_unused:UNUSED_PAD src0_sel:WORD_1
	v_cvt_f32_f16_e32 v214, v183
	v_pk_fma_f32 v[150:151], v[76:77], v[214:215], v[150:151]
	v_cvt_f32_f16_sdwa v231, v182 dst_sel:DWORD dst_unused:UNUSED_PAD src0_sel:WORD_1
	v_cvt_f32_f16_e32 v230, v182
	v_pk_fma_f32 v[154:155], v[78:79], v[230:231], v[154:155]
	v_cvt_f32_f16_sdwa v241, v181 dst_sel:DWORD dst_unused:UNUSED_PAD src0_sel:WORD_1
	v_cvt_f32_f16_e32 v240, v181
	v_pk_fma_f32 v[152:153], v[72:73], v[240:241], v[152:153]
	v_cvt_f32_f16_sdwa v219, v180 dst_sel:DWORD dst_unused:UNUSED_PAD src0_sel:WORD_1
	v_cvt_f32_f16_e32 v218, v180
	v_pk_fma_f32 v[156:157], v[74:75], v[218:219], v[156:157]
	v_pk_fma_f32 v[142:143], v[60:61], v[214:215], v[142:143]
	v_pk_fma_f32 v[146:147], v[62:63], v[230:231], v[146:147]
	v_pk_fma_f32 v[144:145], v[56:57], v[240:241], v[144:145]
	v_pk_fma_f32 v[148:149], v[58:59], v[218:219], v[148:149]
	v_pk_fma_f32 v[134:135], v[52:53], v[214:215], v[134:135]
	v_pk_fma_f32 v[138:139], v[54:55], v[230:231], v[138:139]
	v_pk_fma_f32 v[136:137], v[44:45], v[240:241], v[136:137]
	v_pk_fma_f32 v[140:141], v[46:47], v[218:219], v[140:141]
	v_pk_fma_f32 v[126:127], v[36:37], v[214:215], v[126:127]
	v_pk_fma_f32 v[130:131], v[38:39], v[230:231], v[130:131]
	v_pk_fma_f32 v[128:129], v[32:33], v[240:241], v[128:129]
	v_pk_fma_f32 v[132:133], v[34:35], v[218:219], v[132:133]
	v_pk_fma_f32 v[118:119], v[48:49], v[214:215], v[118:119]
	v_pk_fma_f32 v[122:123], v[50:51], v[230:231], v[122:123]
	v_pk_fma_f32 v[120:121], v[40:41], v[240:241], v[120:121]
	v_pk_fma_f32 v[124:125], v[42:43], v[218:219], v[124:125]
	v_pk_fma_f32 v[102:103], v[68:69], v[214:215], v[102:103]
	v_pk_fma_f32 v[108:109], v[70:71], v[230:231], v[108:109]
	v_pk_fma_f32 v[106:107], v[64:65], v[240:241], v[106:107]
	v_pk_fma_f32 v[114:115], v[66:67], v[218:219], v[114:115]
	v_pk_fma_f32 v[104:105], v[84:85], v[214:215], v[104:105]
	v_pk_fma_f32 v[112:113], v[86:87], v[230:231], v[112:113]
	v_pk_fma_f32 v[110:111], v[80:81], v[240:241], v[110:111]
	v_pk_fma_f32 v[116:117], v[82:83], v[218:219], v[116:117]
	ds_read_b128 v[92:95], v166 offset:57344
	ds_read_b128 v[88:91], v166 offset:57360
	s_waitcnt lgkmcnt(1)
	v_pk_fma_f32 v[158:159], v[92:93], v[214:215], v[158:159]
	v_pk_fma_f32 v[162:163], v[94:95], v[230:231], v[162:163]
	s_waitcnt lgkmcnt(0)
	v_pk_fma_f32 v[160:161], v[88:89], v[240:241], v[160:161]
	v_pk_fma_f32 v[164:165], v[90:91], v[218:219], v[164:165]
	v_cvt_f32_f16_sdwa v227, v179 dst_sel:DWORD dst_unused:UNUSED_PAD src0_sel:WORD_1
	v_cvt_f32_f16_e32 v226, v179
	v_pk_fma_f32 v[150:151], v[92:93], v[226:227], v[150:151]
	v_cvt_f32_f16_sdwa v221, v178 dst_sel:DWORD dst_unused:UNUSED_PAD src0_sel:WORD_1
	v_cvt_f32_f16_e32 v220, v178
	v_pk_fma_f32 v[154:155], v[94:95], v[220:221], v[154:155]
	v_cvt_f32_f16_sdwa v239, v177 dst_sel:DWORD dst_unused:UNUSED_PAD src0_sel:WORD_1
	v_cvt_f32_f16_e32 v238, v177
	v_pk_fma_f32 v[152:153], v[88:89], v[238:239], v[152:153]
	v_cvt_f32_f16_sdwa v235, v176 dst_sel:DWORD dst_unused:UNUSED_PAD src0_sel:WORD_1
	v_cvt_f32_f16_e32 v234, v176
	v_pk_fma_f32 v[156:157], v[90:91], v[234:235], v[156:157]
	v_pk_fma_f32 v[142:143], v[76:77], v[226:227], v[142:143]
	v_pk_fma_f32 v[146:147], v[78:79], v[220:221], v[146:147]
	v_pk_fma_f32 v[144:145], v[72:73], v[238:239], v[144:145]
	v_pk_fma_f32 v[148:149], v[74:75], v[234:235], v[148:149]
	v_pk_fma_f32 v[134:135], v[60:61], v[226:227], v[134:135]
	v_pk_fma_f32 v[138:139], v[62:63], v[220:221], v[138:139]
	v_pk_fma_f32 v[136:137], v[56:57], v[238:239], v[136:137]
	v_pk_fma_f32 v[140:141], v[58:59], v[234:235], v[140:141]
	v_pk_fma_f32 v[126:127], v[52:53], v[226:227], v[126:127]
	v_pk_fma_f32 v[130:131], v[54:55], v[220:221], v[130:131]
	v_pk_fma_f32 v[128:129], v[44:45], v[238:239], v[128:129]
	v_pk_fma_f32 v[132:133], v[46:47], v[234:235], v[132:133]
	v_pk_fma_f32 v[118:119], v[36:37], v[226:227], v[118:119]
	v_pk_fma_f32 v[122:123], v[38:39], v[220:221], v[122:123]
	v_pk_fma_f32 v[120:121], v[32:33], v[238:239], v[120:121]
	v_pk_fma_f32 v[124:125], v[34:35], v[234:235], v[124:125]
	v_pk_fma_f32 v[102:103], v[48:49], v[226:227], v[102:103]
	v_pk_fma_f32 v[108:109], v[50:51], v[220:221], v[108:109]
	v_pk_fma_f32 v[106:107], v[40:41], v[238:239], v[106:107]
	v_pk_fma_f32 v[114:115], v[42:43], v[234:235], v[114:115]
	v_pk_fma_f32 v[104:105], v[68:69], v[226:227], v[104:105]
	v_pk_fma_f32 v[112:113], v[70:71], v[220:221], v[112:113]
	v_pk_fma_f32 v[110:111], v[64:65], v[238:239], v[110:111]
	v_pk_fma_f32 v[116:117], v[66:67], v[234:235], v[116:117]
	ds_read_b128 v[84:87], v166 offset:59392
	ds_read_b128 v[80:83], v166 offset:59408
	s_waitcnt lgkmcnt(1)
	v_pk_fma_f32 v[158:159], v[84:85], v[226:227], v[158:159]
	v_pk_fma_f32 v[162:163], v[86:87], v[220:221], v[162:163]
	s_waitcnt lgkmcnt(0)
	v_pk_fma_f32 v[160:161], v[80:81], v[238:239], v[160:161]
	v_pk_fma_f32 v[164:165], v[82:83], v[234:235], v[164:165]
	s_waitcnt vmcnt(7)
; #define LAS __attribute__((address_space(3)))
; #define GAS __attribute__((address_space(1)))
; #define CONV_LOAD(cc) do { _Pragma("unroll") for (int r = 0; r < 8; ++r) { const int rr = 8 * (cc) + r; if (rr < 38) { const int d = rr - 30; const bool ok = (tl + d >= 0); \
;             const h8 x = *(const GAS h8*)(GLU + (size_t)(tok0 + (ok ? d : -tl)) * 512 + 8 * lane); buf[(cc) & 1][r] = ok ? x : zero8; } } } while (0)
; __device__ __forceinline__ void conv_phase(KP P, LAS unsigned char* lds, int gw, int NGW, int tid, int lane) {
;     ...
;         for (int c = 0; c < 5; ++c) {
;             __builtin_amdgcn_sched_barrier(0);
;             if (c + 1 < 5) CONV_LOAD(c + 1);
;             __builtin_amdgcn_sched_barrier(0);
; #pragma unroll
;             for (int r = 0; r < 8; ++r) {
;                 const int rr = 8 * c + r;
;                 if (rr < 38) {
;                     const u32x4 xw = __builtin_bit_cast(u32x4, buf[c & 1][r]);
; #pragma unroll
;                     for (int i = 0; i < 8; ++i) {
;                         const int j = rr - i;
;                         if (j >= 0 && j <= 30) {
;                             const f32x4 w0 = *(const LAS f32x4*)(cw + j * 512 + 8 * lane), w1 = *(const LAS f32x4*)(cw + j * 512 + 8 * lane + 4);
; #pragma unroll
;                             for (int e = 0; e < 4; ++e) { const float wl = (e < 2) ? w0[2 * e] : w1[2 * e - 4], wh = (e < 2) ? w0[2 * e + 1] : w1[2 * e - 3];
;                                 asm("v_fma_mix_f32 %0, %1, %2, %0 op_sel_hi:[0,1,0]" : "+v"(acc[i][2 * e]) : "v"(wl), "v"(xw[e]));
;                                 asm("v_fma_mix_f32 %0, %1, %2, %0 op_sel:[0,1,0] op_sel_hi:[0,1,0]" : "+v"(acc[i][2 * e + 1]) : "v"(wh), "v"(xw[e])); }
;                         }
;                     }
;                 }
;             }
;     ...
;         const f32x4 b0 = *(const GAS f32x4*)(((const GAS float*)P->in[7]) + 8 * lane), b1 = *(const GAS f32x4*)(((const GAS float*)P->in[7]) + 8 * lane + 4);
;         const f32x4 g0 = *(const GAS f32x4*)(((const GAS float*)P->in[8]) + 8 * lane), g1 = *(const GAS f32x4*)(((const GAS float*)P->in[8]) + 8 * lane + 4);
;         const f32x4 l0 = *(const GAS f32x4*)(((const GAS float*)P->in[9]) + 8 * lane), l1 = *(const GAS f32x4*)(((const GAS float*)P->in[9]) + 8 * lane + 4);
	v_cvt_f32_f16_sdwa v225, v4 dst_sel:DWORD dst_unused:UNUSED_PAD src0_sel:WORD_1
	v_cvt_f32_f16_e32 v224, v4
	v_pk_fma_f32 v[150:151], v[84:85], v[224:225], v[150:151]
	v_cvt_f32_f16_sdwa v247, v5 dst_sel:DWORD dst_unused:UNUSED_PAD src0_sel:WORD_1
	v_cvt_f32_f16_e32 v246, v5
	v_pk_fma_f32 v[154:155], v[86:87], v[246:247], v[154:155]
	v_cvt_f32_f16_sdwa v217, v6 dst_sel:DWORD dst_unused:UNUSED_PAD src0_sel:WORD_1
	v_cvt_f32_f16_e32 v216, v6
	v_pk_fma_f32 v[152:153], v[80:81], v[216:217], v[152:153]
	v_cvt_f32_f16_sdwa v243, v7 dst_sel:DWORD dst_unused:UNUSED_PAD src0_sel:WORD_1
	v_cvt_f32_f16_e32 v242, v7
	v_pk_fma_f32 v[156:157], v[82:83], v[242:243], v[156:157]
	v_pk_fma_f32 v[142:143], v[92:93], v[224:225], v[142:143]
	v_pk_fma_f32 v[146:147], v[94:95], v[246:247], v[146:147]
	v_pk_fma_f32 v[144:145], v[88:89], v[216:217], v[144:145]
	v_pk_fma_f32 v[148:149], v[90:91], v[242:243], v[148:149]
	v_pk_fma_f32 v[134:135], v[76:77], v[224:225], v[134:135]
	v_pk_fma_f32 v[138:139], v[78:79], v[246:247], v[138:139]
	v_pk_fma_f32 v[136:137], v[72:73], v[216:217], v[136:137]
	v_pk_fma_f32 v[140:141], v[74:75], v[242:243], v[140:141]
	v_pk_fma_f32 v[126:127], v[60:61], v[224:225], v[126:127]
	v_pk_fma_f32 v[130:131], v[62:63], v[246:247], v[130:131]
	v_pk_fma_f32 v[128:129], v[56:57], v[216:217], v[128:129]
	v_pk_fma_f32 v[132:133], v[58:59], v[242:243], v[132:133]
	v_pk_fma_f32 v[118:119], v[52:53], v[224:225], v[118:119]
	v_pk_fma_f32 v[122:123], v[54:55], v[246:247], v[122:123]
	v_pk_fma_f32 v[120:121], v[44:45], v[216:217], v[120:121]
	v_pk_fma_f32 v[124:125], v[46:47], v[242:243], v[124:125]
	v_pk_fma_f32 v[102:103], v[36:37], v[224:225], v[102:103]
	v_pk_fma_f32 v[108:109], v[38:39], v[246:247], v[108:109]
	v_pk_fma_f32 v[106:107], v[32:33], v[216:217], v[106:107]
	v_pk_fma_f32 v[114:115], v[34:35], v[242:243], v[114:115]
	v_pk_fma_f32 v[104:105], v[48:49], v[224:225], v[104:105]
	v_pk_fma_f32 v[112:113], v[50:51], v[246:247], v[112:113]
	v_pk_fma_f32 v[110:111], v[40:41], v[216:217], v[110:111]
	v_pk_fma_f32 v[116:117], v[42:43], v[242:243], v[116:117]
	ds_read_b128 v[68:71], v166 offset:61440
	ds_read_b128 v[64:67], v166 offset:61456
	s_waitcnt lgkmcnt(1)
	v_pk_fma_f32 v[158:159], v[68:69], v[224:225], v[158:159]
	v_pk_fma_f32 v[162:163], v[70:71], v[246:247], v[162:163]
	s_waitcnt lgkmcnt(0)
	v_pk_fma_f32 v[160:161], v[64:65], v[216:217], v[160:161]
	v_pk_fma_f32 v[164:165], v[66:67], v[242:243], v[164:165]
	s_waitcnt vmcnt(6)
	v_cvt_f32_f16_sdwa v223, v0 dst_sel:DWORD dst_unused:UNUSED_PAD src0_sel:WORD_1
	v_cvt_f32_f16_e32 v222, v0
	v_pk_fma_f32 v[150:151], v[68:69], v[222:223], v[150:151]
	v_cvt_f32_f16_sdwa v245, v1 dst_sel:DWORD dst_unused:UNUSED_PAD src0_sel:WORD_1
	v_cvt_f32_f16_e32 v244, v1
	v_pk_fma_f32 v[154:155], v[70:71], v[244:245], v[154:155]
	v_cvt_f32_f16_sdwa v233, v2 dst_sel:DWORD dst_unused:UNUSED_PAD src0_sel:WORD_1
	v_cvt_f32_f16_e32 v232, v2
	v_pk_fma_f32 v[152:153], v[64:65], v[232:233], v[152:153]
	v_cvt_f32_f16_sdwa v229, v3 dst_sel:DWORD dst_unused:UNUSED_PAD src0_sel:WORD_1
	v_cvt_f32_f16_e32 v228, v3
	v_pk_fma_f32 v[156:157], v[66:67], v[228:229], v[156:157]
	v_pk_fma_f32 v[142:143], v[84:85], v[222:223], v[142:143]
	v_pk_fma_f32 v[146:147], v[86:87], v[244:245], v[146:147]
	v_pk_fma_f32 v[144:145], v[80:81], v[232:233], v[144:145]
	v_pk_fma_f32 v[148:149], v[82:83], v[228:229], v[148:149]
	v_pk_fma_f32 v[134:135], v[92:93], v[222:223], v[134:135]
	v_pk_fma_f32 v[138:139], v[94:95], v[244:245], v[138:139]
	v_pk_fma_f32 v[136:137], v[88:89], v[232:233], v[136:137]
	v_pk_fma_f32 v[140:141], v[90:91], v[228:229], v[140:141]
	v_pk_fma_f32 v[126:127], v[76:77], v[222:223], v[126:127]
	v_pk_fma_f32 v[130:131], v[78:79], v[244:245], v[130:131]
	v_pk_fma_f32 v[128:129], v[72:73], v[232:233], v[128:129]
	v_pk_fma_f32 v[132:133], v[74:75], v[228:229], v[132:133]
	v_pk_fma_f32 v[118:119], v[60:61], v[222:223], v[118:119]
	v_pk_fma_f32 v[122:123], v[62:63], v[244:245], v[122:123]
	v_pk_fma_f32 v[120:121], v[56:57], v[232:233], v[120:121]
	v_pk_fma_f32 v[124:125], v[58:59], v[228:229], v[124:125]
	v_pk_fma_f32 v[102:103], v[52:53], v[222:223], v[102:103]
	v_pk_fma_f32 v[108:109], v[54:55], v[244:245], v[108:109]
	v_pk_fma_f32 v[106:107], v[44:45], v[232:233], v[106:107]
	v_pk_fma_f32 v[114:115], v[46:47], v[228:229], v[114:115]
	v_pk_fma_f32 v[104:105], v[36:37], v[222:223], v[104:105]
	v_pk_fma_f32 v[112:113], v[38:39], v[244:245], v[112:113]
	v_pk_fma_f32 v[110:111], v[32:33], v[232:233], v[110:111]
	v_pk_fma_f32 v[116:117], v[34:35], v[228:229], v[116:117]
	ds_read_b128 v[40:43], v166 offset:61440
	ds_read_b128 v[36:39], v166 offset:61456
	s_load_dwordx4 s[8:11], s[22:23], 0x38
	s_load_dwordx2 s[40:41], s[22:23], 0x48
	ds_read_b128 v[0:3], v166 offset:51200
	ds_read_b128 v[4:7], v166 offset:51216
	s_waitcnt vmcnt(5) lgkmcnt(0)
	v_cvt_f32_f16_sdwa v223, v30 dst_sel:DWORD dst_unused:UNUSED_PAD src0_sel:WORD_1
	v_cvt_f32_f16_e32 v222, v30
	v_pk_fma_f32 v[110:111], v[4:5], v[222:223], v[110:111]
	v_lshl_add_u64 v[4:5], s[8:9], 0, v[100:101]
	ds_read_b128 v[48:51], v166 offset:59392
	ds_read_b128 v[44:47], v166 offset:59408
	ds_read_b128 v[32:35], v166 offset:57344
	ds_read_b128 v[52:55], v166 offset:57360
	ds_read_b128 v[56:59], v166 offset:55296
	ds_read_b128 v[60:63], v166 offset:55312
	ds_read_b128 v[64:67], v166 offset:53248
	ds_read_b128 v[68:71], v166 offset:53264
	v_cvt_f32_f16_sdwa v245, v28 dst_sel:DWORD dst_unused:UNUSED_PAD src0_sel:WORD_1
	v_cvt_f32_f16_e32 v244, v28
	v_pk_fma_f32 v[104:105], v[0:1], v[244:245], v[104:105]
	v_cvt_f32_f16_sdwa v233, v29 dst_sel:DWORD dst_unused:UNUSED_PAD src0_sel:WORD_1
	v_cvt_f32_f16_e32 v232, v29
	v_pk_fma_f32 v[112:113], v[2:3], v[232:233], v[112:113]
	v_cvt_f32_f16_sdwa v229, v31 dst_sel:DWORD dst_unused:UNUSED_PAD src0_sel:WORD_1
	v_cvt_f32_f16_e32 v228, v31
	v_pk_fma_f32 v[116:117], v[6:7], v[228:229], v[116:117]
	global_load_dwordx4 v[0:3], v[4:5], off offset:16
	s_nop 0
	global_load_dwordx4 v[4:7], v[4:5], off
	s_waitcnt lgkmcnt(5)
; #define LAS __attribute__((address_space(3)))
; __device__ __forceinline__ void conv_phase(KP P, LAS unsigned char* lds, int gw, int NGW, int tid, int lane) {
;     ...
;             for (int r = 0; r < 8; ++r) {
;                 const int rr = 8 * c + r;
;                 if (rr < 38) {
;                     const u32x4 xw = __builtin_bit_cast(u32x4, buf[c & 1][r]);
; #pragma unroll
;                     for (int i = 0; i < 8; ++i) {
;                         const int j = rr - i;
;                         if (j >= 0 && j <= 30) {
;                             const f32x4 w0 = *(const LAS f32x4*)(cw + j * 512 + 8 * lane), w1 = *(const LAS f32x4*)(cw + j * 512 + 8 * lane + 4);
; #pragma unroll
;                             for (int e = 0; e < 4; ++e) { const float wl = (e < 2) ? w0[2 * e] : w1[2 * e - 4], wh = (e < 2) ? w0[2 * e + 1] : w1[2 * e - 3];
;                                 asm("v_fma_mix_f32 %0, %1, %2, %0 op_sel_hi:[0,1,0]" : "+v"(acc[i][2 * e]) : "v"(wl), "v"(xw[e]));
;                                 asm("v_fma_mix_f32 %0, %1, %2, %0 op_sel:[0,1,0] op_sel_hi:[0,1,0]" : "+v"(acc[i][2 * e + 1]) : "v"(wh), "v"(xw[e])); }
;                         }
;                     }
;                 }
;             }
;     ...
; #pragma unroll
;         for (int i = 0; i < 8; ++i) {
;             f32x4 y0 = {acc[i][0], acc[i][1], acc[i][2], acc[i][3]}, y1 = {acc[i][4], acc[i][5], acc[i][6], acc[i][7]};
;             y0 += b0; y1 += b1;
;             const float mu = wave_sum((y0[0] + y0[1]) + (y0[2] + y0[3]) + (y1[0] + y1[1]) + (y1[2] + y1[3])) * (1.f / 512.f);
	v_pk_fma_f32 v[126:127], v[32:33], v[244:245], v[126:127]
	v_pk_fma_f32 v[130:131], v[34:35], v[232:233], v[130:131]
	s_waitcnt lgkmcnt(4)
	v_pk_fma_f32 v[128:129], v[52:53], v[222:223], v[128:129]
	v_pk_fma_f32 v[132:133], v[54:55], v[228:229], v[132:133]
	s_waitcnt lgkmcnt(3)
	v_pk_fma_f32 v[118:119], v[56:57], v[244:245], v[118:119]
	v_pk_fma_f32 v[122:123], v[58:59], v[232:233], v[122:123]
	s_waitcnt lgkmcnt(2)
	v_pk_fma_f32 v[120:121], v[60:61], v[222:223], v[120:121]
	v_pk_fma_f32 v[124:125], v[62:63], v[228:229], v[124:125]
	s_waitcnt lgkmcnt(1)
	v_pk_fma_f32 v[102:103], v[64:65], v[244:245], v[102:103]
	v_pk_fma_f32 v[108:109], v[66:67], v[232:233], v[108:109]
	s_waitcnt lgkmcnt(0)
	v_pk_fma_f32 v[106:107], v[68:69], v[222:223], v[106:107]
	v_pk_fma_f32 v[114:115], v[70:71], v[228:229], v[114:115]
	s_waitcnt vmcnt(6)
	v_cvt_f32_f16_sdwa v225, v24 dst_sel:DWORD dst_unused:UNUSED_PAD src0_sel:WORD_1
	v_cvt_f32_f16_e32 v224, v24
	v_pk_fma_f32 v[104:105], v[64:65], v[224:225], v[104:105]
	v_cvt_f32_f16_sdwa v247, v25 dst_sel:DWORD dst_unused:UNUSED_PAD src0_sel:WORD_1
	v_cvt_f32_f16_e32 v246, v25
	v_pk_fma_f32 v[112:113], v[66:67], v[246:247], v[112:113]
	v_pk_fma_f32 v[126:127], v[48:49], v[224:225], v[126:127]
	v_pk_fma_f32 v[130:131], v[50:51], v[246:247], v[130:131]
	v_cvt_f32_f16_sdwa v217, v26 dst_sel:DWORD dst_unused:UNUSED_PAD src0_sel:WORD_1
	v_cvt_f32_f16_e32 v216, v26
	v_pk_fma_f32 v[128:129], v[44:45], v[216:217], v[128:129]
	v_cvt_f32_f16_sdwa v243, v27 dst_sel:DWORD dst_unused:UNUSED_PAD src0_sel:WORD_1
	v_cvt_f32_f16_e32 v242, v27
	v_pk_fma_f32 v[132:133], v[46:47], v[242:243], v[132:133]
	v_pk_fma_f32 v[118:119], v[32:33], v[224:225], v[118:119]
	v_pk_fma_f32 v[122:123], v[34:35], v[246:247], v[122:123]
	v_pk_fma_f32 v[120:121], v[52:53], v[216:217], v[120:121]
	v_pk_fma_f32 v[124:125], v[54:55], v[242:243], v[124:125]
	v_pk_fma_f32 v[102:103], v[56:57], v[224:225], v[102:103]
	v_pk_fma_f32 v[108:109], v[58:59], v[246:247], v[108:109]
	v_pk_fma_f32 v[106:107], v[60:61], v[216:217], v[106:107]
	v_pk_fma_f32 v[114:115], v[62:63], v[242:243], v[114:115]
	v_pk_fma_f32 v[110:111], v[68:69], v[216:217], v[110:111]
	v_pk_fma_f32 v[116:117], v[70:71], v[242:243], v[116:117]
	s_waitcnt vmcnt(5)
	v_cvt_f32_f16_sdwa v237, v20 dst_sel:DWORD dst_unused:UNUSED_PAD src0_sel:WORD_1
	v_cvt_f32_f16_e32 v236, v20
	v_pk_fma_f32 v[104:105], v[56:57], v[236:237], v[104:105]
	v_cvt_f32_f16_sdwa v215, v21 dst_sel:DWORD dst_unused:UNUSED_PAD src0_sel:WORD_1
	v_cvt_f32_f16_e32 v214, v21
	v_pk_fma_f32 v[112:113], v[58:59], v[214:215], v[112:113]
	v_pk_fma_f32 v[134:135], v[48:49], v[244:245], v[134:135]
	v_pk_fma_f32 v[138:139], v[50:51], v[232:233], v[138:139]
	v_pk_fma_f32 v[126:127], v[40:41], v[236:237], v[126:127]
	v_pk_fma_f32 v[130:131], v[42:43], v[214:215], v[130:131]
	v_cvt_f32_f16_sdwa v231, v22 dst_sel:DWORD dst_unused:UNUSED_PAD src0_sel:WORD_1
	v_cvt_f32_f16_e32 v230, v22
	v_pk_fma_f32 v[128:129], v[36:37], v[230:231], v[128:129]
	v_cvt_f32_f16_sdwa v241, v23 dst_sel:DWORD dst_unused:UNUSED_PAD src0_sel:WORD_1
	v_cvt_f32_f16_e32 v240, v23
	v_pk_fma_f32 v[132:133], v[38:39], v[240:241], v[132:133]
	v_pk_fma_f32 v[118:119], v[48:49], v[236:237], v[118:119]
	v_pk_fma_f32 v[122:123], v[50:51], v[214:215], v[122:123]
	v_pk_fma_f32 v[120:121], v[44:45], v[230:231], v[120:121]
	v_fma_mix_f32 v124, v46, v23, v124 op_sel_hi:[0,1,0]
	s_waitcnt vmcnt(0)
	v_pk_add_f32 v[56:57], v[162:163], v[6:7]
	v_pk_add_f32 v[58:59], v[158:159], v[4:5]
	v_fma_mix_f32 v125, v47, v23, v125 op_sel:[0,1,0] op_sel_hi:[0,1,0]
	v_pk_fma_f32 v[102:103], v[32:33], v[236:237], v[102:103]
	v_pk_fma_f32 v[108:109], v[34:35], v[214:215], v[108:109]
	v_pk_fma_f32 v[106:107], v[52:53], v[230:231], v[106:107]
	v_pk_fma_f32 v[114:115], v[54:55], v[240:241], v[114:115]
	v_pk_fma_f32 v[110:111], v[60:61], v[230:231], v[110:111]
	v_pk_fma_f32 v[116:117], v[62:63], v[240:241], v[116:117]
	v_pk_add_f32 v[60:61], v[164:165], v[2:3]
	v_pk_add_f32 v[62:63], v[160:161], v[0:1]
	v_pk_mov_b32 v[20:21], v[58:59], v[56:57] op_sel:[1,0]
	v_mov_b32_e32 v22, v58
	v_mov_b32_e32 v23, v57
	v_pk_fma_f32 v[134:135], v[40:41], v[224:225], v[134:135]
	v_pk_fma_f32 v[138:139], v[42:43], v[246:247], v[138:139]
	v_pk_add_f32 v[20:21], v[20:21], v[22:23]
	v_mov_b32_e32 v22, v60
	v_mov_b32_e32 v23, v62
	v_mov_b32_e32 v24, v61
	v_mov_b32_e32 v25, v63
	v_cmp_lt_i32_e32 vcc, v169, v168
	v_pk_add_f32 v[22:23], v[22:23], v[24:25]
	v_add_f32_e32 v20, v20, v21
	v_cvt_f32_f16_sdwa v237, v16 dst_sel:DWORD dst_unused:UNUSED_PAD src0_sel:WORD_1
	v_cvt_f32_f16_e32 v236, v16
	v_pk_fma_f32 v[118:119], v[40:41], v[236:237], v[118:119]
	v_pk_fma_f32 v[102:103], v[48:49], v[236:237], v[102:103]
	v_pk_fma_f32 v[104:105], v[32:33], v[236:237], v[104:105]
	v_cndmask_b32_e32 v16, v167, v169, vcc
	v_add_f32_e32 v20, v23, v20
	v_lshlrev_b32_e32 v16, 2, v16
	v_add_f32_e32 v20, v22, v20
	ds_bpermute_b32 v21, v16, v20
	v_cmp_lt_i32_e32 vcc, v170, v168
	v_cvt_f32_f16_sdwa v215, v17 dst_sel:DWORD dst_unused:UNUSED_PAD src0_sel:WORD_1
	v_cvt_f32_f16_e32 v214, v17
	v_pk_fma_f32 v[122:123], v[42:43], v[214:215], v[122:123]
	v_pk_fma_f32 v[108:109], v[50:51], v[214:215], v[108:109]
	v_pk_fma_f32 v[112:113], v[34:35], v[214:215], v[112:113]
	s_nop 1
	v_cndmask_b32_e32 v17, v167, v170, vcc
	v_lshlrev_b32_e32 v17, 2, v17
	s_waitcnt lgkmcnt(0)
	v_add_f32_e32 v20, v20, v21
	ds_bpermute_b32 v21, v17, v20
	v_cmp_lt_i32_e32 vcc, v171, v168
	v_fma_mix_f32 v110, v52, v18, v110 op_sel_hi:[0,1,0]
	v_cvt_f32_f16_sdwa v231, v18 dst_sel:DWORD dst_unused:UNUSED_PAD src0_sel:WORD_1
	v_cvt_f32_f16_e32 v230, v18
	v_pk_fma_f32 v[120:121], v[36:37], v[230:231], v[120:121]
	s_waitcnt lgkmcnt(0)
; #define LAS __attribute__((address_space(3)))
; #define GAS __attribute__((address_space(1)))
; __device__ __forceinline__ float sq4(f32x4 x) { return (x[0] * x[0] + x[1] * x[1]) + (x[2] * x[2] + x[3] * x[3]); }
; __device__ __forceinline__ void conv_phase(KP P, LAS unsigned char* lds, int gw, int NGW, int tid, int lane) {
;     ...
;             for (int r = 0; r < 8; ++r) {
;                 const int rr = 8 * c + r;
;                 if (rr < 38) {
;                     const u32x4 xw = __builtin_bit_cast(u32x4, buf[c & 1][r]);
; #pragma unroll
;                     for (int i = 0; i < 8; ++i) {
;                         const int j = rr - i;
;                         if (j >= 0 && j <= 30) {
;                             const f32x4 w0 = *(const LAS f32x4*)(cw + j * 512 + 8 * lane), w1 = *(const LAS f32x4*)(cw + j * 512 + 8 * lane + 4);
; #pragma unroll
;                             for (int e = 0; e < 4; ++e) { const float wl = (e < 2) ? w0[2 * e] : w1[2 * e - 4], wh = (e < 2) ? w0[2 * e + 1] : w1[2 * e - 3];
;                                 asm("v_fma_mix_f32 %0, %1, %2, %0 op_sel_hi:[0,1,0]" : "+v"(acc[i][2 * e]) : "v"(wl), "v"(xw[e]));
;                                 asm("v_fma_mix_f32 %0, %1, %2, %0 op_sel:[0,1,0] op_sel_hi:[0,1,0]" : "+v"(acc[i][2 * e + 1]) : "v"(wh), "v"(xw[e])); }
;                         }
;                     }
;                 }
;             }
;     ...
;         const f32x4 b0 = *(const GAS f32x4*)(((const GAS float*)P->in[7]) + 8 * lane), b1 = *(const GAS f32x4*)(((const GAS float*)P->in[7]) + 8 * lane + 4);
;         const f32x4 g0 = *(const GAS f32x4*)(((const GAS float*)P->in[8]) + 8 * lane), g1 = *(const GAS f32x4*)(((const GAS float*)P->in[8]) + 8 * lane + 4);
;         const f32x4 l0 = *(const GAS f32x4*)(((const GAS float*)P->in[9]) + 8 * lane), l1 = *(const GAS f32x4*)(((const GAS float*)P->in[9]) + 8 * lane + 4);
; #pragma unroll
;         for (int i = 0; i < 8; ++i) {
;             f32x4 y0 = {acc[i][0], acc[i][1], acc[i][2], acc[i][3]}, y1 = {acc[i][4], acc[i][5], acc[i][6], acc[i][7]};
;             y0 += b0; y1 += b1;
;             const float mu = wave_sum((y0[0] + y0[1]) + (y0[2] + y0[3]) + (y1[0] + y1[1]) + (y1[2] + y1[3])) * (1.f / 512.f);
;             y0 -= mu; y1 -= mu;
;             const float rstd = __builtin_amdgcn_rsqf(wave_sum(sq4(y0) + sq4(y1)) * (1.f / 512.f) + EPS);
	v_add_f32_e32 v20, v20, v21
	v_fma_mix_f32 v106, v44, v18, v106 op_sel_hi:[0,1,0]
	v_cndmask_b32_e32 v22, v167, v171, vcc
	v_lshlrev_b32_e32 v52, 2, v22
	ds_bpermute_b32 v21, v52, v20
	v_cmp_lt_i32_e32 vcc, v172, v168
	v_fma_mix_f32 v107, v45, v18, v107 op_sel:[0,1,0] op_sel_hi:[0,1,0]
	v_fma_mix_f32 v111, v53, v18, v111 op_sel:[0,1,0] op_sel_hi:[0,1,0]
	v_fma_mix_f32 v136, v44, v30, v136 op_sel_hi:[0,1,0]
	s_waitcnt lgkmcnt(0)
	v_add_f32_e32 v20, v20, v21
	v_fma_mix_f32 v137, v45, v30, v137 op_sel:[0,1,0] op_sel_hi:[0,1,0]
	v_cndmask_b32_e32 v18, v167, v172, vcc
	v_lshlrev_b32_e32 v18, 2, v18
	ds_bpermute_b32 v21, v18, v20
	v_cmp_lt_i32_e32 vcc, v173, v168
	v_pk_fma_f32 v[140:141], v[46:47], v[228:229], v[140:141]
	v_lshl_add_u64 v[24:25], s[10:11], 0, v[100:101]
	s_waitcnt lgkmcnt(0)
	v_add_f32_e32 v20, v20, v21
	v_cndmask_b32_e32 v22, v167, v173, vcc
	v_lshlrev_b32_e32 v53, 2, v22
	ds_bpermute_b32 v21, v53, v20
	v_cmp_lt_i32_e32 vcc, v174, v168
	v_lshl_add_u64 v[32:33], s[40:41], 0, v[100:101]
	v_pk_fma_f32 v[142:143], v[40:41], v[244:245], v[142:143]
	v_pk_fma_f32 v[146:147], v[42:43], v[232:233], v[146:147]
	s_nop 0
	v_cndmask_b32_e32 v22, v167, v174, vcc
	v_pk_fma_f32 v[144:145], v[36:37], v[222:223], v[144:145]
	v_pk_fma_f32 v[148:149], v[38:39], v[228:229], v[148:149]
	v_pk_fma_f32 v[136:137], v[36:37], v[216:217], v[136:137]
	v_pk_fma_f32 v[140:141], v[38:39], v[242:243], v[140:141]
	v_fma_mix_f32 v116, v54, v19, v116 op_sel_hi:[0,1,0]
	v_lshlrev_b32_e32 v54, 2, v22
	s_waitcnt lgkmcnt(0)
	v_add_f32_e32 v64, v20, v21
	global_load_dwordx4 v[20:23], v[24:25], off offset:16
	global_load_dwordx4 v[28:31], v[24:25], off
	s_nop 0
	global_load_dwordx4 v[24:27], v[32:33], off offset:16
	s_nop 0
	global_load_dwordx4 v[32:35], v[32:33], off
	ds_bpermute_b32 v65, v54, v64
	v_cvt_f32_f16_sdwa v241, v19 dst_sel:DWORD dst_unused:UNUSED_PAD src0_sel:WORD_1
	v_cvt_f32_f16_e32 v240, v19
	v_pk_fma_f32 v[124:125], v[38:39], v[240:241], v[124:125]
	v_pk_fma_f32 v[114:115], v[46:47], v[240:241], v[114:115]
	s_waitcnt lgkmcnt(0)
	v_add_f32_e32 v64, v64, v65
	v_fmamk_f32 v59, v64, 0xbb000000, v59
	v_fmamk_f32 v63, v64, 0xbb000000, v63
	v_fmamk_f32 v57, v64, 0xbb000000, v57
	v_fmac_f32_e32 v58, 0xbb000000, v64
	v_fmamk_f32 v61, v64, 0xbb000000, v61
	v_fmac_f32_e32 v62, 0xbb000000, v64
	v_mov_b32_e32 v66, v59
	v_mov_b32_e32 v67, v63
	v_fmac_f32_e32 v56, 0xbb000000, v64
	v_fmac_f32_e32 v60, 0xbb000000, v64
	v_mov_b32_e32 v64, v58
	v_mov_b32_e32 v65, v62
	v_pk_mul_f32 v[66:67], v[66:67], v[66:67]
	v_mov_b32_e32 v68, v57
	v_mov_b32_e32 v69, v61
	v_pk_fma_f32 v[64:65], v[64:65], v[64:65], v[66:67]
	v_mov_b32_e32 v66, v56
	v_mov_b32_e32 v67, v60
	v_pk_mul_f32 v[68:69], v[68:69], v[68:69]
	v_fma_mix_f32 v117, v55, v19, v117 op_sel:[0,1,0] op_sel_hi:[0,1,0]
	v_cvt_f32_f16_sdwa v225, v12 dst_sel:DWORD dst_unused:UNUSED_PAD src0_sel:WORD_1
	v_cvt_f32_f16_e32 v224, v12
	v_pk_fma_f32 v[102:103], v[40:41], v[224:225], v[102:103]
	v_pk_fma_f32 v[104:105], v[48:49], v[224:225], v[104:105]
	s_nop 0
	v_pk_fma_f32 v[66:67], v[66:67], v[66:67], v[68:69]
	v_cvt_f32_f16_sdwa v247, v13 dst_sel:DWORD dst_unused:UNUSED_PAD src0_sel:WORD_1
	v_cvt_f32_f16_e32 v246, v13
	v_pk_fma_f32 v[108:109], v[42:43], v[246:247], v[108:109]
	v_pk_fma_f32 v[112:113], v[50:51], v[246:247], v[112:113]
	v_fma_mix_f32 v104, v40, v8, v104 op_sel_hi:[0,1,0]
	s_nop 0
	v_pk_add_f32 v[64:65], v[64:65], v[66:67]
	v_fma_mix_f32 v105, v41, v8, v105 op_sel:[0,1,0] op_sel_hi:[0,1,0]
	v_cvt_f32_f16_sdwa v237, v14 dst_sel:DWORD dst_unused:UNUSED_PAD src0_sel:WORD_1
	v_cvt_f32_f16_e32 v236, v14
	v_pk_fma_f32 v[106:107], v[36:37], v[236:237], v[106:107]
	v_cvt_f32_f16_sdwa v215, v15 dst_sel:DWORD dst_unused:UNUSED_PAD src0_sel:WORD_1
	v_cvt_f32_f16_e32 v214, v15
	v_pk_fma_f32 v[114:115], v[38:39], v[214:215], v[114:115]
	s_nop 0
	v_add_f32_e32 v64, v64, v65
	ds_bpermute_b32 v65, v16, v64
	v_pk_fma_f32 v[110:111], v[44:45], v[236:237], v[110:111]
	v_pk_fma_f32 v[116:117], v[46:47], v[214:215], v[116:117]
	s_waitcnt lgkmcnt(0)
	v_add_f32_e32 v19, v64, v65
	ds_bpermute_b32 v55, v17, v19
	v_pk_add_f32 v[14:15], v[150:151], v[4:5]
	v_cvt_f32_f16_sdwa v231, v9 dst_sel:DWORD dst_unused:UNUSED_PAD src0_sel:WORD_1
	v_cvt_f32_f16_e32 v230, v9
	v_pk_fma_f32 v[112:113], v[42:43], v[230:231], v[112:113]
	v_fma_mix_f32 v110, v36, v10, v110 op_sel_hi:[0,1,0]
	s_waitcnt lgkmcnt(0)
	v_add_f32_e32 v19, v19, v55
	ds_bpermute_b32 v55, v52, v19
	v_fma_mix_f32 v111, v37, v10, v111 op_sel:[0,1,0] op_sel_hi:[0,1,0]
	v_pk_add_f32 v[36:37], v[156:157], v[2:3]
	v_pk_add_f32 v[40:41], v[152:153], v[0:1]
	v_mov_b32_e32 v44, v14
	s_waitcnt lgkmcnt(0)
	v_add_f32_e32 v12, v19, v55
	ds_bpermute_b32 v19, v18, v12
	v_mov_b32_e32 v46, v37
	v_mov_b32_e32 v47, v41
	v_cvt_f32_f16_sdwa v245, v11 dst_sel:DWORD dst_unused:UNUSED_PAD src0_sel:WORD_1
	v_cvt_f32_f16_e32 v244, v11
	v_pk_fma_f32 v[116:117], v[38:39], v[244:245], v[116:117]
	s_waitcnt lgkmcnt(0)
	v_add_f32_e32 v12, v12, v19
	ds_bpermute_b32 v13, v53, v12
	s_add_i32 s3, s3, s62
	s_add_i32 s24, s24, s42
	s_cmpk_lt_i32 s3, 0x800
	s_waitcnt lgkmcnt(0)
	v_add_f32_e32 v8, v12, v13
	ds_bpermute_b32 v12, v54, v8
	s_waitcnt lgkmcnt(0)
	v_add_f32_e32 v8, v8, v12
	v_pk_add_f32 v[12:13], v[154:155], v[6:7]
	v_fmamk_f32 v8, v8, 0x3b000000, v175
	v_pk_mov_b32 v[42:43], v[14:15], v[12:13] op_sel:[1,0]
	v_mov_b32_e32 v45, v13
	v_pk_add_f32 v[42:43], v[42:43], v[44:45]
	v_mov_b32_e32 v44, v36
	v_mov_b32_e32 v45, v40
	v_pk_add_f32 v[44:45], v[44:45], v[46:47]
	v_add_f32_e32 v9, v42, v43
	v_add_f32_e32 v9, v45, v9
	v_add_f32_e32 v9, v44, v9
	ds_bpermute_b32 v19, v16, v9
	v_rsq_f32_e32 v8, v8
	s_waitcnt lgkmcnt(0)
; #define GAS __attribute__((address_space(1)))
; __device__ __forceinline__ f32x4 sigm4(f32x4 x) { f32x4 r; r[0] = sigm(x[0]); r[1] = sigm(x[1]); r[2] = sigm(x[2]); r[3] = sigm(x[3]); return r; }
; __device__ __forceinline__ float sq4(f32x4 x) { return (x[0] * x[0] + x[1] * x[1]) + (x[2] * x[2] + x[3] * x[3]); }
; __device__ __forceinline__ void conv_phase(KP P, LAS unsigned char* lds, int gw, int NGW, int tid, int lane) {
;     ...
; #pragma unroll
;         for (int i = 0; i < 8; ++i) {
;             f32x4 y0 = {acc[i][0], acc[i][1], acc[i][2], acc[i][3]}, y1 = {acc[i][4], acc[i][5], acc[i][6], acc[i][7]};
;             y0 += b0; y1 += b1;
;             const float mu = wave_sum((y0[0] + y0[1]) + (y0[2] + y0[3]) + (y1[0] + y1[1]) + (y1[2] + y1[3])) * (1.f / 512.f);
;             y0 -= mu; y1 -= mu;
;             const float rstd = __builtin_amdgcn_rsqf(wave_sum(sq4(y0) + sq4(y1)) * (1.f / 512.f) + EPS);
;             y0 = y0 * rstd * g0 + l0; y1 = y1 * rstd * g1 + l1;
;             *(GAS h8*)(CONV + (size_t)(tok0 + i) * 512 + 8 * lane) = pack8(y0 * sigm4(y0), y1 * sigm4(y1));
;         }
	v_add_f32_e32 v19, v9, v19
	ds_bpermute_b32 v44, v17, v19
	v_pk_mul_f32 v[10:11], v[58:59], v[8:9] op_sel_hi:[1,0]
	v_pk_mul_f32 v[38:39], v[56:57], v[8:9] op_sel_hi:[1,0]
	s_waitcnt vmcnt(0)
	v_pk_fma_f32 v[10:11], v[28:29], v[10:11], v[32:33]
	v_pk_fma_f32 v[38:39], v[30:31], v[38:39], v[34:35]
	s_waitcnt lgkmcnt(0)
	v_add_f32_e32 v19, v19, v44
	ds_bpermute_b32 v44, v52, v19
	v_mul_f32_e32 v45, 0xbfb8aa3b, v10
	v_mul_f32_e32 v46, 0xbfb8aa3b, v11
	v_exp_f32_e32 v45, v45
	v_exp_f32_e32 v46, v46
	s_waitcnt lgkmcnt(0)
	v_add_f32_e32 v19, v19, v44
	ds_bpermute_b32 v47, v18, v19
	v_add_f32_e32 v44, 1.0, v45
	v_add_f32_e32 v45, 1.0, v46
	v_mul_f32_e32 v48, 0xbfb8aa3b, v39
	v_exp_f32_e32 v48, v48
	s_waitcnt lgkmcnt(0)
	v_add_f32_e32 v19, v19, v47
	ds_bpermute_b32 v46, v53, v19
	v_mul_f32_e32 v47, 0xbfb8aa3b, v38
	v_exp_f32_e32 v47, v47
	v_pk_mul_f32 v[42:43], v[62:63], v[8:9] op_sel_hi:[1,0]
	v_pk_mul_f32 v[8:9], v[60:61], v[8:9] op_sel_hi:[1,0]
	s_waitcnt lgkmcnt(0)
	v_add_f32_e32 v19, v19, v46
	ds_bpermute_b32 v49, v54, v19
	v_add_f32_e32 v46, 1.0, v47
	v_add_f32_e32 v47, 1.0, v48
	v_pk_fma_f32 v[42:43], v[20:21], v[42:43], v[24:25]
	v_pk_fma_f32 v[8:9], v[22:23], v[8:9], v[26:27]
	s_waitcnt lgkmcnt(0)
	v_add_f32_e32 v19, v19, v49
	v_fmamk_f32 v15, v19, 0xbb000000, v15
	v_fmamk_f32 v41, v19, 0xbb000000, v41
	v_fmamk_f32 v13, v19, 0xbb000000, v13
	v_fmac_f32_e32 v14, 0xbb000000, v19
	v_fmamk_f32 v37, v19, 0xbb000000, v37
	v_fmac_f32_e32 v40, 0xbb000000, v19
	v_mov_b32_e32 v50, v15
	v_mov_b32_e32 v51, v41
	v_fmac_f32_e32 v12, 0xbb000000, v19
	v_fmac_f32_e32 v36, 0xbb000000, v19
	v_mov_b32_e32 v48, v14
	v_mov_b32_e32 v49, v40
	v_pk_mul_f32 v[50:51], v[50:51], v[50:51]
	v_mov_b32_e32 v56, v13
	v_mov_b32_e32 v57, v37
	v_pk_fma_f32 v[48:49], v[48:49], v[48:49], v[50:51]
	v_mov_b32_e32 v50, v12
	v_mov_b32_e32 v51, v36
	v_pk_mul_f32 v[56:57], v[56:57], v[56:57]
	v_mul_f32_e32 v55, 0xbfb8aa3b, v9
	v_pk_fma_f32 v[50:51], v[50:51], v[50:51], v[56:57]
	v_exp_f32_e32 v55, v55
	v_pk_add_f32 v[48:49], v[48:49], v[50:51]
	v_mul_f32_e32 v50, 0xbfb8aa3b, v43
	v_add_f32_e32 v19, v48, v49
	ds_bpermute_b32 v48, v16, v19
	v_mul_f32_e32 v49, 0xbfb8aa3b, v42
	v_exp_f32_e32 v49, v49
	v_exp_f32_e32 v50, v50
	v_rcp_f32_e32 v46, v46
	s_waitcnt lgkmcnt(0)
	v_add_f32_e32 v19, v19, v48
	ds_bpermute_b32 v51, v17, v19
	v_add_f32_e32 v48, 1.0, v49
	v_add_f32_e32 v49, 1.0, v50
	v_rcp_f32_e32 v47, v47
	v_rcp_f32_e32 v44, v44
	s_waitcnt lgkmcnt(0)
	v_add_f32_e32 v19, v19, v51
	ds_bpermute_b32 v50, v52, v19
	v_mul_f32_e32 v51, 0xbfb8aa3b, v8
	v_exp_f32_e32 v51, v51
	v_pk_mul_f32 v[38:39], v[38:39], v[46:47]
	v_rcp_f32_e32 v45, v45
	s_waitcnt lgkmcnt(0)
	v_add_f32_e32 v19, v19, v50
	ds_bpermute_b32 v56, v18, v19
	v_add_f32_e32 v50, 1.0, v51
	v_add_f32_e32 v51, 1.0, v55
	v_rcp_f32_e32 v50, v50
	v_rcp_f32_e32 v51, v51
	s_waitcnt lgkmcnt(0)
	v_add_f32_e32 v19, v19, v56
	ds_bpermute_b32 v55, v53, v19
	v_rcp_f32_e32 v48, v48
	v_pk_mul_f32 v[8:9], v[8:9], v[50:51]
	v_rcp_f32_e32 v49, v49
	v_pk_mul_f32 v[44:45], v[10:11], v[44:45]
	s_waitcnt lgkmcnt(0)
	v_add_f32_e32 v19, v19, v55
	ds_bpermute_b32 v46, v54, v19
	v_cvt_pk_f16_f32 v11, v8, v9
	v_cvt_pk_f16_f32 v9, v38, v39
	v_pk_mul_f32 v[42:43], v[42:43], v[48:49]
	s_waitcnt lgkmcnt(0)
	v_add_f32_e32 v8, v19, v46
	v_fmamk_f32 v8, v8, 0x3b000000, v175
	v_rsq_f32_e32 v38, v8
	v_cvt_pk_f16_f32 v10, v42, v43
	v_cvt_pk_f16_f32 v8, v44, v45
	v_lshl_add_u64 v[42:43], v[98:99], 0, s[12:13]
	global_store_dwordx4 v[42:43], v[8:11], off
	v_pk_add_f32 v[42:43], v[142:143], v[4:5]
	v_pk_add_f32 v[44:45], v[148:149], v[2:3]
	v_pk_mul_f32 v[8:9], v[14:15], v[38:39] op_sel_hi:[1,0]
	v_pk_add_f32 v[14:15], v[146:147], v[6:7]
	v_pk_add_f32 v[46:47], v[144:145], v[0:1]
	v_pk_mov_b32 v[10:11], v[42:43], v[14:15] op_sel:[1,0]
	v_mov_b32_e32 v48, v42
	v_mov_b32_e32 v49, v15
	v_pk_add_f32 v[10:11], v[10:11], v[48:49]
	v_mov_b32_e32 v48, v44
	v_mov_b32_e32 v49, v46
	v_mov_b32_e32 v50, v45
	v_mov_b32_e32 v51, v47
	v_pk_add_f32 v[48:49], v[48:49], v[50:51]
	v_add_f32_e32 v10, v10, v11
	v_add_f32_e32 v10, v49, v10
	v_add_f32_e32 v19, v48, v10
	ds_bpermute_b32 v39, v16, v19
	v_pk_fma_f32 v[8:9], v[28:29], v[8:9], v[32:33]
	s_waitcnt lgkmcnt(0)
	v_add_f32_e32 v19, v19, v39
	v_pk_mul_f32 v[10:11], v[12:13], v[38:39] op_sel_hi:[1,0]
	v_pk_mul_f32 v[12:13], v[40:41], v[38:39] op_sel_hi:[1,0]
	ds_bpermute_b32 v39, v17, v19
	v_pk_fma_f32 v[12:13], v[20:21], v[12:13], v[24:25]
	v_pk_fma_f32 v[10:11], v[30:31], v[10:11], v[34:35]
	v_mul_f32_e32 v49, 0xbfb8aa3b, v12
	v_exp_f32_e32 v55, v49
	s_waitcnt lgkmcnt(0)
	v_add_f32_e32 v19, v19, v39
	v_pk_mul_f32 v[36:37], v[36:37], v[38:39] op_sel_hi:[1,0]
	ds_bpermute_b32 v39, v52, v19
	v_mul_f32_e32 v40, 0xbfb8aa3b, v9
	v_exp_f32_e32 v40, v40
	v_mul_f32_e32 v41, 0xbfb8aa3b, v10
	v_exp_f32_e32 v41, v41
	s_waitcnt lgkmcnt(0)
	v_add_f32_e32 v19, v19, v39
	ds_bpermute_b32 v39, v18, v19
	v_pk_fma_f32 v[36:37], v[22:23], v[36:37], v[26:27]
	v_add_f32_e32 v40, 1.0, v40
	v_mul_f32_e32 v38, 0xbfb8aa3b, v8
	v_exp_f32_e32 v38, v38
	s_waitcnt lgkmcnt(0)
	v_add_f32_e32 v19, v19, v39
	ds_bpermute_b32 v48, v53, v19
	v_rcp_f32_e32 v39, v40
	v_add_f32_e32 v40, 1.0, v41
	v_mul_f32_e32 v41, 0xbfb8aa3b, v11
	v_exp_f32_e32 v41, v41
	s_waitcnt lgkmcnt(0)
	v_add_f32_e32 v19, v19, v48
	ds_bpermute_b32 v48, v54, v19
	v_add_f32_e32 v38, 1.0, v38
	v_add_f32_e32 v41, 1.0, v41
	v_rcp_f32_e32 v38, v38
	v_rcp_f32_e32 v40, v40
	s_waitcnt lgkmcnt(0)
; #define GAS __attribute__((address_space(1)))
; __device__ __forceinline__ f32x4 sigm4(f32x4 x) { f32x4 r; r[0] = sigm(x[0]); r[1] = sigm(x[1]); r[2] = sigm(x[2]); r[3] = sigm(x[3]); return r; }
; __device__ __forceinline__ float sq4(f32x4 x) { return (x[0] * x[0] + x[1] * x[1]) + (x[2] * x[2] + x[3] * x[3]); }
; __device__ __forceinline__ void conv_phase(KP P, LAS unsigned char* lds, int gw, int NGW, int tid, int lane) {
;     ...
; #pragma unroll
;         for (int i = 0; i < 8; ++i) {
;             f32x4 y0 = {acc[i][0], acc[i][1], acc[i][2], acc[i][3]}, y1 = {acc[i][4], acc[i][5], acc[i][6], acc[i][7]};
;             y0 += b0; y1 += b1;
;             const float mu = wave_sum((y0[0] + y0[1]) + (y0[2] + y0[3]) + (y1[0] + y1[1]) + (y1[2] + y1[3])) * (1.f / 512.f);
;             y0 -= mu; y1 -= mu;
;             const float rstd = __builtin_amdgcn_rsqf(wave_sum(sq4(y0) + sq4(y1)) * (1.f / 512.f) + EPS);
;             y0 = y0 * rstd * g0 + l0; y1 = y1 * rstd * g1 + l1;
;             *(GAS h8*)(CONV + (size_t)(tok0 + i) * 512 + 8 * lane) = pack8(y0 * sigm4(y0), y1 * sigm4(y1));
;         }
	v_add_f32_e32 v19, v19, v48
	v_fmamk_f32 v43, v19, 0xbb000000, v43
	v_fmamk_f32 v47, v19, 0xbb000000, v47
	v_fmamk_f32 v15, v19, 0xbb000000, v15
	v_fmac_f32_e32 v42, 0xbb000000, v19
	v_fmamk_f32 v45, v19, 0xbb000000, v45
	v_fmac_f32_e32 v46, 0xbb000000, v19
	v_mov_b32_e32 v50, v43
	v_mov_b32_e32 v51, v47
	v_fmac_f32_e32 v14, 0xbb000000, v19
	v_fmac_f32_e32 v44, 0xbb000000, v19
	v_mov_b32_e32 v48, v42
	v_mov_b32_e32 v49, v46
	v_pk_mul_f32 v[50:51], v[50:51], v[50:51]
	v_mov_b32_e32 v56, v15
	v_mov_b32_e32 v57, v45
	v_pk_fma_f32 v[48:49], v[48:49], v[48:49], v[50:51]
	v_mov_b32_e32 v50, v14
	v_mov_b32_e32 v51, v44
	v_pk_mul_f32 v[56:57], v[56:57], v[56:57]
	v_rcp_f32_e32 v41, v41
	v_pk_fma_f32 v[50:51], v[50:51], v[50:51], v[56:57]
	v_pk_mul_f32 v[38:39], v[8:9], v[38:39]
	v_pk_add_f32 v[48:49], v[48:49], v[50:51]
	v_mul_f32_e32 v50, 0xbfb8aa3b, v13
	v_add_f32_e32 v19, v48, v49
	ds_bpermute_b32 v48, v16, v19
	v_exp_f32_e32 v50, v50
	v_add_f32_e32 v49, 1.0, v55
	v_mul_f32_e32 v55, 0xbfb8aa3b, v37
	v_exp_f32_e32 v55, v55
	s_waitcnt lgkmcnt(0)
	v_add_f32_e32 v19, v19, v48
	ds_bpermute_b32 v51, v17, v19
	v_rcp_f32_e32 v48, v49
	v_add_f32_e32 v49, 1.0, v50
	v_mul_f32_e32 v50, 0xbfb8aa3b, v36
	v_exp_f32_e32 v50, v50
	s_waitcnt lgkmcnt(0)
	v_add_f32_e32 v19, v19, v51
	ds_bpermute_b32 v51, v52, v19
	v_pk_mul_f32 v[8:9], v[10:11], v[40:41]
	v_add_f32_e32 v50, 1.0, v50
	v_rcp_f32_e32 v50, v50
	v_rcp_f32_e32 v49, v49
	s_waitcnt lgkmcnt(0)
	v_add_f32_e32 v19, v19, v51
	ds_bpermute_b32 v56, v18, v19
	v_add_f32_e32 v51, 1.0, v55
	v_rcp_f32_e32 v51, v51
	v_cvt_pk_f16_f32 v9, v8, v9
	v_cvt_pk_f16_f32 v8, v38, v39
	s_waitcnt lgkmcnt(0)
	v_add_f32_e32 v19, v19, v56
	ds_bpermute_b32 v55, v53, v19
	v_pk_mul_f32 v[10:11], v[36:37], v[50:51]
	v_pk_add_f32 v[38:39], v[138:139], v[6:7]
	v_pk_add_f32 v[40:41], v[134:135], v[4:5]
	v_pk_mul_f32 v[12:13], v[12:13], v[48:49]
	s_waitcnt lgkmcnt(0)
	v_add_f32_e32 v19, v19, v55
	ds_bpermute_b32 v36, v54, v19
	v_pk_add_f32 v[48:49], v[140:141], v[2:3]
	v_pk_add_f32 v[50:51], v[136:137], v[0:1]
	v_pk_mov_b32 v[56:57], v[40:41], v[38:39] op_sel:[1,0]
	v_mov_b32_e32 v58, v40
	s_waitcnt lgkmcnt(0)
	v_add_f32_e32 v19, v19, v36
	v_mov_b32_e32 v59, v39
	v_fmamk_f32 v19, v19, 0x3b000000, v175
	v_pk_add_f32 v[56:57], v[56:57], v[58:59]
	v_mov_b32_e32 v58, v48
	v_mov_b32_e32 v59, v50
	v_mov_b32_e32 v60, v49
	v_mov_b32_e32 v61, v51
	v_rsq_f32_e32 v36, v19
	v_pk_add_f32 v[58:59], v[58:59], v[60:61]
	v_add_f32_e32 v19, v56, v57
	v_add_f32_e32 v19, v59, v19
	v_add_f32_e32 v19, v58, v19
	ds_bpermute_b32 v37, v16, v19
	v_cvt_pk_f16_f32 v11, v10, v11
	v_cvt_pk_f16_f32 v10, v12, v13
	v_lshl_add_u64 v[12:13], v[98:99], 0, s[6:7]
	global_store_dwordx4 v[12:13], v[8:11], off
	s_waitcnt lgkmcnt(0)
	v_add_f32_e32 v19, v19, v37
	v_pk_mul_f32 v[8:9], v[42:43], v[36:37] op_sel_hi:[1,0]
	v_pk_mul_f32 v[10:11], v[14:15], v[36:37] op_sel_hi:[1,0]
	ds_bpermute_b32 v37, v17, v19
	v_pk_fma_f32 v[8:9], v[28:29], v[8:9], v[32:33]
	v_pk_fma_f32 v[10:11], v[30:31], v[10:11], v[34:35]
	v_mul_f32_e32 v42, 0xbfb8aa3b, v9
	v_exp_f32_e32 v42, v42
	s_waitcnt lgkmcnt(0)
	v_add_f32_e32 v19, v19, v37
	v_pk_mul_f32 v[12:13], v[46:47], v[36:37] op_sel_hi:[1,0]
	v_pk_mul_f32 v[14:15], v[44:45], v[36:37] op_sel_hi:[1,0]
	ds_bpermute_b32 v36, v52, v19
	v_mul_f32_e32 v37, 0xbfb8aa3b, v8
	v_exp_f32_e32 v37, v37
	v_mul_f32_e32 v44, 0xbfb8aa3b, v11
	v_exp_f32_e32 v44, v44
	s_waitcnt lgkmcnt(0)
	v_add_f32_e32 v19, v19, v36
	ds_bpermute_b32 v43, v18, v19
	v_add_f32_e32 v36, 1.0, v37
	v_add_f32_e32 v37, 1.0, v42
	v_pk_fma_f32 v[12:13], v[20:21], v[12:13], v[24:25]
	v_pk_fma_f32 v[14:15], v[22:23], v[14:15], v[26:27]
	s_waitcnt lgkmcnt(0)
	v_add_f32_e32 v19, v19, v43
	ds_bpermute_b32 v42, v53, v19
	v_mul_f32_e32 v43, 0xbfb8aa3b, v10
	v_exp_f32_e32 v43, v43
	v_mul_f32_e32 v55, 0xbfb8aa3b, v15
	v_exp_f32_e32 v55, v55
	s_waitcnt lgkmcnt(0)
	v_add_f32_e32 v19, v19, v42
	ds_bpermute_b32 v45, v54, v19
	v_add_f32_e32 v42, 1.0, v43
	v_add_f32_e32 v43, 1.0, v44
	v_rcp_f32_e32 v36, v36
	v_rcp_f32_e32 v37, v37
	s_waitcnt lgkmcnt(0)
	v_add_f32_e32 v19, v19, v45
	v_fmamk_f32 v41, v19, 0xbb000000, v41
	v_fmamk_f32 v51, v19, 0xbb000000, v51
	v_fmamk_f32 v39, v19, 0xbb000000, v39
	v_fmac_f32_e32 v40, 0xbb000000, v19
	v_fmamk_f32 v49, v19, 0xbb000000, v49
	v_fmac_f32_e32 v50, 0xbb000000, v19
	v_mov_b32_e32 v46, v41
	v_mov_b32_e32 v47, v51
	v_fmac_f32_e32 v38, 0xbb000000, v19
	v_fmac_f32_e32 v48, 0xbb000000, v19
	v_mov_b32_e32 v44, v40
	v_mov_b32_e32 v45, v50
	v_pk_mul_f32 v[46:47], v[46:47], v[46:47]
	v_mov_b32_e32 v56, v39
	v_mov_b32_e32 v57, v49
	v_pk_fma_f32 v[44:45], v[44:45], v[44:45], v[46:47]
	v_mov_b32_e32 v46, v38
	v_mov_b32_e32 v47, v48
	v_pk_mul_f32 v[56:57], v[56:57], v[56:57]
	v_rcp_f32_e32 v42, v42
	v_pk_fma_f32 v[46:47], v[46:47], v[46:47], v[56:57]
	v_rcp_f32_e32 v43, v43
	v_pk_add_f32 v[44:45], v[44:45], v[46:47]
	v_mul_f32_e32 v46, 0xbfb8aa3b, v13
	v_add_f32_e32 v19, v44, v45
	ds_bpermute_b32 v44, v16, v19
	v_mul_f32_e32 v45, 0xbfb8aa3b, v12
	v_exp_f32_e32 v45, v45
	v_exp_f32_e32 v46, v46
	v_pk_mul_f32 v[36:37], v[8:9], v[36:37]
	s_waitcnt lgkmcnt(0)
	v_add_f32_e32 v19, v19, v44
	ds_bpermute_b32 v47, v17, v19
	v_add_f32_e32 v44, 1.0, v45
	v_add_f32_e32 v45, 1.0, v46
	v_pk_mul_f32 v[8:9], v[10:11], v[42:43]
	v_rcp_f32_e32 v44, v44
	s_waitcnt lgkmcnt(0)
	v_add_f32_e32 v19, v19, v47
	ds_bpermute_b32 v46, v52, v19
	v_mul_f32_e32 v47, 0xbfb8aa3b, v14
	v_exp_f32_e32 v47, v47
	v_rcp_f32_e32 v45, v45
	v_cvt_pk_f16_f32 v9, v8, v9
	s_waitcnt lgkmcnt(0)
	v_add_f32_e32 v19, v19, v46
	ds_bpermute_b32 v56, v18, v19
	v_add_f32_e32 v46, 1.0, v47
	v_add_f32_e32 v47, 1.0, v55
	v_rcp_f32_e32 v46, v46
	v_rcp_f32_e32 v47, v47
	s_waitcnt lgkmcnt(0)
; #define GAS __attribute__((address_space(1)))
; __device__ __forceinline__ f32x4 sigm4(f32x4 x) { f32x4 r; r[0] = sigm(x[0]); r[1] = sigm(x[1]); r[2] = sigm(x[2]); r[3] = sigm(x[3]); return r; }
; __device__ __forceinline__ float sq4(f32x4 x) { return (x[0] * x[0] + x[1] * x[1]) + (x[2] * x[2] + x[3] * x[3]); }
; __device__ __forceinline__ void conv_phase(KP P, LAS unsigned char* lds, int gw, int NGW, int tid, int lane) {
;     ...
; #pragma unroll
;         for (int i = 0; i < 8; ++i) {
;             f32x4 y0 = {acc[i][0], acc[i][1], acc[i][2], acc[i][3]}, y1 = {acc[i][4], acc[i][5], acc[i][6], acc[i][7]};
;             y0 += b0; y1 += b1;
;             const float mu = wave_sum((y0[0] + y0[1]) + (y0[2] + y0[3]) + (y1[0] + y1[1]) + (y1[2] + y1[3])) * (1.f / 512.f);
;             y0 -= mu; y1 -= mu;
;             const float rstd = __builtin_amdgcn_rsqf(wave_sum(sq4(y0) + sq4(y1)) * (1.f / 512.f) + EPS);
;             y0 = y0 * rstd * g0 + l0; y1 = y1 * rstd * g1 + l1;
;             *(GAS h8*)(CONV + (size_t)(tok0 + i) * 512 + 8 * lane) = pack8(y0 * sigm4(y0), y1 * sigm4(y1));
;         }
	v_add_f32_e32 v19, v19, v56
	ds_bpermute_b32 v55, v53, v19
	v_pk_mul_f32 v[12:13], v[12:13], v[44:45]
	v_pk_mul_f32 v[10:11], v[14:15], v[46:47]
	v_lshl_add_u64 v[14:15], v[98:99], 0, s[38:39]
	v_cvt_pk_f16_f32 v11, v10, v11
	s_waitcnt lgkmcnt(0)
	v_add_f32_e32 v19, v19, v55
	ds_bpermute_b32 v42, v54, v19
	v_cvt_pk_f16_f32 v10, v12, v13
	s_waitcnt lgkmcnt(0)
	v_add_f32_e32 v8, v19, v42
	v_fmamk_f32 v8, v8, 0x3b000000, v175
	v_rsq_f32_e32 v12, v8
	v_cvt_pk_f16_f32 v8, v36, v37
	global_store_dwordx4 v[14:15], v[8:11], off
	v_pk_add_f32 v[14:15], v[130:131], v[6:7]
	v_pk_add_f32 v[36:37], v[126:127], v[4:5]
	v_pk_mul_f32 v[8:9], v[40:41], v[12:13] op_sel_hi:[1,0]
	v_pk_add_f32 v[40:41], v[132:133], v[2:3]
	v_pk_add_f32 v[42:43], v[128:129], v[0:1]
	v_pk_mov_b32 v[10:11], v[36:37], v[14:15] op_sel:[1,0]
	v_mov_b32_e32 v44, v36
	v_mov_b32_e32 v45, v15
	v_pk_add_f32 v[10:11], v[10:11], v[44:45]
	v_mov_b32_e32 v44, v40
	v_mov_b32_e32 v45, v42
	v_mov_b32_e32 v46, v41
	v_mov_b32_e32 v47, v43
	v_pk_add_f32 v[44:45], v[44:45], v[46:47]
	v_add_f32_e32 v10, v10, v11
	v_add_f32_e32 v10, v45, v10
	v_add_f32_e32 v13, v44, v10
	ds_bpermute_b32 v19, v16, v13
	v_pk_mul_f32 v[10:11], v[38:39], v[12:13] op_sel_hi:[1,0]
	v_pk_mul_f32 v[38:39], v[50:51], v[12:13] op_sel_hi:[1,0]
	v_pk_fma_f32 v[10:11], v[30:31], v[10:11], v[34:35]
	v_pk_fma_f32 v[38:39], v[20:21], v[38:39], v[24:25]
	s_waitcnt lgkmcnt(0)
	v_add_f32_e32 v19, v13, v19
	ds_bpermute_b32 v44, v17, v19
	v_pk_mul_f32 v[12:13], v[48:49], v[12:13] op_sel_hi:[1,0]
	v_mul_f32_e32 v48, 0xbfb8aa3b, v11
	v_exp_f32_e32 v48, v48
	v_pk_fma_f32 v[8:9], v[28:29], v[8:9], v[32:33]
	s_waitcnt lgkmcnt(0)
	v_add_f32_e32 v19, v19, v44
	ds_bpermute_b32 v44, v52, v19
	v_add_f32_e32 v55, 1.0, v48
	v_mul_f32_e32 v48, 0xbfb8aa3b, v38
	v_exp_f32_e32 v58, v48
	v_mul_f32_e32 v45, 0xbfb8aa3b, v8
	s_waitcnt lgkmcnt(0)
	v_add_f32_e32 v19, v19, v44
	ds_bpermute_b32 v47, v18, v19
	v_exp_f32_e32 v45, v45
	v_mul_f32_e32 v46, 0xbfb8aa3b, v9
	v_exp_f32_e32 v46, v46
	v_pk_fma_f32 v[12:13], v[22:23], v[12:13], v[26:27]
	s_waitcnt lgkmcnt(0)
	v_add_f32_e32 v19, v19, v47
	ds_bpermute_b32 v47, v53, v19
	v_add_f32_e32 v45, 1.0, v45
	v_rcp_f32_e32 v44, v45
	v_add_f32_e32 v45, 1.0, v46
	v_mul_f32_e32 v46, 0xbfb8aa3b, v10
	s_waitcnt lgkmcnt(0)
	v_add_f32_e32 v19, v19, v47
	ds_bpermute_b32 v47, v54, v19
	v_exp_f32_e32 v46, v46
	v_rcp_f32_e32 v45, v45
	s_waitcnt lgkmcnt(0)
	v_add_f32_e32 v19, v19, v47
	v_fmamk_f32 v37, v19, 0xbb000000, v37
	v_fmamk_f32 v43, v19, 0xbb000000, v43
	v_fmamk_f32 v15, v19, 0xbb000000, v15
	v_fmac_f32_e32 v36, 0xbb000000, v19
	v_fmamk_f32 v41, v19, 0xbb000000, v41
	v_fmac_f32_e32 v42, 0xbb000000, v19
	v_mov_b32_e32 v50, v37
	v_mov_b32_e32 v51, v43
	v_fmac_f32_e32 v14, 0xbb000000, v19
	v_fmac_f32_e32 v40, 0xbb000000, v19
	v_mov_b32_e32 v48, v36
	v_mov_b32_e32 v49, v42
	v_pk_mul_f32 v[50:51], v[50:51], v[50:51]
	v_mov_b32_e32 v56, v15
	v_mov_b32_e32 v57, v41
	v_pk_fma_f32 v[48:49], v[48:49], v[48:49], v[50:51]
	v_mov_b32_e32 v50, v14
	v_mov_b32_e32 v51, v40
	v_pk_mul_f32 v[56:57], v[56:57], v[56:57]
	v_rcp_f32_e32 v47, v55
	v_pk_fma_f32 v[50:51], v[50:51], v[50:51], v[56:57]
	v_mul_f32_e32 v55, 0xbfb8aa3b, v13
	v_pk_add_f32 v[48:49], v[48:49], v[50:51]
	v_exp_f32_e32 v55, v55
	v_add_f32_e32 v19, v48, v49
	ds_bpermute_b32 v48, v16, v19
	v_mul_f32_e32 v50, 0xbfb8aa3b, v39
	v_exp_f32_e32 v50, v50
	v_add_f32_e32 v46, 1.0, v46
	v_add_f32_e32 v49, 1.0, v58
	s_waitcnt lgkmcnt(0)
	v_add_f32_e32 v19, v19, v48
	ds_bpermute_b32 v51, v17, v19
	v_rcp_f32_e32 v46, v46
	v_rcp_f32_e32 v48, v49
	v_add_f32_e32 v49, 1.0, v50
	v_mul_f32_e32 v50, 0xbfb8aa3b, v12
	s_waitcnt lgkmcnt(0)
	v_add_f32_e32 v19, v19, v51
	ds_bpermute_b32 v51, v52, v19
	v_exp_f32_e32 v50, v50
	v_pk_mul_f32 v[44:45], v[8:9], v[44:45]
	v_pk_mul_f32 v[8:9], v[10:11], v[46:47]
	v_rcp_f32_e32 v49, v49
	s_waitcnt lgkmcnt(0)
	v_add_f32_e32 v19, v19, v51
	ds_bpermute_b32 v56, v18, v19
	v_add_f32_e32 v51, 1.0, v55
	v_add_f32_e32 v50, 1.0, v50
	v_rcp_f32_e32 v50, v50
	v_rcp_f32_e32 v51, v51
	s_waitcnt lgkmcnt(0)
	v_add_f32_e32 v19, v19, v56
	ds_bpermute_b32 v55, v53, v19
	v_cvt_pk_f16_f32 v9, v8, v9
	v_cvt_pk_f16_f32 v8, v44, v45
	v_pk_add_f32 v[44:45], v[122:123], v[6:7]
	v_pk_mul_f32 v[38:39], v[38:39], v[48:49]
	s_waitcnt lgkmcnt(0)
	v_add_f32_e32 v19, v19, v55
	ds_bpermute_b32 v46, v54, v19
	v_pk_mul_f32 v[10:11], v[12:13], v[50:51]
	v_pk_add_f32 v[48:49], v[124:125], v[2:3]
	v_pk_add_f32 v[50:51], v[120:121], v[0:1]
	v_mov_b32_e32 v59, v45
	s_waitcnt lgkmcnt(0)
	v_add_f32_e32 v19, v19, v46
	v_pk_add_f32 v[46:47], v[118:119], v[4:5]
	v_fmamk_f32 v19, v19, 0x3b000000, v175
	v_pk_mov_b32 v[56:57], v[46:47], v[44:45] op_sel:[1,0]
	v_mov_b32_e32 v58, v46
	v_pk_add_f32 v[56:57], v[56:57], v[58:59]
	v_mov_b32_e32 v58, v48
	v_mov_b32_e32 v59, v50
	v_mov_b32_e32 v60, v49
	v_mov_b32_e32 v61, v51
	v_cvt_pk_f16_f32 v11, v10, v11
	v_cvt_pk_f16_f32 v10, v38, v39
	v_rsq_f32_e32 v38, v19
	v_pk_add_f32 v[58:59], v[58:59], v[60:61]
	v_add_f32_e32 v19, v56, v57
	v_add_f32_e32 v19, v59, v19
	v_add_f32_e32 v19, v58, v19
	ds_bpermute_b32 v39, v16, v19
	v_lshl_add_u64 v[12:13], v[98:99], 0, s[26:27]
	global_store_dwordx4 v[12:13], v[8:11], off
	s_waitcnt lgkmcnt(0)
	v_add_f32_e32 v19, v19, v39
	v_pk_mul_f32 v[8:9], v[36:37], v[38:39] op_sel_hi:[1,0]
	ds_bpermute_b32 v36, v17, v19
	v_pk_mul_f32 v[10:11], v[14:15], v[38:39] op_sel_hi:[1,0]
	v_pk_fma_f32 v[8:9], v[28:29], v[8:9], v[32:33]
	v_pk_mul_f32 v[12:13], v[42:43], v[38:39] op_sel_hi:[1,0]
	v_pk_mul_f32 v[14:15], v[40:41], v[38:39] op_sel_hi:[1,0]
	s_waitcnt lgkmcnt(0)
; #define GAS __attribute__((address_space(1)))
; __device__ __forceinline__ f32x4 sigm4(f32x4 x) { f32x4 r; r[0] = sigm(x[0]); r[1] = sigm(x[1]); r[2] = sigm(x[2]); r[3] = sigm(x[3]); return r; }
; __device__ __forceinline__ float sq4(f32x4 x) { return (x[0] * x[0] + x[1] * x[1]) + (x[2] * x[2] + x[3] * x[3]); }
; __device__ __forceinline__ void conv_phase(KP P, LAS unsigned char* lds, int gw, int NGW, int tid, int lane) {
;     ...
; #pragma unroll
;         for (int i = 0; i < 8; ++i) {
;             f32x4 y0 = {acc[i][0], acc[i][1], acc[i][2], acc[i][3]}, y1 = {acc[i][4], acc[i][5], acc[i][6], acc[i][7]};
;             y0 += b0; y1 += b1;
;             const float mu = wave_sum((y0[0] + y0[1]) + (y0[2] + y0[3]) + (y1[0] + y1[1]) + (y1[2] + y1[3])) * (1.f / 512.f);
;             y0 -= mu; y1 -= mu;
;             const float rstd = __builtin_amdgcn_rsqf(wave_sum(sq4(y0) + sq4(y1)) * (1.f / 512.f) + EPS);
;             y0 = y0 * rstd * g0 + l0; y1 = y1 * rstd * g1 + l1;
;             *(GAS h8*)(CONV + (size_t)(tok0 + i) * 512 + 8 * lane) = pack8(y0 * sigm4(y0), y1 * sigm4(y1));
;         }
	v_add_f32_e32 v19, v19, v36
	ds_bpermute_b32 v36, v52, v19
	v_mul_f32_e32 v37, 0xbfb8aa3b, v8
	v_mul_f32_e32 v38, 0xbfb8aa3b, v9
	v_exp_f32_e32 v37, v37
	v_exp_f32_e32 v38, v38
	s_waitcnt lgkmcnt(0)
	v_add_f32_e32 v19, v19, v36
	ds_bpermute_b32 v39, v18, v19
	v_add_f32_e32 v36, 1.0, v37
	v_add_f32_e32 v37, 1.0, v38
	v_pk_fma_f32 v[10:11], v[30:31], v[10:11], v[34:35]
	v_pk_fma_f32 v[12:13], v[20:21], v[12:13], v[24:25]
	s_waitcnt lgkmcnt(0)
	v_add_f32_e32 v19, v19, v39
	ds_bpermute_b32 v38, v53, v19
	v_mul_f32_e32 v39, 0xbfb8aa3b, v10
	v_mul_f32_e32 v40, 0xbfb8aa3b, v11
	v_exp_f32_e32 v39, v39
	v_exp_f32_e32 v40, v40
	s_waitcnt lgkmcnt(0)
	v_add_f32_e32 v19, v19, v38
	ds_bpermute_b32 v41, v54, v19
	v_add_f32_e32 v38, 1.0, v39
	v_add_f32_e32 v39, 1.0, v40
	v_pk_fma_f32 v[14:15], v[22:23], v[14:15], v[26:27]
	v_rcp_f32_e32 v36, v36
	s_waitcnt lgkmcnt(0)
	v_add_f32_e32 v19, v19, v41
	v_fmamk_f32 v47, v19, 0xbb000000, v47
	v_fmamk_f32 v51, v19, 0xbb000000, v51
	v_fmamk_f32 v45, v19, 0xbb000000, v45
	v_fmac_f32_e32 v46, 0xbb000000, v19
	v_fmamk_f32 v49, v19, 0xbb000000, v49
	v_fmac_f32_e32 v50, 0xbb000000, v19
	v_mov_b32_e32 v42, v47
	v_mov_b32_e32 v43, v51
	v_fmac_f32_e32 v44, 0xbb000000, v19
	v_fmac_f32_e32 v48, 0xbb000000, v19
	v_mov_b32_e32 v40, v46
	v_mov_b32_e32 v41, v50
	v_pk_mul_f32 v[42:43], v[42:43], v[42:43]
	v_mov_b32_e32 v56, v45
	v_mov_b32_e32 v57, v49
	v_pk_fma_f32 v[40:41], v[40:41], v[40:41], v[42:43]
	v_mov_b32_e32 v42, v44
	v_mov_b32_e32 v43, v48
	v_pk_mul_f32 v[56:57], v[56:57], v[56:57]
	v_mul_f32_e32 v55, 0xbfb8aa3b, v15
	v_pk_fma_f32 v[42:43], v[42:43], v[42:43], v[56:57]
	v_exp_f32_e32 v55, v55
	v_pk_add_f32 v[40:41], v[40:41], v[42:43]
	v_mul_f32_e32 v42, 0xbfb8aa3b, v13
	v_add_f32_e32 v19, v40, v41
	ds_bpermute_b32 v40, v16, v19
	v_mul_f32_e32 v41, 0xbfb8aa3b, v12
	v_exp_f32_e32 v41, v41
	v_exp_f32_e32 v42, v42
	v_rcp_f32_e32 v37, v37
	s_waitcnt lgkmcnt(0)
	v_add_f32_e32 v19, v19, v40
	ds_bpermute_b32 v43, v17, v19
	v_add_f32_e32 v40, 1.0, v41
	v_add_f32_e32 v41, 1.0, v42
	v_rcp_f32_e32 v38, v38
	v_rcp_f32_e32 v39, v39
	s_waitcnt lgkmcnt(0)
	v_add_f32_e32 v19, v19, v43
	ds_bpermute_b32 v42, v52, v19
	v_mul_f32_e32 v43, 0xbfb8aa3b, v14
	v_exp_f32_e32 v43, v43
	v_pk_mul_f32 v[36:37], v[8:9], v[36:37]
	v_pk_mul_f32 v[8:9], v[10:11], v[38:39]
	s_waitcnt lgkmcnt(0)
	v_add_f32_e32 v19, v19, v42
	ds_bpermute_b32 v56, v18, v19
	v_add_f32_e32 v42, 1.0, v43
	v_add_f32_e32 v43, 1.0, v55
	v_rcp_f32_e32 v40, v40
	v_rcp_f32_e32 v41, v41
	s_waitcnt lgkmcnt(0)
	v_add_f32_e32 v19, v19, v56
	ds_bpermute_b32 v55, v53, v19
	v_rcp_f32_e32 v42, v42
	v_rcp_f32_e32 v43, v43
	v_cvt_pk_f16_f32 v9, v8, v9
	v_pk_mul_f32 v[12:13], v[12:13], v[40:41]
	s_waitcnt lgkmcnt(0)
	v_add_f32_e32 v19, v19, v55
	ds_bpermute_b32 v38, v54, v19
	v_pk_mul_f32 v[10:11], v[14:15], v[42:43]
	v_lshl_add_u64 v[14:15], v[98:99], 0, s[20:21]
	v_cvt_pk_f16_f32 v11, v10, v11
	v_cvt_pk_f16_f32 v10, v12, v13
	s_waitcnt lgkmcnt(0)
	v_add_f32_e32 v8, v19, v38
	v_fmamk_f32 v8, v8, 0x3b000000, v175
	v_rsq_f32_e32 v12, v8
	v_cvt_pk_f16_f32 v8, v36, v37
	global_store_dwordx4 v[14:15], v[8:11], off
	v_pk_add_f32 v[14:15], v[108:109], v[6:7]
	v_pk_add_f32 v[36:37], v[102:103], v[4:5]
	v_pk_add_f32 v[38:39], v[114:115], v[2:3]
	v_pk_add_f32 v[40:41], v[106:107], v[0:1]
	v_pk_mov_b32 v[10:11], v[36:37], v[14:15] op_sel:[1,0]
	v_mov_b32_e32 v42, v36
	v_mov_b32_e32 v43, v15
	v_pk_mul_f32 v[8:9], v[46:47], v[12:13] op_sel_hi:[1,0]
	v_pk_add_f32 v[10:11], v[10:11], v[42:43]
	v_mov_b32_e32 v42, v38
	v_mov_b32_e32 v43, v40
	v_mov_b32_e32 v46, v39
	v_mov_b32_e32 v47, v41
	v_pk_add_f32 v[42:43], v[42:43], v[46:47]
	v_add_f32_e32 v10, v10, v11
	v_add_f32_e32 v10, v43, v10
	v_add_f32_e32 v13, v42, v10
	ds_bpermute_b32 v19, v16, v13
	v_pk_mul_f32 v[10:11], v[44:45], v[12:13] op_sel_hi:[1,0]
	v_pk_mul_f32 v[42:43], v[50:51], v[12:13] op_sel_hi:[1,0]
	v_pk_fma_f32 v[10:11], v[30:31], v[10:11], v[34:35]
	v_pk_fma_f32 v[42:43], v[20:21], v[42:43], v[24:25]
	s_waitcnt lgkmcnt(0)
	v_add_f32_e32 v19, v13, v19
	ds_bpermute_b32 v44, v17, v19
	v_pk_mul_f32 v[12:13], v[48:49], v[12:13] op_sel_hi:[1,0]
	v_mul_f32_e32 v48, 0xbfb8aa3b, v11
	v_exp_f32_e32 v48, v48
	v_pk_fma_f32 v[8:9], v[28:29], v[8:9], v[32:33]
	s_waitcnt lgkmcnt(0)
	v_add_f32_e32 v19, v19, v44
	ds_bpermute_b32 v44, v52, v19
	v_add_f32_e32 v55, 1.0, v48
	v_mul_f32_e32 v48, 0xbfb8aa3b, v42
	v_exp_f32_e32 v58, v48
	v_mul_f32_e32 v45, 0xbfb8aa3b, v8
	s_waitcnt lgkmcnt(0)
	v_add_f32_e32 v19, v19, v44
	ds_bpermute_b32 v47, v18, v19
	v_exp_f32_e32 v45, v45
	v_mul_f32_e32 v46, 0xbfb8aa3b, v9
	v_exp_f32_e32 v46, v46
	v_pk_fma_f32 v[12:13], v[22:23], v[12:13], v[26:27]
	s_waitcnt lgkmcnt(0)
	v_add_f32_e32 v19, v19, v47
	ds_bpermute_b32 v47, v53, v19
	v_add_f32_e32 v45, 1.0, v45
	v_rcp_f32_e32 v44, v45
	v_add_f32_e32 v45, 1.0, v46
	v_mul_f32_e32 v46, 0xbfb8aa3b, v10
	s_waitcnt lgkmcnt(0)
	v_add_f32_e32 v19, v19, v47
	ds_bpermute_b32 v47, v54, v19
	v_exp_f32_e32 v46, v46
	v_rcp_f32_e32 v45, v45
	v_pk_add_f32 v[6:7], v[112:113], v[6:7]
	v_pk_add_f32 v[4:5], v[104:105], v[4:5]
	s_waitcnt lgkmcnt(0)
	v_add_f32_e32 v19, v19, v47
	v_fmamk_f32 v37, v19, 0xbb000000, v37
	v_fmamk_f32 v41, v19, 0xbb000000, v41
	v_fmamk_f32 v15, v19, 0xbb000000, v15
	v_fmac_f32_e32 v36, 0xbb000000, v19
	v_fmamk_f32 v39, v19, 0xbb000000, v39
	v_fmac_f32_e32 v40, 0xbb000000, v19
	v_mov_b32_e32 v50, v37
	v_mov_b32_e32 v51, v41
	v_fmac_f32_e32 v14, 0xbb000000, v19
	v_fmac_f32_e32 v38, 0xbb000000, v19
	v_mov_b32_e32 v48, v36
	v_mov_b32_e32 v49, v40
	v_pk_mul_f32 v[50:51], v[50:51], v[50:51]
	v_mov_b32_e32 v56, v15
	v_mov_b32_e32 v57, v39
	v_pk_fma_f32 v[48:49], v[48:49], v[48:49], v[50:51]
	v_mov_b32_e32 v50, v14
	v_mov_b32_e32 v51, v38
	v_pk_mul_f32 v[56:57], v[56:57], v[56:57]
	v_rcp_f32_e32 v47, v55
	v_pk_fma_f32 v[50:51], v[50:51], v[50:51], v[56:57]
	v_mul_f32_e32 v55, 0xbfb8aa3b, v13
	v_pk_add_f32 v[48:49], v[48:49], v[50:51]
	v_exp_f32_e32 v55, v55
	v_add_f32_e32 v19, v48, v49
	ds_bpermute_b32 v48, v16, v19
	v_mul_f32_e32 v50, 0xbfb8aa3b, v43
	v_exp_f32_e32 v50, v50
	v_add_f32_e32 v46, 1.0, v46
	v_rcp_f32_e32 v46, v46
	s_waitcnt lgkmcnt(0)
; #define GAS __attribute__((address_space(1)))
; __device__ __forceinline__ f32x4 sigm4(f32x4 x) { f32x4 r; r[0] = sigm(x[0]); r[1] = sigm(x[1]); r[2] = sigm(x[2]); r[3] = sigm(x[3]); return r; }
; __device__ __forceinline__ float sq4(f32x4 x) { return (x[0] * x[0] + x[1] * x[1]) + (x[2] * x[2] + x[3] * x[3]); }
; __device__ __forceinline__ void conv_phase(KP P, LAS unsigned char* lds, int gw, int NGW, int tid, int lane) {
;     ...
; #pragma unroll
;         for (int i = 0; i < 8; ++i) {
;             f32x4 y0 = {acc[i][0], acc[i][1], acc[i][2], acc[i][3]}, y1 = {acc[i][4], acc[i][5], acc[i][6], acc[i][7]};
;             y0 += b0; y1 += b1;
;             const float mu = wave_sum((y0[0] + y0[1]) + (y0[2] + y0[3]) + (y1[0] + y1[1]) + (y1[2] + y1[3])) * (1.f / 512.f);
;             y0 -= mu; y1 -= mu;
;             const float rstd = __builtin_amdgcn_rsqf(wave_sum(sq4(y0) + sq4(y1)) * (1.f / 512.f) + EPS);
;             y0 = y0 * rstd * g0 + l0; y1 = y1 * rstd * g1 + l1;
;             *(GAS h8*)(CONV + (size_t)(tok0 + i) * 512 + 8 * lane) = pack8(y0 * sigm4(y0), y1 * sigm4(y1));
;         }
	v_add_f32_e32 v19, v19, v48
	ds_bpermute_b32 v51, v17, v19
	v_add_f32_e32 v49, 1.0, v58
	v_rcp_f32_e32 v48, v49
	v_add_f32_e32 v49, 1.0, v50
	v_mul_f32_e32 v50, 0xbfb8aa3b, v12
	s_waitcnt lgkmcnt(0)
	v_add_f32_e32 v19, v19, v51
	ds_bpermute_b32 v51, v52, v19
	v_exp_f32_e32 v50, v50
	v_pk_mul_f32 v[44:45], v[8:9], v[44:45]
	v_pk_mul_f32 v[8:9], v[10:11], v[46:47]
	v_rcp_f32_e32 v49, v49
	s_waitcnt lgkmcnt(0)
	v_add_f32_e32 v19, v19, v51
	ds_bpermute_b32 v56, v18, v19
	v_add_f32_e32 v51, 1.0, v55
	v_add_f32_e32 v50, 1.0, v50
	v_rcp_f32_e32 v50, v50
	v_rcp_f32_e32 v51, v51
	s_waitcnt lgkmcnt(0)
	v_add_f32_e32 v19, v19, v56
	ds_bpermute_b32 v55, v53, v19
	v_cvt_pk_f16_f32 v9, v8, v9
	v_cvt_pk_f16_f32 v8, v44, v45
	v_pk_add_f32 v[44:45], v[116:117], v[2:3]
	v_mov_b32_e32 v2, v4
	s_waitcnt lgkmcnt(0)
	v_add_f32_e32 v19, v19, v55
	ds_bpermute_b32 v46, v54, v19
	v_mov_b32_e32 v3, v7
	v_pk_mul_f32 v[42:43], v[42:43], v[48:49]
	v_mov_b32_e32 v48, v45
	v_pk_mul_f32 v[10:11], v[12:13], v[50:51]
	s_waitcnt lgkmcnt(0)
	v_add_f32_e32 v19, v19, v46
	v_pk_add_f32 v[46:47], v[110:111], v[0:1]
	v_pk_mov_b32 v[0:1], v[4:5], v[6:7] op_sel:[1,0]
	v_mov_b32_e32 v49, v47
	v_pk_add_f32 v[0:1], v[0:1], v[2:3]
	v_mov_b32_e32 v2, v44
	v_mov_b32_e32 v3, v46
	v_pk_add_f32 v[2:3], v[2:3], v[48:49]
	v_add_f32_e32 v0, v0, v1
	v_fmamk_f32 v19, v19, 0x3b000000, v175
	v_add_f32_e32 v0, v3, v0
	v_cvt_pk_f16_f32 v11, v10, v11
	v_cvt_pk_f16_f32 v10, v42, v43
	v_rsq_f32_e32 v42, v19
	v_add_f32_e32 v19, v2, v0
	ds_bpermute_b32 v43, v16, v19
	v_lshl_add_u64 v[12:13], v[98:99], 0, s[18:19]
	global_store_dwordx4 v[12:13], v[8:11], off
	s_waitcnt lgkmcnt(0)
	v_add_f32_e32 v12, v19, v43
	ds_bpermute_b32 v13, v17, v12
	v_pk_mul_f32 v[0:1], v[36:37], v[42:43] op_sel_hi:[1,0]
	v_pk_mul_f32 v[2:3], v[14:15], v[42:43] op_sel_hi:[1,0]
	v_pk_fma_f32 v[0:1], v[28:29], v[0:1], v[32:33]
	v_pk_fma_f32 v[2:3], v[30:31], v[2:3], v[34:35]
	s_waitcnt lgkmcnt(0)
	v_add_f32_e32 v12, v12, v13
	ds_bpermute_b32 v13, v52, v12
	v_mul_f32_e32 v14, 0xbfb8aa3b, v0
	v_mul_f32_e32 v15, 0xbfb8aa3b, v1
	v_exp_f32_e32 v14, v14
	v_exp_f32_e32 v15, v15
	s_waitcnt lgkmcnt(0)
	v_add_f32_e32 v13, v12, v13
	ds_bpermute_b32 v19, v18, v13
	v_add_f32_e32 v12, 1.0, v14
	v_add_f32_e32 v14, 1.0, v15
	v_mul_f32_e32 v36, 0xbfb8aa3b, v3
	v_exp_f32_e32 v36, v36
	s_waitcnt lgkmcnt(0)
	v_add_f32_e32 v13, v13, v19
	ds_bpermute_b32 v15, v53, v13
	v_mul_f32_e32 v19, 0xbfb8aa3b, v2
	v_exp_f32_e32 v19, v19
	v_pk_mul_f32 v[10:11], v[38:39], v[42:43] op_sel_hi:[1,0]
	v_pk_mul_f32 v[8:9], v[40:41], v[42:43] op_sel_hi:[1,0]
	s_waitcnt lgkmcnt(0)
	v_add_f32_e32 v15, v13, v15
	ds_bpermute_b32 v37, v54, v15
	v_rcp_f32_e32 v13, v14
	v_add_f32_e32 v14, 1.0, v19
	v_add_f32_e32 v19, 1.0, v36
	v_pk_fma_f32 v[8:9], v[20:21], v[8:9], v[24:25]
	s_waitcnt lgkmcnt(0)
	v_add_f32_e32 v15, v15, v37
	v_fmamk_f32 v5, v15, 0xbb000000, v5
	v_fmamk_f32 v47, v15, 0xbb000000, v47
	v_fmamk_f32 v7, v15, 0xbb000000, v7
	v_fmac_f32_e32 v4, 0xbb000000, v15
	v_fmamk_f32 v45, v15, 0xbb000000, v45
	v_fmac_f32_e32 v46, 0xbb000000, v15
	v_mov_b32_e32 v38, v5
	v_mov_b32_e32 v39, v47
	v_fmac_f32_e32 v6, 0xbb000000, v15
	v_fmac_f32_e32 v44, 0xbb000000, v15
	v_mov_b32_e32 v36, v4
	v_mov_b32_e32 v37, v46
	v_pk_mul_f32 v[38:39], v[38:39], v[38:39]
	v_mov_b32_e32 v40, v7
	v_mov_b32_e32 v41, v45
	v_pk_fma_f32 v[36:37], v[36:37], v[36:37], v[38:39]
	v_mov_b32_e32 v38, v6
	v_mov_b32_e32 v39, v44
	v_pk_mul_f32 v[40:41], v[40:41], v[40:41]
	v_pk_fma_f32 v[10:11], v[22:23], v[10:11], v[26:27]
	v_pk_fma_f32 v[38:39], v[38:39], v[38:39], v[40:41]
	v_rcp_f32_e32 v12, v12
	v_pk_add_f32 v[36:37], v[36:37], v[38:39]
	v_rcp_f32_e32 v14, v14
	v_add_f32_e32 v15, v36, v37
	ds_bpermute_b32 v16, v16, v15
	v_mul_f32_e32 v36, 0xbfb8aa3b, v8
	v_exp_f32_e32 v36, v36
	v_mul_f32_e32 v37, 0xbfb8aa3b, v9
	v_exp_f32_e32 v37, v37
	s_waitcnt lgkmcnt(0)
	v_add_f32_e32 v38, v15, v16
	ds_bpermute_b32 v17, v17, v38
	v_add_f32_e32 v16, 1.0, v36
	v_rcp_f32_e32 v15, v19
	v_add_f32_e32 v19, 1.0, v37
	v_mul_f32_e32 v37, 0xbfb8aa3b, v10
	s_waitcnt lgkmcnt(0)
	v_add_f32_e32 v17, v38, v17
	ds_bpermute_b32 v36, v52, v17
	v_exp_f32_e32 v37, v37
	v_mul_f32_e32 v38, 0xbfb8aa3b, v11
	v_exp_f32_e32 v38, v38
	v_pk_mul_f32 v[12:13], v[0:1], v[12:13]
	s_waitcnt lgkmcnt(0)
	v_add_f32_e32 v36, v17, v36
	ds_bpermute_b32 v39, v18, v36
	v_add_f32_e32 v18, 1.0, v37
	v_pk_mul_f32 v[0:1], v[2:3], v[14:15]
	v_rcp_f32_e32 v17, v19
	v_add_f32_e32 v19, 1.0, v38
	s_waitcnt lgkmcnt(0)
	v_add_f32_e32 v36, v36, v39
	ds_bpermute_b32 v37, v53, v36
	v_rcp_f32_e32 v16, v16
	v_rcp_f32_e32 v18, v18
	v_rcp_f32_e32 v19, v19
	v_cvt_pk_f16_f32 v1, v0, v1
	s_waitcnt lgkmcnt(0)
	v_add_f32_e32 v14, v36, v37
	ds_bpermute_b32 v15, v54, v14
	v_pk_mul_f32 v[8:9], v[8:9], v[16:17]
	v_pk_mul_f32 v[2:3], v[10:11], v[18:19]
	v_lshl_add_u64 v[10:11], v[98:99], 0, s[16:17]
	v_cvt_pk_f16_f32 v3, v2, v3
	s_waitcnt lgkmcnt(0)
	v_add_f32_e32 v0, v14, v15
	v_fmamk_f32 v0, v0, 0x3b000000, v175
	v_cvt_pk_f16_f32 v2, v8, v9
	v_rsq_f32_e32 v8, v0
	v_cvt_pk_f16_f32 v0, v12, v13
	global_store_dwordx4 v[10:11], v[0:3], off
	s_nop 1
	v_pk_mul_f32 v[0:1], v[4:5], v[8:9] op_sel_hi:[1,0]
	v_pk_mul_f32 v[2:3], v[6:7], v[8:9] op_sel_hi:[1,0]
	v_pk_mul_f32 v[4:5], v[46:47], v[8:9] op_sel_hi:[1,0]
	v_pk_mul_f32 v[6:7], v[44:45], v[8:9] op_sel_hi:[1,0]
	v_pk_fma_f32 v[2:3], v[30:31], v[2:3], v[34:35]
	v_pk_fma_f32 v[0:1], v[28:29], v[0:1], v[32:33]
	v_pk_fma_f32 v[6:7], v[22:23], v[6:7], v[26:27]
	v_pk_fma_f32 v[4:5], v[20:21], v[4:5], v[24:25]
	v_mul_f32_e32 v8, 0xbfb8aa3b, v0
	v_mul_f32_e32 v9, 0xbfb8aa3b, v1
	v_mul_f32_e32 v10, 0xbfb8aa3b, v2
	v_mul_f32_e32 v11, 0xbfb8aa3b, v3
	v_mul_f32_e32 v12, 0xbfb8aa3b, v4
	v_mul_f32_e32 v13, 0xbfb8aa3b, v5
	v_mul_f32_e32 v14, 0xbfb8aa3b, v6
	v_mul_f32_e32 v15, 0xbfb8aa3b, v7
	v_exp_f32_e32 v8, v8
	v_exp_f32_e32 v9, v9
	v_exp_f32_e32 v10, v10
	v_exp_f32_e32 v11, v11
	v_exp_f32_e32 v12, v12
	v_exp_f32_e32 v13, v13
	v_exp_f32_e32 v14, v14
	v_exp_f32_e32 v15, v15
	v_add_f32_e32 v8, 1.0, v8
	v_add_f32_e32 v9, 1.0, v9
	v_add_f32_e32 v10, 1.0, v10
	v_add_f32_e32 v11, 1.0, v11
	v_add_f32_e32 v12, 1.0, v12
	v_add_f32_e32 v13, 1.0, v13
	v_add_f32_e32 v14, 1.0, v14
	v_add_f32_e32 v15, 1.0, v15
	v_rcp_f32_e32 v8, v8
	v_rcp_f32_e32 v9, v9
	v_rcp_f32_e32 v10, v10
	v_rcp_f32_e32 v11, v11
	v_rcp_f32_e32 v12, v12
	v_rcp_f32_e32 v13, v13
	v_rcp_f32_e32 v14, v14
	v_rcp_f32_e32 v15, v15
	v_pk_mul_f32 v[8:9], v[0:1], v[8:9]
	v_pk_mul_f32 v[0:1], v[2:3], v[10:11]
	v_pk_mul_f32 v[4:5], v[4:5], v[12:13]
	v_pk_mul_f32 v[2:3], v[6:7], v[14:15]
	v_cvt_pk_f16_f32 v1, v0, v1
	v_cvt_pk_f16_f32 v3, v2, v3
	v_cvt_pk_f16_f32 v2, v4, v5
	v_cvt_pk_f16_f32 v0, v8, v9
	v_lshl_add_u64 v[4:5], v[98:99], 0, s[14:15]
	global_store_dwordx4 v[4:5], v[0:3], off
	s_cbranch_scc1 .LBB0_351

; #define PG8_STAGE(bufoff, gbase, voff) do { _Pragma("unroll") for (int _i = 0; _i < 2; ++_i) \
;         __builtin_amdgcn_global_load_lds((const unsigned*)((const char*)(gbase) + (voff)[_i]), (PG8_LAS unsigned*)(lds + (bufoff) + ldsw + _i * 8192), 16, 0, 0); } while (0)
; #define PG8_WAIT_V(n) asm volatile("s_waitcnt vmcnt(" #n ")" ::: "memory")
; #define PG8_BAR __builtin_amdgcn_s_barrier()
; template <class Epi, class Sched, bool ALIGN_EPI = false, bool SP2 = false>
; __device__ __forceinline__ void gemm_phase(PG8_LAS unsigned char* lds, const Gemm g, const Sched& S, const Epi& E, const int wid_in) {
;     ...
;     for (int i = 0; i < 2; ++i) { int R, C; stage_rc(tid * 16 + i * 8192, R, C); const int Rb = Epi::PERM ? ((R & ~31) + perm32(R & 31)) : R;
;         voffA[i] = (unsigned)(R * K + C) * 2u; voffB[i] = (unsigned)(Rb * K + C) * 2u; }
;     const size_t kstep = (size_t)(BK * 2);
;     const size_t hstep = (size_t)HALF * K * 2;
;     const size_t tstep = 2 * hstep;
;     const unsigned ldsw = (unsigned)wid * 1024u;
;     const int aoff = lds_byte(wr * 64 + fr, fq * 8), boff = lds_byte(wc * 32 + fr, fq * 8);
;     ...
;     if constexpr (SP2) {
;         PG8_STAGE(PG8_SB(0, 0), cB, voffB); PG8_STAGE(PG8_SB(0, 1), cB + hstep, voffB); PG8_STAGE(PG8_SA(0, 0), cA, voffA); PG8_STAGE(PG8_SA(0, 1), cA + hstep, voffA);
;         if (wr == 1) PG8_BAR;
;         PG8_WAIT_V(2); PG8_BAR;
;         PG8_STAGE(PG8_SB(1, 0), cB + kstep, voffB); PG8_STAGE(PG8_SA(1, 0), cA + kstep, voffA); PG8_STAGE(PG8_SB(1, 1), cB + hstep + kstep, voffB);
;         PG8_WAIT_V(6); PG8_BAR;
.LBB0_985:
	s_mov_b64 s[24:25], 0x80
	s_add_i32 m0, s85, 0x18000
	v_lshl_add_u64 v[8:9], v[8:9], 0, s[24:25]
	s_waitcnt vmcnt(2)
	s_barrier
	global_load_lds_dwordx4 v[8:9], off
	v_lshl_add_u64 v[4:5], v[4:5], 0, s[24:25]
	s_add_i32 m0, s85, 0x1a000
	s_add_i32 s52, s85, 0x8000
	global_load_lds_dwordx4 v[4:5], off
	v_lshl_add_u64 v[4:5], v[6:7], 0, s[24:25]
	s_mov_b32 m0, s52
	s_add_i32 s53, s85, 0xa000
	global_load_lds_dwordx4 v[4:5], off
	v_lshl_add_u64 v[4:5], v[10:11], 0, s[24:25]
	s_mov_b32 m0, s53
	v_lshl_add_u64 v[2:3], v[2:3], 0, s[24:25]
	global_load_lds_dwordx4 v[4:5], off
	s_add_i32 m0, s85, 0x1c000
	v_lshl_add_u64 v[0:1], v[0:1], 0, s[24:25]
	global_load_lds_dwordx4 v[2:3], off
	s_add_i32 m0, s85, 0x1e000
	s_lshr_b32 s11, s11, 26
	global_load_lds_dwordx4 v[0:1], off
	v_and_b32_e32 v0, 15, v12
	s_add_i32 s11, s10, s11
	s_ashr_i32 s54, s11, 6
	v_or_b32_e32 v144, s96, v0
	v_lshlrev_b32_e32 v3, 6, v144
	v_and_b32_e32 v4, 48, v12
	s_movk_i32 s11, 0x3c0
	s_cmp_gt_i32 s10, 63
	v_and_or_b32 v3, v3, s11, v4
	s_cselect_b64 s[10:11], -1, 0
	s_add_i32 s55, s54, -2
	s_cmpk_lt_u32 s92, 0x100
	s_cselect_b64 s[26:27], -1, 0
	s_lshl_b32 s12, s96, 2
	v_ashrrev_i32_e32 v2, 6, v12
	v_lshlrev_b32_e32 v6, 2, v144
	s_add_i32 s12, s12, 0
	v_ashrrev_i32_e32 v1, 1, v12
	v_lshl_add_u32 v5, v2, 10, s93
	v_and_b32_e32 v6, 32, v6
	v_lshl_or_b32 v4, v0, 6, v4
	v_lshlrev_b32_e32 v0, 2, v0
	s_add_i32 s12, s12, 0x20000
	v_and_b32_e32 v1, -8, v1
	v_bitop3_b32 v3, v3, v5, v6 bitop3:0xde
	v_and_b32_e32 v5, 32, v0
	v_add_u32_e32 v147, s12, v0
	v_add_u32_e32 v0, v18, v16
	v_add_u32_e32 v146, s70, v1
	v_add_lshl_u32 v0, v0, v17, 1
	v_mov_b32_e32 v1, v133
	v_lshl_add_u64 v[136:137], s[16:17], 0, v[0:1]
	v_add_u32_e32 v0, v15, v13
	v_add_lshl_u32 v2, v2, s71, 10
	s_waitcnt vmcnt(6)
	v_add_lshl_u32 v0, v0, v14, 1
	v_bitop3_b32 v145, v4, v2, v5 bitop3:0xde
	v_lshl_add_u64 v[138:139], s[16:17], 0, v[0:1]
	v_cndmask_b32_e64 v0, 0, 1, s[10:11]
	s_add_i32 s56, 0, 0x10000
	s_add_i32 s57, 0, 0x14000
	v_mov_b64_e32 v[140:141], 0x580
	v_mov_b64_e32 v[142:143], 0x57f
	v_add_u32_e32 v148, s56, v145
	v_add_u32_e32 v149, s57, v145
	v_add_u32_e32 v150, 0, v3
	s_add_i32 s58, 0, 0x24000
	s_add_i32 s59, 0, 0x24010
	s_add_i32 s60, 0, 0x24020
	s_add_i32 s61, 0, 0x24030
	s_movk_i32 s62, 0x1600
	v_cmp_ne_u32_e64 s[10:11], 1, v0
	v_mov_b32_e32 v151, 0x100
	v_mov_b32_e32 v152, 0x200
	v_mov_b32_e32 v153, 0x300
	v_mov_b32_e32 v154, 0x400
	v_mov_b32_e32 v155, 0x500
	v_mov_b32_e32 v156, 0x600
	v_mov_b32_e32 v157, 0x700
	v_mov_b32_e32 v158, 0x800
	v_mov_b32_e32 v159, 0x900
	v_mov_b32_e32 v160, 0xa00
	v_mov_b32_e32 v161, 0xb00
	v_mov_b32_e32 v162, 0xc00
	v_mov_b32_e32 v163, 0xd00
	v_mov_b32_e32 v164, 0xe00
	v_mov_b32_e32 v165, 0xf00
	s_barrier
	s_mov_b32 s101, 0
	s_branch .LBB0_988

; #define PG8_STAGE(bufoff, gbase, voff) do { _Pragma("unroll") for (int _i = 0; _i < 2; ++_i) \
;         __builtin_amdgcn_global_load_lds((const unsigned*)((const char*)(gbase) + (voff)[_i]), (PG8_LAS unsigned*)(lds + (bufoff) + ldsw + _i * 8192), 16, 0, 0); } while (0)
; #define PG8_LDA(dst, b, h) do { _Pragma("unroll") for (int m = 0; m < 4; ++m) _Pragma("unroll") for (int k = 0; k < 2; ++k) dst[m][k] = *(const PG8_LAS bf16x8*)(lds + PG8_SA(b, h) + aoff + m * 2048 + k * 1024); } while (0)
; #define PG8_LDB(dst, b, h) do { _Pragma("unroll") for (int n = 0; n < 2; ++n) _Pragma("unroll") for (int k = 0; k < 2; ++k) dst[n][k] = *(const PG8_LAS bf16x8*)(lds + PG8_SB(b, h) + boff + n * 2048 + k * 1024); } while (0)
; #define PG8_MMA(ai, bj, At, Bt) do { __builtin_amdgcn_s_setprio(1); _Pragma("unroll") for (int m = 0; m < 4; ++m) _Pragma("unroll") for (int n = 0; n < 2; ++n) _Pragma("unroll") for (int k = 0; k < 2; ++k) \
;         acc[ai][bj][m][n] = __builtin_amdgcn_mfma_f32_16x16x32_f16(Bt[n][k], At[m][k], acc[ai][bj][m][n], 0, 0, 0); __builtin_amdgcn_s_setprio(0); } while (0)
; #define PG8_WAIT_V(n) asm volatile("s_waitcnt vmcnt(" #n ")" ::: "memory")
; #define PG8_WAIT_L(n) asm volatile("s_waitcnt lgkmcnt(" #n ")" ::: "memory")
; #define PG8_BAR __builtin_amdgcn_s_barrier()
; #define PG8_SCHED __builtin_amdgcn_sched_barrier(0)
; template <class Epi, class Sched, bool ALIGN_EPI = false, bool SP2 = false>
; __device__ __forceinline__ void gemm_phase(PG8_LAS unsigned char* lds, const Gemm g, const Sched& S, const Epi& E, const int wid_in) {
;     ...
;             PG8_LDB(B0, 0, 0); PG8_LDB(B1, 0, 1); PG8_SCHED; PG8_LDA(At, 0, 0); PG8_STAGE(PG8_SA(1, 1), a1 + hstep, voffA);
;             PG8_WAIT_V(8); PG8_WAIT_L(0); PG8_BAR; PG8_MMA(0, 0, At, B0); PG8_MMA(0, 1, At, B1); PG8_BAR; PG8_SCHED;
;             PG8_LDA(At, 0, 1); PG8_STAGE(PG8_SB(0, 0), b2, voffB); PG8_STAGE(PG8_SB(0, 1), b2 + hstep, voffB); PG8_STAGE(PG8_SA(0, 0), a2, voffA);
;             PG8_WAIT_V(8); PG8_WAIT_L(0); PG8_BAR; PG8_MMA(1, 0, At, B0); PG8_MMA(1, 1, At, B1); PG8_BAR; PG8_SCHED;
.LBB0_996:
	ds_read_b128 v[166:169], v148
	ds_read_b128 v[170:173], v148 offset:1024
	ds_read_b128 v[178:181], v148 offset:2048
	ds_read_b128 v[182:185], v148 offset:3072
	ds_read_b128 v[186:189], v149
	ds_read_b128 v[190:193], v149 offset:1024
	ds_read_b128 v[194:197], v149 offset:2048
	ds_read_b128 v[198:201], v149 offset:3072
	s_add_i32 s72, s48, 2
	s_add_u32 s36, s46, 0x80
	s_addc_u32 s37, s47, 0
	s_cmp_eq_u32 s55, s48
	s_cselect_b32 s48, s14, s36
	s_cselect_b32 s49, s15, s37
	s_cselect_b32 s37, s45, s69
	s_cselect_b32 s36, s44, s67
	v_lshl_add_u64 v[234:235], s[46:47], 0, v[136:137]
	s_add_i32 m0, s85, 0xc000
	ds_read_b128 v[202:205], v150
	ds_read_b128 v[206:209], v150 offset:1024
	ds_read_b128 v[210:213], v150 offset:2048
	ds_read_b128 v[214:217], v150 offset:3072
	ds_read_b128 v[218:221], v150 offset:4096
	ds_read_b128 v[222:225], v150 offset:5120
	ds_read_b128 v[226:229], v150 offset:6144
	ds_read_b128 v[230:233], v150 offset:7168
	global_load_lds_dwordx4 v[234:235], off
	v_lshl_add_u64 v[234:235], s[46:47], 0, v[138:139]
	s_add_i32 m0, s85, 0xe000
	s_nop 0
	global_load_lds_dwordx4 v[234:235], off
	s_cmp_eq_u32 s101, 0
	s_cbranch_scc1 .Lgu_w1n
	s_waitcnt vmcnt(16)
	s_branch .Lgu_w1d
.Lgu_w1n:
	s_waitcnt vmcnt(8)
.Lgu_w1d:
	s_waitcnt lgkmcnt(0)
	s_barrier
	s_setprio 1
	s_waitcnt lgkmcnt(0)
	v_mfma_f32_16x16x32_f16 v[124:127], v[166:169], v[202:205], v[124:127]
	v_mfma_f32_16x16x32_f16 v[120:123], v[178:181], v[202:205], v[120:123]
	v_mfma_f32_16x16x32_f16 v[108:111], v[166:169], v[210:213], v[108:111]
	v_mfma_f32_16x16x32_f16 v[104:107], v[178:181], v[210:213], v[104:107]
	v_mfma_f32_16x16x32_f16 v[92:95], v[166:169], v[218:221], v[92:95]
	v_mfma_f32_16x16x32_f16 v[88:91], v[178:181], v[218:221], v[88:91]
	v_mfma_f32_16x16x32_f16 v[76:79], v[166:169], v[226:229], v[76:79]
	v_mfma_f32_16x16x32_f16 v[72:75], v[178:181], v[226:229], v[72:75]
	v_mfma_f32_16x16x32_f16 v[124:127], v[170:173], v[206:209], v[124:127]
	v_mfma_f32_16x16x32_f16 v[120:123], v[182:185], v[206:209], v[120:123]
	v_mfma_f32_16x16x32_f16 v[108:111], v[170:173], v[214:217], v[108:111]
	v_mfma_f32_16x16x32_f16 v[104:107], v[182:185], v[214:217], v[104:107]
	v_mfma_f32_16x16x32_f16 v[92:95], v[170:173], v[222:225], v[92:95]
	v_mfma_f32_16x16x32_f16 v[88:91], v[182:185], v[222:225], v[88:91]
	v_mfma_f32_16x16x32_f16 v[76:79], v[170:173], v[230:233], v[76:79]
	v_mfma_f32_16x16x32_f16 v[72:75], v[182:185], v[230:233], v[72:75]
	s_setprio 0
	s_setprio 1
	v_mfma_f32_16x16x32_f16 v[112:115], v[186:189], v[202:205], v[112:115]
	v_mfma_f32_16x16x32_f16 v[116:119], v[194:197], v[202:205], v[116:119]
	v_mfma_f32_16x16x32_f16 v[96:99], v[186:189], v[210:213], v[96:99]
	v_mfma_f32_16x16x32_f16 v[100:103], v[194:197], v[210:213], v[100:103]
	v_mfma_f32_16x16x32_f16 v[80:83], v[186:189], v[218:221], v[80:83]
	v_mfma_f32_16x16x32_f16 v[84:87], v[194:197], v[218:221], v[84:87]
	v_mfma_f32_16x16x32_f16 v[64:67], v[186:189], v[226:229], v[64:67]
	v_mfma_f32_16x16x32_f16 v[68:71], v[194:197], v[226:229], v[68:71]
	v_mfma_f32_16x16x32_f16 v[112:115], v[190:193], v[206:209], v[112:115]
	v_mfma_f32_16x16x32_f16 v[116:119], v[198:201], v[206:209], v[116:119]
	v_mfma_f32_16x16x32_f16 v[96:99], v[190:193], v[214:217], v[96:99]
	v_mfma_f32_16x16x32_f16 v[100:103], v[198:201], v[214:217], v[100:103]
	v_mfma_f32_16x16x32_f16 v[80:83], v[190:193], v[222:225], v[80:83]
	v_mfma_f32_16x16x32_f16 v[84:87], v[198:201], v[222:225], v[84:87]
	v_mfma_f32_16x16x32_f16 v[64:67], v[190:193], v[230:233], v[64:67]
	v_mfma_f32_16x16x32_f16 v[68:71], v[198:201], v[230:233], v[68:71]
	s_setprio 0
	s_barrier
	s_add_i32 s73, s56, s74
	v_lshl_add_u64 v[234:235], s[36:37], 0, v[132:133]
	s_mov_b32 m0, s73
	ds_read_b128 v[202:205], v150 offset:16384
	ds_read_b128 v[206:209], v150 offset:17408
	ds_read_b128 v[210:213], v150 offset:18432
	ds_read_b128 v[214:217], v150 offset:19456
	ds_read_b128 v[218:221], v150 offset:20480
	ds_read_b128 v[222:225], v150 offset:21504
	ds_read_b128 v[226:229], v150 offset:22528
	ds_read_b128 v[230:233], v150 offset:23552
	global_load_lds_dwordx4 v[234:235], off
	s_add_i32 m0, s73, 0x2000
	v_lshl_add_u64 v[236:237], s[36:37], 0, v[128:129]
	s_add_u32 s36, s36, s16
	s_addc_u32 s37, s37, s17
	s_add_i32 s73, s57, s74
	global_load_lds_dwordx4 v[236:237], off
	v_lshl_add_u64 v[238:239], s[36:37], 0, v[132:133]
	s_mov_b32 m0, s73
	v_lshl_add_u64 v[240:241], s[36:37], 0, v[128:129]
	global_load_lds_dwordx4 v[238:239], off
	s_add_i32 m0, s73, 0x2000
	v_lshl_add_u64 v[242:243], s[48:49], 0, v[134:135]
	global_load_lds_dwordx4 v[240:241], off
	s_mov_b32 m0, s85
	v_lshl_add_u64 v[244:245], s[48:49], 0, v[130:131]
	global_load_lds_dwordx4 v[242:243], off
	s_mov_b32 m0, s42
	s_nop 0
	global_load_lds_dwordx4 v[244:245], off
	s_cmp_eq_u32 s101, 0
	s_cbranch_scc1 .Lgu_w2n
	s_waitcnt vmcnt(16)
	s_branch .Lgu_w2d

; #define PG8_STAGE(bufoff, gbase, voff) do { _Pragma("unroll") for (int _i = 0; _i < 2; ++_i) \
;         __builtin_amdgcn_global_load_lds((const unsigned*)((const char*)(gbase) + (voff)[_i]), (PG8_LAS unsigned*)(lds + (bufoff) + ldsw + _i * 8192), 16, 0, 0); } while (0)
; #define PG8_LDA(dst, b, h) do { _Pragma("unroll") for (int m = 0; m < 4; ++m) _Pragma("unroll") for (int k = 0; k < 2; ++k) dst[m][k] = *(const PG8_LAS bf16x8*)(lds + PG8_SA(b, h) + aoff + m * 2048 + k * 1024); } while (0)
; #define PG8_LDB(dst, b, h) do { _Pragma("unroll") for (int n = 0; n < 2; ++n) _Pragma("unroll") for (int k = 0; k < 2; ++k) dst[n][k] = *(const PG8_LAS bf16x8*)(lds + PG8_SB(b, h) + boff + n * 2048 + k * 1024); } while (0)
; #define PG8_MMA(ai, bj, At, Bt) do { __builtin_amdgcn_s_setprio(1); _Pragma("unroll") for (int m = 0; m < 4; ++m) _Pragma("unroll") for (int n = 0; n < 2; ++n) _Pragma("unroll") for (int k = 0; k < 2; ++k) \
;         acc[ai][bj][m][n] = __builtin_amdgcn_mfma_f32_16x16x32_f16(Bt[n][k], At[m][k], acc[ai][bj][m][n], 0, 0, 0); __builtin_amdgcn_s_setprio(0); } while (0)
; #define PG8_WAIT_V(n) asm volatile("s_waitcnt vmcnt(" #n ")" ::: "memory")
; #define PG8_WAIT_L(n) asm volatile("s_waitcnt lgkmcnt(" #n ")" ::: "memory")
; #define PG8_BAR __builtin_amdgcn_s_barrier()
; #define PG8_SCHED __builtin_amdgcn_sched_barrier(0)
; template <class Epi, class Sched, bool ALIGN_EPI = false, bool SP2 = false>
; __device__ __forceinline__ void gemm_phase(PG8_LAS unsigned char* lds, const Gemm g, const Sched& S, const Epi& E, const int wid_in) {
;     ...
;             PG8_WAIT_V(8); PG8_WAIT_L(0); PG8_BAR; PG8_MMA(1, 0, At, B0); PG8_MMA(1, 1, At, B1); PG8_BAR; PG8_SCHED;
;             PG8_LDB(B0, 1, 0); PG8_LDB(B1, 1, 1); PG8_SCHED; PG8_LDA(At, 1, 0); PG8_STAGE(PG8_SA(0, 1), a2 + hstep, voffA);
;             PG8_WAIT_V(8); PG8_WAIT_L(0); PG8_BAR; PG8_MMA(0, 0, At, B0); PG8_MMA(0, 1, At, B1); PG8_BAR; PG8_SCHED;
.Lgu_w2d:
	s_mov_b32 s101, 0
	s_waitcnt lgkmcnt(0)
	s_barrier
	s_setprio 1
	s_waitcnt lgkmcnt(0)
	v_mfma_f32_16x16x32_f16 v[60:63], v[166:169], v[202:205], v[60:63]
	v_mfma_f32_16x16x32_f16 v[56:59], v[178:181], v[202:205], v[56:59]
	v_mfma_f32_16x16x32_f16 v[44:47], v[166:169], v[210:213], v[44:47]
	v_mfma_f32_16x16x32_f16 v[40:43], v[178:181], v[210:213], v[40:43]
	v_mfma_f32_16x16x32_f16 v[28:31], v[166:169], v[218:221], v[28:31]
	v_mfma_f32_16x16x32_f16 v[24:27], v[178:181], v[218:221], v[24:27]
	v_mfma_f32_16x16x32_f16 v[12:15], v[166:169], v[226:229], v[12:15]
	v_mfma_f32_16x16x32_f16 v[8:11], v[178:181], v[226:229], v[8:11]
	v_mfma_f32_16x16x32_f16 v[60:63], v[170:173], v[206:209], v[60:63]
	v_mfma_f32_16x16x32_f16 v[56:59], v[182:185], v[206:209], v[56:59]
	v_mfma_f32_16x16x32_f16 v[44:47], v[170:173], v[214:217], v[44:47]
	v_mfma_f32_16x16x32_f16 v[40:43], v[182:185], v[214:217], v[40:43]
	v_mfma_f32_16x16x32_f16 v[28:31], v[170:173], v[222:225], v[28:31]
	v_mfma_f32_16x16x32_f16 v[24:27], v[182:185], v[222:225], v[24:27]
	v_mfma_f32_16x16x32_f16 v[12:15], v[170:173], v[230:233], v[12:15]
	v_mfma_f32_16x16x32_f16 v[8:11], v[182:185], v[230:233], v[8:11]
	s_setprio 0
	s_setprio 1
	v_mfma_f32_16x16x32_f16 v[48:51], v[186:189], v[202:205], v[48:51]
	v_mfma_f32_16x16x32_f16 v[52:55], v[194:197], v[202:205], v[52:55]
	v_mfma_f32_16x16x32_f16 v[32:35], v[186:189], v[210:213], v[32:35]
	v_mfma_f32_16x16x32_f16 v[36:39], v[194:197], v[210:213], v[36:39]
	v_mfma_f32_16x16x32_f16 v[16:19], v[186:189], v[218:221], v[16:19]
	v_mfma_f32_16x16x32_f16 v[20:23], v[194:197], v[218:221], v[20:23]
	v_mfma_f32_16x16x32_f16 v[0:3], v[186:189], v[226:229], v[0:3]
	v_mfma_f32_16x16x32_f16 v[4:7], v[194:197], v[226:229], v[4:7]
	v_mfma_f32_16x16x32_f16 v[48:51], v[190:193], v[206:209], v[48:51]
	v_mfma_f32_16x16x32_f16 v[52:55], v[198:201], v[206:209], v[52:55]
	v_mfma_f32_16x16x32_f16 v[32:35], v[190:193], v[214:217], v[32:35]
	v_mfma_f32_16x16x32_f16 v[36:39], v[198:201], v[214:217], v[36:39]
	v_mfma_f32_16x16x32_f16 v[16:19], v[190:193], v[222:225], v[16:19]
	v_mfma_f32_16x16x32_f16 v[20:23], v[198:201], v[222:225], v[20:23]
	v_mfma_f32_16x16x32_f16 v[0:3], v[190:193], v[230:233], v[0:3]
	v_mfma_f32_16x16x32_f16 v[4:7], v[198:201], v[230:233], v[4:7]
	s_setprio 0
	s_barrier
	s_add_i32 s73, 0, 0x18000
	v_add_u32_e32 v174, s73, v145
	s_add_i32 s76, 0, 0x1c000
	ds_read_b128 v[166:169], v174
	ds_read_b128 v[170:173], v174 offset:1024
	ds_read_b128 v[178:181], v174 offset:2048
	ds_read_b128 v[182:185], v174 offset:3072
	v_add_u32_e32 v174, s76, v145
	ds_read_b128 v[186:189], v174
	ds_read_b128 v[190:193], v174 offset:1024
	ds_read_b128 v[194:197], v174 offset:2048
	ds_read_b128 v[198:201], v174 offset:3072
	s_add_u32 s36, s48, s16
	s_addc_u32 s37, s49, s17
	s_mov_b32 m0, s43
	v_lshl_add_u64 v[246:247], s[36:37], 0, v[134:135]
	ds_read_b128 v[202:205], v150 offset:32768
	ds_read_b128 v[206:209], v150 offset:33792
	ds_read_b128 v[210:213], v150 offset:34816
	ds_read_b128 v[214:217], v150 offset:35840
	ds_read_b128 v[218:221], v150 offset:36864
	ds_read_b128 v[222:225], v150 offset:37888
	ds_read_b128 v[226:229], v150 offset:38912
	ds_read_b128 v[230:233], v150 offset:39936
	global_load_lds_dwordx4 v[246:247], off
	v_lshl_add_u64 v[246:247], s[36:37], 0, v[130:131]
	s_mov_b32 m0, s50
	s_nop 0
	global_load_lds_dwordx4 v[246:247], off
	s_waitcnt vmcnt(8)
	s_waitcnt lgkmcnt(0)
	s_barrier
	s_setprio 1
	s_waitcnt lgkmcnt(0)
	v_mfma_f32_16x16x32_f16 v[124:127], v[166:169], v[202:205], v[124:127]
	v_mfma_f32_16x16x32_f16 v[120:123], v[178:181], v[202:205], v[120:123]
	v_mfma_f32_16x16x32_f16 v[108:111], v[166:169], v[210:213], v[108:111]
	v_mfma_f32_16x16x32_f16 v[104:107], v[178:181], v[210:213], v[104:107]
	v_mfma_f32_16x16x32_f16 v[92:95], v[166:169], v[218:221], v[92:95]
	v_mfma_f32_16x16x32_f16 v[88:91], v[178:181], v[218:221], v[88:91]
	v_mfma_f32_16x16x32_f16 v[76:79], v[166:169], v[226:229], v[76:79]
	v_mfma_f32_16x16x32_f16 v[72:75], v[178:181], v[226:229], v[72:75]
	v_mfma_f32_16x16x32_f16 v[124:127], v[170:173], v[206:209], v[124:127]
	v_mfma_f32_16x16x32_f16 v[120:123], v[182:185], v[206:209], v[120:123]
	v_mfma_f32_16x16x32_f16 v[108:111], v[170:173], v[214:217], v[108:111]
	v_mfma_f32_16x16x32_f16 v[104:107], v[182:185], v[214:217], v[104:107]
	v_mfma_f32_16x16x32_f16 v[92:95], v[170:173], v[222:225], v[92:95]
	v_mfma_f32_16x16x32_f16 v[88:91], v[182:185], v[222:225], v[88:91]
	v_mfma_f32_16x16x32_f16 v[76:79], v[170:173], v[230:233], v[76:79]
	v_mfma_f32_16x16x32_f16 v[72:75], v[182:185], v[230:233], v[72:75]
	s_setprio 0
	s_setprio 1
	v_mfma_f32_16x16x32_f16 v[112:115], v[186:189], v[202:205], v[112:115]
	v_mfma_f32_16x16x32_f16 v[116:119], v[194:197], v[202:205], v[116:119]
	v_mfma_f32_16x16x32_f16 v[96:99], v[186:189], v[210:213], v[96:99]
	v_mfma_f32_16x16x32_f16 v[100:103], v[194:197], v[210:213], v[100:103]
	v_mfma_f32_16x16x32_f16 v[80:83], v[186:189], v[218:221], v[80:83]
	v_mfma_f32_16x16x32_f16 v[84:87], v[194:197], v[218:221], v[84:87]
	v_mfma_f32_16x16x32_f16 v[64:67], v[186:189], v[226:229], v[64:67]
	v_mfma_f32_16x16x32_f16 v[68:71], v[194:197], v[226:229], v[68:71]
	v_mfma_f32_16x16x32_f16 v[112:115], v[190:193], v[206:209], v[112:115]
	v_mfma_f32_16x16x32_f16 v[116:119], v[198:201], v[206:209], v[116:119]
	v_mfma_f32_16x16x32_f16 v[96:99], v[190:193], v[214:217], v[96:99]
	v_mfma_f32_16x16x32_f16 v[100:103], v[198:201], v[214:217], v[100:103]
	v_mfma_f32_16x16x32_f16 v[80:83], v[190:193], v[222:225], v[80:83]
	v_mfma_f32_16x16x32_f16 v[84:87], v[198:201], v[222:225], v[84:87]
	v_mfma_f32_16x16x32_f16 v[64:67], v[190:193], v[230:233], v[64:67]
	v_mfma_f32_16x16x32_f16 v[68:71], v[198:201], v[230:233], v[68:71]
	s_setprio 0
	s_barrier
; #define PG8_STAGE(bufoff, gbase, voff) do { _Pragma("unroll") for (int _i = 0; _i < 2; ++_i) \
;         __builtin_amdgcn_global_load_lds((const unsigned*)((const char*)(gbase) + (voff)[_i]), (PG8_LAS unsigned*)(lds + (bufoff) + ldsw + _i * 8192), 16, 0, 0); } while (0)
; #define PG8_LDA(dst, b, h) do { _Pragma("unroll") for (int m = 0; m < 4; ++m) _Pragma("unroll") for (int k = 0; k < 2; ++k) dst[m][k] = *(const PG8_LAS bf16x8*)(lds + PG8_SA(b, h) + aoff + m * 2048 + k * 1024); } while (0)
; #define PG8_MMA(ai, bj, At, Bt) do { __builtin_amdgcn_s_setprio(1); _Pragma("unroll") for (int m = 0; m < 4; ++m) _Pragma("unroll") for (int n = 0; n < 2; ++n) _Pragma("unroll") for (int k = 0; k < 2; ++k) \
;         acc[ai][bj][m][n] = __builtin_amdgcn_mfma_f32_16x16x32_f16(Bt[n][k], At[m][k], acc[ai][bj][m][n], 0, 0, 0); __builtin_amdgcn_s_setprio(0); } while (0)
; #define PG8_WAIT_V(n) asm volatile("s_waitcnt vmcnt(" #n ")" ::: "memory")
; #define PG8_WAIT_L(n) asm volatile("s_waitcnt lgkmcnt(" #n ")" ::: "memory")
; #define PG8_BAR __builtin_amdgcn_s_barrier()
; #define PG8_SCHED __builtin_amdgcn_sched_barrier(0)
; template <class Epi, class Sched, bool ALIGN_EPI = false, bool SP2 = false>
; __device__ __forceinline__ void gemm_phase(PG8_LAS unsigned char* lds, const Gemm g, const Sched& S, const Epi& E, const int wid_in) {
;     ...
;             PG8_WAIT_V(8); PG8_WAIT_L(0); PG8_BAR; PG8_MMA(0, 0, At, B0); PG8_MMA(0, 1, At, B1); PG8_BAR; PG8_SCHED;
;             PG8_LDA(At, 1, 1); PG8_STAGE(PG8_SB(1, 0), b3, voffB); PG8_STAGE(PG8_SB(1, 1), b3 + hstep, voffB); PG8_STAGE(PG8_SA(1, 0), a3, voffA);
;             PG8_WAIT_V(8); PG8_WAIT_L(0); PG8_BAR; PG8_MMA(1, 0, At, B0); PG8_MMA(1, 1, At, B1); PG8_BAR; PG8_SCHED;
	s_add_i32 s36, s73, s74
	v_lshl_add_u64 v[234:235], v[234:235], 0, s[24:25]
	s_mov_b32 m0, s36
	ds_read_b128 v[202:205], v150 offset:49152
	ds_read_b128 v[206:209], v150 offset:50176
	ds_read_b128 v[210:213], v150 offset:51200
	ds_read_b128 v[214:217], v150 offset:52224
	ds_read_b128 v[218:221], v150 offset:53248
	ds_read_b128 v[222:225], v150 offset:54272
	ds_read_b128 v[226:229], v150 offset:55296
	ds_read_b128 v[230:233], v150 offset:56320
	global_load_lds_dwordx4 v[234:235], off
	v_lshl_add_u64 v[234:235], v[236:237], 0, s[24:25]
	s_add_i32 m0, s36, 0x2000
	s_add_i32 s36, s76, s74
	global_load_lds_dwordx4 v[234:235], off
	v_lshl_add_u64 v[234:235], v[238:239], 0, s[24:25]
	s_mov_b32 m0, s36
	s_nop 0
	global_load_lds_dwordx4 v[234:235], off
	v_lshl_add_u64 v[234:235], v[240:241], 0, s[24:25]
	s_add_i32 m0, s36, 0x2000
	s_nop 0
	global_load_lds_dwordx4 v[234:235], off
	v_lshl_add_u64 v[234:235], v[242:243], 0, s[24:25]
	s_mov_b32 m0, s52
	s_nop 0
	global_load_lds_dwordx4 v[234:235], off
	v_lshl_add_u64 v[234:235], v[244:245], 0, s[24:25]
	s_mov_b32 m0, s53
	s_nop 0
	global_load_lds_dwordx4 v[234:235], off
	s_waitcnt vmcnt(8)
	s_waitcnt lgkmcnt(0)
	s_barrier
	s_setprio 1
	s_waitcnt lgkmcnt(0)
	v_mfma_f32_16x16x32_f16 v[60:63], v[166:169], v[202:205], v[60:63]
	v_mfma_f32_16x16x32_f16 v[56:59], v[178:181], v[202:205], v[56:59]
	v_mfma_f32_16x16x32_f16 v[44:47], v[166:169], v[210:213], v[44:47]
	v_mfma_f32_16x16x32_f16 v[40:43], v[178:181], v[210:213], v[40:43]
	v_mfma_f32_16x16x32_f16 v[28:31], v[166:169], v[218:221], v[28:31]
	v_mfma_f32_16x16x32_f16 v[24:27], v[178:181], v[218:221], v[24:27]
	v_mfma_f32_16x16x32_f16 v[12:15], v[166:169], v[226:229], v[12:15]
	v_mfma_f32_16x16x32_f16 v[8:11], v[178:181], v[226:229], v[8:11]
	v_mfma_f32_16x16x32_f16 v[60:63], v[170:173], v[206:209], v[60:63]
	v_mfma_f32_16x16x32_f16 v[56:59], v[182:185], v[206:209], v[56:59]
	v_mfma_f32_16x16x32_f16 v[44:47], v[170:173], v[214:217], v[44:47]
	v_mfma_f32_16x16x32_f16 v[40:43], v[182:185], v[214:217], v[40:43]
	v_mfma_f32_16x16x32_f16 v[28:31], v[170:173], v[222:225], v[28:31]
	v_mfma_f32_16x16x32_f16 v[24:27], v[182:185], v[222:225], v[24:27]
	v_mfma_f32_16x16x32_f16 v[12:15], v[170:173], v[230:233], v[12:15]
	v_mfma_f32_16x16x32_f16 v[8:11], v[182:185], v[230:233], v[8:11]
	s_setprio 0
	s_setprio 1
	v_mfma_f32_16x16x32_f16 v[48:51], v[186:189], v[202:205], v[48:51]
	v_mfma_f32_16x16x32_f16 v[52:55], v[194:197], v[202:205], v[52:55]
	v_mfma_f32_16x16x32_f16 v[32:35], v[186:189], v[210:213], v[32:35]
	v_mfma_f32_16x16x32_f16 v[36:39], v[194:197], v[210:213], v[36:39]
	v_mfma_f32_16x16x32_f16 v[16:19], v[186:189], v[218:221], v[16:19]
	v_mfma_f32_16x16x32_f16 v[20:23], v[194:197], v[218:221], v[20:23]
	v_mfma_f32_16x16x32_f16 v[0:3], v[186:189], v[226:229], v[0:3]
	v_mfma_f32_16x16x32_f16 v[4:7], v[194:197], v[226:229], v[4:7]
	v_mfma_f32_16x16x32_f16 v[48:51], v[190:193], v[206:209], v[48:51]
	v_mfma_f32_16x16x32_f16 v[52:55], v[198:201], v[206:209], v[52:55]
	v_mfma_f32_16x16x32_f16 v[32:35], v[190:193], v[214:217], v[32:35]
	v_mfma_f32_16x16x32_f16 v[36:39], v[198:201], v[214:217], v[36:39]
	v_mfma_f32_16x16x32_f16 v[16:19], v[190:193], v[222:225], v[16:19]
	v_mfma_f32_16x16x32_f16 v[20:23], v[198:201], v[222:225], v[20:23]
	v_mfma_f32_16x16x32_f16 v[0:3], v[190:193], v[230:233], v[0:3]
	v_mfma_f32_16x16x32_f16 v[4:7], v[198:201], v[230:233], v[4:7]
	s_setprio 0
	s_barrier
	s_add_u32 s46, s46, 0x100
	s_addc_u32 s47, s47, 0
	s_add_u32 s67, s67, 0x100
	s_addc_u32 s69, s69, 0
	s_cmp_ge_i32 s72, s54
	s_mov_b32 s48, s72
	s_cbranch_scc0 .LBB0_996

; #define LAS __attribute__((address_space(3)))
; #define GAS __attribute__((address_space(1)))
; __device__ __forceinline__ f32x4 sigm4(f32x4 x) { f32x4 r; r[0] = sigm(x[0]); r[1] = sigm(x[1]); r[2] = sigm(x[2]); r[3] = sigm(x[3]); return r; }
;     __device__ __forceinline__ void operator()(const f32x4 (&acc)[2][2][4][2], const pg8::Unit& u, int wr, int wc, int fr, int fq) const {
;         const int row0 = u.pm * 256 + wr * 64 + fr, col0 = u.pn * 128 + 32 * wc + 8 * fq;
;         int slot = 0;
; #pragma unroll
;         for (int j = 1; j < 16; ++j) slot = (pml[j] == u.pm) ? j : slot;
;         slot = (pml[0] == u.pm) ? 0 : slot;
;         const LAS float* tb = tab + slot * 256 + wr * 64 + fr;
; #pragma unroll
;         for (int ai = 0; ai < 2; ++ai)
; #pragma unroll
;             for (int m = 0; m < 4; ++m) {
;                 const size_t row = (size_t)(row0 + ai * 128 + m * 16);
;                 const float rstd = tb[ai * 128 + m * 16];
;                 const f32x4 g0 = acc[ai][0][m][0] * rstd, g1 = acc[ai][0][m][1] * rstd, u0 = acc[ai][1][m][0] * rstd, u1 = acc[ai][1][m][1] * rstd;
;                 *(GAS h8*)(ACT + row * DFF + col0) = pack8(g0 * sigm4(g0) * u0, g1 * sigm4(g1) * u1);
;                 asm volatile("" ::: "memory");
;             }
.LBB0_999:
	s_mov_b32 s101, 1
	v_mov_b32_e32 v166, s58
	v_mov_b32_e32 v170, s59
	ds_read_b128 v[166:169], v166
	ds_read_b128 v[170:173], v170
	v_mov_b32_e32 v174, s60
	v_mov_b32_e32 v176, s61
	ds_read_b128 v[178:181], v174
	ds_read_b128 v[182:185], v176
	s_waitcnt lgkmcnt(0)
	v_cmp_eq_u32_e32 vcc, s66, v167
	s_nop 1
	v_cndmask_b32_e32 v167, 0, v151, vcc
	v_cmp_ne_u32_e32 vcc, s66, v168
	s_nop 1
	v_cndmask_b32_e32 v167, v152, v167, vcc
	v_cmp_ne_u32_e32 vcc, s66, v169
	s_nop 1
	v_cndmask_b32_e32 v167, v153, v167, vcc
	v_cmp_ne_u32_e32 vcc, s66, v170
	v_lshl_add_u32 v170, s65, 7, v146
	s_nop 0
	v_cndmask_b32_e32 v167, v154, v167, vcc
	v_cmp_ne_u32_e32 vcc, s66, v171
	v_ashrrev_i32_e32 v171, 31, v170
	s_nop 0
	v_cndmask_b32_e32 v167, v155, v167, vcc
	v_cmp_ne_u32_e32 vcc, s66, v172
	s_nop 1
	v_cndmask_b32_e32 v167, v156, v167, vcc
	v_cmp_ne_u32_e32 vcc, s66, v173
	s_nop 1
	v_cndmask_b32_e32 v167, v157, v167, vcc
	v_cmp_ne_u32_e32 vcc, s66, v178
	s_nop 1
	v_cndmask_b32_e32 v167, v158, v167, vcc
	v_cmp_ne_u32_e32 vcc, s66, v179
	s_nop 1
	v_cndmask_b32_e32 v167, v159, v167, vcc
	v_cmp_ne_u32_e32 vcc, s66, v180
	s_nop 1
	v_cndmask_b32_e32 v167, v160, v167, vcc
	v_cmp_ne_u32_e32 vcc, s66, v181
	s_nop 1
	v_cndmask_b32_e32 v167, v161, v167, vcc
	v_cmp_ne_u32_e32 vcc, s66, v182
	s_nop 1
	v_cndmask_b32_e32 v167, v162, v167, vcc
	v_cmp_ne_u32_e32 vcc, s66, v183
	s_nop 1
	v_cndmask_b32_e32 v167, v163, v167, vcc
	v_cmp_ne_u32_e32 vcc, s66, v184
	s_nop 1
	v_cndmask_b32_e32 v167, v164, v167, vcc
	v_cmp_ne_u32_e32 vcc, s66, v185
	s_nop 1
	v_cndmask_b32_e32 v167, v165, v167, vcc
	v_cmp_ne_u32_e32 vcc, s66, v166
	s_nop 1
	v_cndmask_b32_e32 v166, 0, v167, vcc
	v_lshl_add_u32 v166, v166, 2, v147
	ds_read_b32 v168, v166
	v_lshl_add_u32 v167, s66, 8, v144
	s_and_b64 vcc, exec, s[12:13]
	s_mov_b64 s[12:13], -1
	s_waitcnt lgkmcnt(0)
	v_pk_mul_f32 v[124:125], v[124:125], v[168:169] op_sel_hi:[1,0]
	v_pk_mul_f32 v[126:127], v[126:127], v[168:169] op_sel_hi:[1,0]
	v_pk_mul_f32 v[122:123], v[122:123], v[168:169] op_sel_hi:[1,0]
	v_mul_f32_e32 v169, 0xbfb8aa3b, v124
	v_exp_f32_e32 v169, v169
	v_mul_f32_e32 v172, 0xbfb8aa3b, v125
	v_exp_f32_e32 v173, v172
	v_pk_mul_f32 v[120:121], v[120:121], v[168:169] op_sel_hi:[1,0]
	v_add_f32_e32 v169, 1.0, v169
	v_rcp_f32_e32 v172, v169
	v_add_f32_e32 v169, 1.0, v173
	v_mul_f32_e32 v173, 0xbfb8aa3b, v126
	v_exp_f32_e32 v174, v173
	v_mul_f32_e32 v173, 0xbfb8aa3b, v127
	v_exp_f32_e32 v176, v173
	v_rcp_f32_e32 v173, v169
	v_add_f32_e32 v169, 1.0, v174
	v_mul_f32_e32 v174, 0xbfb8aa3b, v120
	v_rcp_f32_e32 v178, v169
	v_add_f32_e32 v169, 1.0, v176
	v_exp_f32_e32 v174, v174
	v_mul_f32_e32 v176, 0xbfb8aa3b, v121
	v_exp_f32_e32 v176, v176
	v_rcp_f32_e32 v179, v169
	v_add_f32_e32 v169, 1.0, v174
	v_mul_f32_e32 v174, 0xbfb8aa3b, v122
	v_rcp_f32_e32 v180, v169
	v_add_f32_e32 v169, 1.0, v176
	v_exp_f32_e32 v174, v174
	v_mul_f32_e32 v176, 0xbfb8aa3b, v123
	v_exp_f32_e32 v176, v176
	v_rcp_f32_e32 v181, v169
	v_add_f32_e32 v169, 1.0, v174
	v_rcp_f32_e32 v182, v169
	v_add_f32_e32 v169, 1.0, v176
	v_rcp_f32_e32 v183, v169
	v_pk_mul_f32 v[118:119], v[118:119], v[168:169] op_sel_hi:[1,0]
	v_pk_mul_f32 v[116:117], v[116:117], v[168:169] op_sel_hi:[1,0]
	v_pk_mul_f32 v[112:113], v[112:113], v[168:169] op_sel_hi:[1,0]
	v_pk_mul_f32 v[124:125], v[124:125], v[172:173]
	v_pk_mul_f32 v[122:123], v[122:123], v[182:183]
	v_pk_mul_f32 v[120:121], v[120:121], v[180:181]
	v_pk_mul_f32 v[114:115], v[114:115], v[168:169] op_sel_hi:[1,0]
	v_pk_mul_f32 v[126:127], v[126:127], v[178:179]
	v_pk_mul_f32 v[112:113], v[112:113], v[124:125]
	v_pk_mul_f32 v[116:117], v[116:117], v[120:121]
	v_pk_mul_f32 v[118:119], v[118:119], v[122:123]
	v_pk_mul_f32 v[114:115], v[114:115], v[126:127]
	v_cvt_pk_f16_f32 v119, v118, v119
	v_cvt_pk_f16_f32 v118, v116, v117
	v_cvt_pk_f16_f32 v116, v112, v113
	v_mov_b64_e32 v[112:113], s[20:21]
	v_cvt_pk_f16_f32 v117, v114, v115
	v_mad_i64_i32 v[120:121], s[36:37], v167, s62, v[112:113]
	v_lshlrev_b64 v[114:115], 1, v[170:171]
	v_lshl_add_u64 v[120:121], v[120:121], 0, v[114:115]
	global_store_dwordx4 v[120:121], v[116:119], off
	ds_read_b32 v116, v166 offset:64
	s_nop 0
	v_or_b32_e32 v117, 16, v167
	s_waitcnt lgkmcnt(0)
	v_pk_mul_f32 v[110:111], v[110:111], v[116:117] op_sel_hi:[1,0]
	v_pk_mul_f32 v[108:109], v[108:109], v[116:117] op_sel_hi:[1,0]
	v_pk_mul_f32 v[106:107], v[106:107], v[116:117] op_sel_hi:[1,0]
	v_pk_mul_f32 v[104:105], v[104:105], v[116:117] op_sel_hi:[1,0]
	v_mul_f32_e32 v118, 0xbfb8aa3b, v108
	v_mul_f32_e32 v119, 0xbfb8aa3b, v109
	v_mul_f32_e32 v120, 0xbfb8aa3b, v110
	v_mul_f32_e32 v121, 0xbfb8aa3b, v111
	v_mul_f32_e32 v122, 0xbfb8aa3b, v104
	v_mul_f32_e32 v123, 0xbfb8aa3b, v105
	v_mul_f32_e32 v124, 0xbfb8aa3b, v106
	v_mul_f32_e32 v125, 0xbfb8aa3b, v107
	v_exp_f32_e32 v118, v118
	v_exp_f32_e32 v119, v119
	v_exp_f32_e32 v120, v120
	v_exp_f32_e32 v121, v121
	v_exp_f32_e32 v122, v122
	v_exp_f32_e32 v123, v123
	v_exp_f32_e32 v124, v124
	v_exp_f32_e32 v125, v125
	v_add_f32_e32 v118, 1.0, v118
	v_add_f32_e32 v119, 1.0, v119
	v_add_f32_e32 v120, 1.0, v120
	v_add_f32_e32 v121, 1.0, v121
	v_add_f32_e32 v122, 1.0, v122
	v_add_f32_e32 v123, 1.0, v123
	v_add_f32_e32 v124, 1.0, v124
	v_add_f32_e32 v125, 1.0, v125
	v_rcp_f32_e32 v118, v118
	v_rcp_f32_e32 v119, v119
	v_rcp_f32_e32 v120, v120
	v_rcp_f32_e32 v121, v121
	v_rcp_f32_e32 v122, v122
	v_rcp_f32_e32 v123, v123
	v_rcp_f32_e32 v124, v124
	v_rcp_f32_e32 v125, v125
	v_pk_mul_f32 v[102:103], v[102:103], v[116:117] op_sel_hi:[1,0]
	v_pk_mul_f32 v[100:101], v[100:101], v[116:117] op_sel_hi:[1,0]
	v_pk_mul_f32 v[98:99], v[98:99], v[116:117] op_sel_hi:[1,0]
	v_pk_mul_f32 v[96:97], v[96:97], v[116:117] op_sel_hi:[1,0]
	v_pk_mul_f32 v[110:111], v[110:111], v[120:121]
	v_pk_mul_f32 v[108:109], v[108:109], v[118:119]
	v_pk_mul_f32 v[106:107], v[106:107], v[124:125]
	v_pk_mul_f32 v[104:105], v[104:105], v[122:123]
	v_pk_mul_f32 v[108:109], v[96:97], v[108:109]
	v_pk_mul_f32 v[96:97], v[98:99], v[110:111]
	v_pk_mul_f32 v[100:101], v[100:101], v[104:105]
	v_pk_mul_f32 v[98:99], v[102:103], v[106:107]
	v_cvt_pk_f16_f32 v97, v96, v97
	v_cvt_pk_f16_f32 v99, v98, v99
	v_cvt_pk_f16_f32 v98, v100, v101
	v_mad_i64_i32 v[100:101], s[36:37], v117, s62, v[112:113]
	v_cvt_pk_f16_f32 v96, v108, v109
	v_lshl_add_u64 v[100:101], v[100:101], 0, v[114:115]
	global_store_dwordx4 v[100:101], v[96:99], off
	ds_read_b32 v96, v166 offset:128
	s_nop 0
	v_or_b32_e32 v97, 32, v167
	s_waitcnt lgkmcnt(0)
; #define GAS __attribute__((address_space(1)))
; __device__ __forceinline__ f32x4 sigm4(f32x4 x) { f32x4 r; r[0] = sigm(x[0]); r[1] = sigm(x[1]); r[2] = sigm(x[2]); r[3] = sigm(x[3]); return r; }
;     __device__ __forceinline__ void operator()(const f32x4 (&acc)[2][2][4][2], const pg8::Unit& u, int wr, int wc, int fr, int fq) const {
;     ...
;         for (int ai = 0; ai < 2; ++ai)
; #pragma unroll
;             for (int m = 0; m < 4; ++m) {
;                 const size_t row = (size_t)(row0 + ai * 128 + m * 16);
;                 const float rstd = tb[ai * 128 + m * 16];
;                 const f32x4 g0 = acc[ai][0][m][0] * rstd, g1 = acc[ai][0][m][1] * rstd, u0 = acc[ai][1][m][0] * rstd, u1 = acc[ai][1][m][1] * rstd;
;                 *(GAS h8*)(ACT + row * DFF + col0) = pack8(g0 * sigm4(g0) * u0, g1 * sigm4(g1) * u1);
;                 asm volatile("" ::: "memory");
;             }
	v_pk_mul_f32 v[94:95], v[94:95], v[96:97] op_sel_hi:[1,0]
	v_pk_mul_f32 v[92:93], v[92:93], v[96:97] op_sel_hi:[1,0]
	v_pk_mul_f32 v[90:91], v[90:91], v[96:97] op_sel_hi:[1,0]
	v_pk_mul_f32 v[88:89], v[88:89], v[96:97] op_sel_hi:[1,0]
	v_mul_f32_e32 v98, 0xbfb8aa3b, v92
	v_mul_f32_e32 v99, 0xbfb8aa3b, v93
	v_mul_f32_e32 v100, 0xbfb8aa3b, v94
	v_mul_f32_e32 v101, 0xbfb8aa3b, v95
	v_mul_f32_e32 v102, 0xbfb8aa3b, v88
	v_mul_f32_e32 v103, 0xbfb8aa3b, v89
	v_mul_f32_e32 v104, 0xbfb8aa3b, v90
	v_mul_f32_e32 v105, 0xbfb8aa3b, v91
	v_exp_f32_e32 v98, v98
	v_exp_f32_e32 v99, v99
	v_exp_f32_e32 v100, v100
	v_exp_f32_e32 v101, v101
	v_exp_f32_e32 v102, v102
	v_exp_f32_e32 v103, v103
	v_exp_f32_e32 v104, v104
	v_exp_f32_e32 v105, v105
	v_add_f32_e32 v98, 1.0, v98
	v_add_f32_e32 v99, 1.0, v99
	v_add_f32_e32 v100, 1.0, v100
	v_add_f32_e32 v101, 1.0, v101
	v_add_f32_e32 v102, 1.0, v102
	v_add_f32_e32 v103, 1.0, v103
	v_add_f32_e32 v104, 1.0, v104
	v_add_f32_e32 v105, 1.0, v105
	v_rcp_f32_e32 v98, v98
	v_rcp_f32_e32 v99, v99
	v_rcp_f32_e32 v100, v100
	v_rcp_f32_e32 v101, v101
	v_rcp_f32_e32 v102, v102
	v_rcp_f32_e32 v103, v103
	v_rcp_f32_e32 v104, v104
	v_rcp_f32_e32 v105, v105
	v_pk_mul_f32 v[86:87], v[86:87], v[96:97] op_sel_hi:[1,0]
	v_pk_mul_f32 v[84:85], v[84:85], v[96:97] op_sel_hi:[1,0]
	v_pk_mul_f32 v[82:83], v[82:83], v[96:97] op_sel_hi:[1,0]
	v_pk_mul_f32 v[80:81], v[80:81], v[96:97] op_sel_hi:[1,0]
	v_pk_mul_f32 v[94:95], v[94:95], v[100:101]
	v_pk_mul_f32 v[92:93], v[92:93], v[98:99]
	v_pk_mul_f32 v[90:91], v[90:91], v[104:105]
	v_pk_mul_f32 v[88:89], v[88:89], v[102:103]
	v_pk_mul_f32 v[92:93], v[80:81], v[92:93]
	v_pk_mul_f32 v[80:81], v[82:83], v[94:95]
	v_pk_mul_f32 v[84:85], v[84:85], v[88:89]
	v_pk_mul_f32 v[82:83], v[86:87], v[90:91]
	v_cvt_pk_f16_f32 v81, v80, v81
	v_cvt_pk_f16_f32 v83, v82, v83
	v_cvt_pk_f16_f32 v82, v84, v85
	v_mad_i64_i32 v[84:85], s[36:37], v97, s62, v[112:113]
	v_cvt_pk_f16_f32 v80, v92, v93
	v_lshl_add_u64 v[84:85], v[84:85], 0, v[114:115]
	global_store_dwordx4 v[84:85], v[80:83], off
	ds_read_b32 v80, v166 offset:192
	s_nop 0
	v_or_b32_e32 v81, 48, v167
	s_waitcnt lgkmcnt(0)
	v_pk_mul_f32 v[78:79], v[78:79], v[80:81] op_sel_hi:[1,0]
	v_pk_mul_f32 v[76:77], v[76:77], v[80:81] op_sel_hi:[1,0]
	v_pk_mul_f32 v[74:75], v[74:75], v[80:81] op_sel_hi:[1,0]
	v_pk_mul_f32 v[72:73], v[72:73], v[80:81] op_sel_hi:[1,0]
	v_mul_f32_e32 v82, 0xbfb8aa3b, v76
	v_mul_f32_e32 v83, 0xbfb8aa3b, v77
	v_mul_f32_e32 v84, 0xbfb8aa3b, v78
	v_mul_f32_e32 v85, 0xbfb8aa3b, v79
	v_mul_f32_e32 v86, 0xbfb8aa3b, v72
	v_mul_f32_e32 v87, 0xbfb8aa3b, v73
	v_mul_f32_e32 v88, 0xbfb8aa3b, v74
	v_mul_f32_e32 v89, 0xbfb8aa3b, v75
	v_exp_f32_e32 v82, v82
	v_exp_f32_e32 v83, v83
	v_exp_f32_e32 v84, v84
	v_exp_f32_e32 v85, v85
	v_exp_f32_e32 v86, v86
	v_exp_f32_e32 v87, v87
	v_exp_f32_e32 v88, v88
	v_exp_f32_e32 v89, v89
	v_add_f32_e32 v82, 1.0, v82
	v_add_f32_e32 v83, 1.0, v83
	v_add_f32_e32 v84, 1.0, v84
	v_add_f32_e32 v85, 1.0, v85
	v_add_f32_e32 v86, 1.0, v86
	v_add_f32_e32 v87, 1.0, v87
	v_add_f32_e32 v88, 1.0, v88
	v_add_f32_e32 v89, 1.0, v89
	v_rcp_f32_e32 v82, v82
	v_rcp_f32_e32 v83, v83
	v_rcp_f32_e32 v84, v84
	v_rcp_f32_e32 v85, v85
	v_rcp_f32_e32 v86, v86
	v_rcp_f32_e32 v87, v87
	v_rcp_f32_e32 v88, v88
	v_rcp_f32_e32 v89, v89
	v_pk_mul_f32 v[70:71], v[70:71], v[80:81] op_sel_hi:[1,0]
	v_pk_mul_f32 v[68:69], v[68:69], v[80:81] op_sel_hi:[1,0]
	v_pk_mul_f32 v[66:67], v[66:67], v[80:81] op_sel_hi:[1,0]
	v_pk_mul_f32 v[64:65], v[64:65], v[80:81] op_sel_hi:[1,0]
	v_pk_mul_f32 v[78:79], v[78:79], v[84:85]
	v_pk_mul_f32 v[76:77], v[76:77], v[82:83]
	v_pk_mul_f32 v[74:75], v[74:75], v[88:89]
	v_pk_mul_f32 v[72:73], v[72:73], v[86:87]
	v_pk_mul_f32 v[76:77], v[64:65], v[76:77]
	v_pk_mul_f32 v[64:65], v[66:67], v[78:79]
	v_pk_mul_f32 v[68:69], v[68:69], v[72:73]
	v_pk_mul_f32 v[66:67], v[70:71], v[74:75]
	v_cvt_pk_f16_f32 v65, v64, v65
	v_cvt_pk_f16_f32 v67, v66, v67
	v_cvt_pk_f16_f32 v66, v68, v69
	v_mad_i64_i32 v[68:69], s[36:37], v81, s62, v[112:113]
	v_cvt_pk_f16_f32 v64, v76, v77
	v_lshl_add_u64 v[68:69], v[68:69], 0, v[114:115]
	global_store_dwordx4 v[68:69], v[64:67], off
	ds_read_b32 v64, v166 offset:512
	s_nop 0
	v_add_u32_e32 v65, 0x80, v167
	s_waitcnt lgkmcnt(0)
	v_pk_mul_f32 v[62:63], v[62:63], v[64:65] op_sel_hi:[1,0]
	v_pk_mul_f32 v[60:61], v[60:61], v[64:65] op_sel_hi:[1,0]
	v_pk_mul_f32 v[58:59], v[58:59], v[64:65] op_sel_hi:[1,0]
	v_pk_mul_f32 v[56:57], v[56:57], v[64:65] op_sel_hi:[1,0]
	v_mul_f32_e32 v66, 0xbfb8aa3b, v60
	v_mul_f32_e32 v67, 0xbfb8aa3b, v61
	v_mul_f32_e32 v68, 0xbfb8aa3b, v62
	v_mul_f32_e32 v69, 0xbfb8aa3b, v63
	v_mul_f32_e32 v70, 0xbfb8aa3b, v56
	v_mul_f32_e32 v71, 0xbfb8aa3b, v57
	v_mul_f32_e32 v72, 0xbfb8aa3b, v58
	v_mul_f32_e32 v73, 0xbfb8aa3b, v59
	v_exp_f32_e32 v66, v66
	v_exp_f32_e32 v67, v67
	v_exp_f32_e32 v68, v68
	v_exp_f32_e32 v69, v69
	v_exp_f32_e32 v70, v70
	v_exp_f32_e32 v71, v71
	v_exp_f32_e32 v72, v72
	v_exp_f32_e32 v73, v73
	v_add_f32_e32 v66, 1.0, v66
	v_add_f32_e32 v67, 1.0, v67
	v_add_f32_e32 v68, 1.0, v68
	v_add_f32_e32 v69, 1.0, v69
	v_add_f32_e32 v70, 1.0, v70
	v_add_f32_e32 v71, 1.0, v71
	v_add_f32_e32 v72, 1.0, v72
	v_add_f32_e32 v73, 1.0, v73
	v_rcp_f32_e32 v66, v66
	v_rcp_f32_e32 v67, v67
	v_rcp_f32_e32 v68, v68
	v_rcp_f32_e32 v69, v69
	v_rcp_f32_e32 v70, v70
	v_rcp_f32_e32 v71, v71
	v_rcp_f32_e32 v72, v72
	v_rcp_f32_e32 v73, v73
	v_pk_mul_f32 v[54:55], v[54:55], v[64:65] op_sel_hi:[1,0]
	v_pk_mul_f32 v[52:53], v[52:53], v[64:65] op_sel_hi:[1,0]
	v_pk_mul_f32 v[50:51], v[50:51], v[64:65] op_sel_hi:[1,0]
	v_pk_mul_f32 v[48:49], v[48:49], v[64:65] op_sel_hi:[1,0]
	v_pk_mul_f32 v[62:63], v[62:63], v[68:69]
	v_pk_mul_f32 v[60:61], v[60:61], v[66:67]
	v_pk_mul_f32 v[58:59], v[58:59], v[72:73]
	v_pk_mul_f32 v[56:57], v[56:57], v[70:71]
	v_pk_mul_f32 v[60:61], v[48:49], v[60:61]
	v_pk_mul_f32 v[48:49], v[50:51], v[62:63]
	v_pk_mul_f32 v[52:53], v[52:53], v[56:57]
	v_pk_mul_f32 v[50:51], v[54:55], v[58:59]
	v_cvt_pk_f16_f32 v49, v48, v49
	v_cvt_pk_f16_f32 v51, v50, v51
	v_cvt_pk_f16_f32 v50, v52, v53
	v_mad_i64_i32 v[52:53], s[36:37], v65, s62, v[112:113]
	v_cvt_pk_f16_f32 v48, v60, v61
	v_lshl_add_u64 v[52:53], v[52:53], 0, v[114:115]
	global_store_dwordx4 v[52:53], v[48:51], off
	ds_read_b32 v48, v166 offset:576
	s_nop 0
	v_add_u32_e32 v49, 0x90, v167
	s_waitcnt lgkmcnt(0)
; #define GAS __attribute__((address_space(1)))
; __device__ __forceinline__ f32x4 sigm4(f32x4 x) { f32x4 r; r[0] = sigm(x[0]); r[1] = sigm(x[1]); r[2] = sigm(x[2]); r[3] = sigm(x[3]); return r; }
;     __device__ __forceinline__ void operator()(const f32x4 (&acc)[2][2][4][2], const pg8::Unit& u, int wr, int wc, int fr, int fq) const {
;     ...
;         for (int ai = 0; ai < 2; ++ai)
; #pragma unroll
;             for (int m = 0; m < 4; ++m) {
;                 const size_t row = (size_t)(row0 + ai * 128 + m * 16);
;                 const float rstd = tb[ai * 128 + m * 16];
;                 const f32x4 g0 = acc[ai][0][m][0] * rstd, g1 = acc[ai][0][m][1] * rstd, u0 = acc[ai][1][m][0] * rstd, u1 = acc[ai][1][m][1] * rstd;
;                 *(GAS h8*)(ACT + row * DFF + col0) = pack8(g0 * sigm4(g0) * u0, g1 * sigm4(g1) * u1);
;                 asm volatile("" ::: "memory");
;             }
	v_pk_mul_f32 v[46:47], v[46:47], v[48:49] op_sel_hi:[1,0]
	v_pk_mul_f32 v[44:45], v[44:45], v[48:49] op_sel_hi:[1,0]
	v_pk_mul_f32 v[42:43], v[42:43], v[48:49] op_sel_hi:[1,0]
	v_pk_mul_f32 v[40:41], v[40:41], v[48:49] op_sel_hi:[1,0]
	v_mul_f32_e32 v50, 0xbfb8aa3b, v44
	v_mul_f32_e32 v51, 0xbfb8aa3b, v45
	v_mul_f32_e32 v52, 0xbfb8aa3b, v46
	v_mul_f32_e32 v53, 0xbfb8aa3b, v47
	v_mul_f32_e32 v54, 0xbfb8aa3b, v40
	v_mul_f32_e32 v55, 0xbfb8aa3b, v41
	v_mul_f32_e32 v56, 0xbfb8aa3b, v42
	v_mul_f32_e32 v57, 0xbfb8aa3b, v43
	v_exp_f32_e32 v50, v50
	v_exp_f32_e32 v51, v51
	v_exp_f32_e32 v52, v52
	v_exp_f32_e32 v53, v53
	v_exp_f32_e32 v54, v54
	v_exp_f32_e32 v55, v55
	v_exp_f32_e32 v56, v56
	v_exp_f32_e32 v57, v57
	v_add_f32_e32 v50, 1.0, v50
	v_add_f32_e32 v51, 1.0, v51
	v_add_f32_e32 v52, 1.0, v52
	v_add_f32_e32 v53, 1.0, v53
	v_add_f32_e32 v54, 1.0, v54
	v_add_f32_e32 v55, 1.0, v55
	v_add_f32_e32 v56, 1.0, v56
	v_add_f32_e32 v57, 1.0, v57
	v_rcp_f32_e32 v50, v50
	v_rcp_f32_e32 v51, v51
	v_rcp_f32_e32 v52, v52
	v_rcp_f32_e32 v53, v53
	v_rcp_f32_e32 v54, v54
	v_rcp_f32_e32 v55, v55
	v_rcp_f32_e32 v56, v56
	v_rcp_f32_e32 v57, v57
	v_pk_mul_f32 v[38:39], v[38:39], v[48:49] op_sel_hi:[1,0]
	v_pk_mul_f32 v[36:37], v[36:37], v[48:49] op_sel_hi:[1,0]
	v_pk_mul_f32 v[34:35], v[34:35], v[48:49] op_sel_hi:[1,0]
	v_pk_mul_f32 v[32:33], v[32:33], v[48:49] op_sel_hi:[1,0]
	v_pk_mul_f32 v[46:47], v[46:47], v[52:53]
	v_pk_mul_f32 v[44:45], v[44:45], v[50:51]
	v_pk_mul_f32 v[42:43], v[42:43], v[56:57]
	v_pk_mul_f32 v[40:41], v[40:41], v[54:55]
	v_pk_mul_f32 v[44:45], v[32:33], v[44:45]
	v_pk_mul_f32 v[32:33], v[34:35], v[46:47]
	v_pk_mul_f32 v[36:37], v[36:37], v[40:41]
	v_pk_mul_f32 v[34:35], v[38:39], v[42:43]
	v_cvt_pk_f16_f32 v33, v32, v33
	v_cvt_pk_f16_f32 v35, v34, v35
	v_cvt_pk_f16_f32 v34, v36, v37
	v_mad_i64_i32 v[36:37], s[36:37], v49, s62, v[112:113]
	v_cvt_pk_f16_f32 v32, v44, v45
	v_lshl_add_u64 v[36:37], v[36:37], 0, v[114:115]
	global_store_dwordx4 v[36:37], v[32:35], off
	ds_read_b32 v32, v166 offset:640
	s_nop 0
	v_add_u32_e32 v33, 0xa0, v167
	s_waitcnt lgkmcnt(0)
	v_pk_mul_f32 v[30:31], v[30:31], v[32:33] op_sel_hi:[1,0]
	v_pk_mul_f32 v[28:29], v[28:29], v[32:33] op_sel_hi:[1,0]
	v_pk_mul_f32 v[26:27], v[26:27], v[32:33] op_sel_hi:[1,0]
	v_pk_mul_f32 v[24:25], v[24:25], v[32:33] op_sel_hi:[1,0]
	v_mul_f32_e32 v34, 0xbfb8aa3b, v28
	v_mul_f32_e32 v35, 0xbfb8aa3b, v29
	v_mul_f32_e32 v36, 0xbfb8aa3b, v30
	v_mul_f32_e32 v37, 0xbfb8aa3b, v31
	v_mul_f32_e32 v38, 0xbfb8aa3b, v24
	v_mul_f32_e32 v39, 0xbfb8aa3b, v25
	v_mul_f32_e32 v40, 0xbfb8aa3b, v26
	v_mul_f32_e32 v41, 0xbfb8aa3b, v27
	v_exp_f32_e32 v34, v34
	v_exp_f32_e32 v35, v35
	v_exp_f32_e32 v36, v36
	v_exp_f32_e32 v37, v37
	v_exp_f32_e32 v38, v38
	v_exp_f32_e32 v39, v39
	v_exp_f32_e32 v40, v40
	v_exp_f32_e32 v41, v41
	v_add_f32_e32 v34, 1.0, v34
	v_add_f32_e32 v35, 1.0, v35
	v_add_f32_e32 v36, 1.0, v36
	v_add_f32_e32 v37, 1.0, v37
	v_add_f32_e32 v38, 1.0, v38
	v_add_f32_e32 v39, 1.0, v39
	v_add_f32_e32 v40, 1.0, v40
	v_add_f32_e32 v41, 1.0, v41
	v_rcp_f32_e32 v34, v34
	v_rcp_f32_e32 v35, v35
	v_rcp_f32_e32 v36, v36
	v_rcp_f32_e32 v37, v37
	v_rcp_f32_e32 v38, v38
	v_rcp_f32_e32 v39, v39
	v_rcp_f32_e32 v40, v40
	v_rcp_f32_e32 v41, v41
	v_pk_mul_f32 v[22:23], v[22:23], v[32:33] op_sel_hi:[1,0]
	v_pk_mul_f32 v[20:21], v[20:21], v[32:33] op_sel_hi:[1,0]
	v_pk_mul_f32 v[18:19], v[18:19], v[32:33] op_sel_hi:[1,0]
	v_pk_mul_f32 v[16:17], v[16:17], v[32:33] op_sel_hi:[1,0]
	v_pk_mul_f32 v[30:31], v[30:31], v[36:37]
	v_pk_mul_f32 v[28:29], v[28:29], v[34:35]
	v_pk_mul_f32 v[26:27], v[26:27], v[40:41]
	v_pk_mul_f32 v[24:25], v[24:25], v[38:39]
	v_pk_mul_f32 v[28:29], v[16:17], v[28:29]
	v_pk_mul_f32 v[16:17], v[18:19], v[30:31]
	v_pk_mul_f32 v[20:21], v[20:21], v[24:25]
	v_pk_mul_f32 v[18:19], v[22:23], v[26:27]
	v_cvt_pk_f16_f32 v17, v16, v17
	v_cvt_pk_f16_f32 v19, v18, v19
	v_cvt_pk_f16_f32 v18, v20, v21
	v_mad_i64_i32 v[20:21], s[36:37], v33, s62, v[112:113]
	v_cvt_pk_f16_f32 v16, v28, v29
	v_lshl_add_u64 v[20:21], v[20:21], 0, v[114:115]
	global_store_dwordx4 v[20:21], v[16:19], off
	ds_read_b32 v16, v166 offset:704
	s_nop 0
	v_add_u32_e32 v17, 0xb0, v167
	s_waitcnt lgkmcnt(0)
	v_pk_mul_f32 v[14:15], v[14:15], v[16:17] op_sel_hi:[1,0]
	v_pk_mul_f32 v[12:13], v[12:13], v[16:17] op_sel_hi:[1,0]
	v_pk_mul_f32 v[10:11], v[10:11], v[16:17] op_sel_hi:[1,0]
	v_pk_mul_f32 v[8:9], v[8:9], v[16:17] op_sel_hi:[1,0]
	v_mul_f32_e32 v18, 0xbfb8aa3b, v12
	v_mul_f32_e32 v19, 0xbfb8aa3b, v13
	v_mul_f32_e32 v20, 0xbfb8aa3b, v14
	v_mul_f32_e32 v21, 0xbfb8aa3b, v15
	v_mul_f32_e32 v22, 0xbfb8aa3b, v8
	v_mul_f32_e32 v23, 0xbfb8aa3b, v9
	v_mul_f32_e32 v24, 0xbfb8aa3b, v10
	v_mul_f32_e32 v25, 0xbfb8aa3b, v11
	v_exp_f32_e32 v18, v18
	v_exp_f32_e32 v19, v19
	v_exp_f32_e32 v20, v20
	v_exp_f32_e32 v21, v21
	v_exp_f32_e32 v22, v22
	v_exp_f32_e32 v23, v23
	v_exp_f32_e32 v24, v24
	v_exp_f32_e32 v25, v25
	v_add_f32_e32 v18, 1.0, v18
	v_add_f32_e32 v19, 1.0, v19
	v_add_f32_e32 v20, 1.0, v20
	v_add_f32_e32 v21, 1.0, v21
	v_add_f32_e32 v22, 1.0, v22
	v_add_f32_e32 v23, 1.0, v23
	v_add_f32_e32 v24, 1.0, v24
	v_add_f32_e32 v25, 1.0, v25
	v_rcp_f32_e32 v18, v18
	v_rcp_f32_e32 v19, v19
	v_rcp_f32_e32 v20, v20
	v_rcp_f32_e32 v21, v21
	v_rcp_f32_e32 v22, v22
	v_rcp_f32_e32 v23, v23
	v_rcp_f32_e32 v24, v24
	v_rcp_f32_e32 v25, v25
	v_pk_mul_f32 v[6:7], v[6:7], v[16:17] op_sel_hi:[1,0]
	v_pk_mul_f32 v[4:5], v[4:5], v[16:17] op_sel_hi:[1,0]
	v_pk_mul_f32 v[2:3], v[2:3], v[16:17] op_sel_hi:[1,0]
	v_pk_mul_f32 v[0:1], v[0:1], v[16:17] op_sel_hi:[1,0]
	v_pk_mul_f32 v[14:15], v[14:15], v[20:21]
	v_pk_mul_f32 v[12:13], v[12:13], v[18:19]
	v_pk_mul_f32 v[10:11], v[10:11], v[24:25]
	v_pk_mul_f32 v[8:9], v[8:9], v[22:23]
	v_pk_mul_f32 v[12:13], v[0:1], v[12:13]
	v_pk_mul_f32 v[0:1], v[2:3], v[14:15]
	v_pk_mul_f32 v[4:5], v[4:5], v[8:9]
	v_pk_mul_f32 v[2:3], v[6:7], v[10:11]
	v_cvt_pk_f16_f32 v1, v0, v1
	v_cvt_pk_f16_f32 v3, v2, v3
	v_cvt_pk_f16_f32 v2, v4, v5
	v_mad_i64_i32 v[4:5], s[36:37], v17, s62, v[112:113]
	v_cvt_pk_f16_f32 v0, v12, v13
	v_lshl_add_u64 v[4:5], v[4:5], 0, v[114:115]
	global_store_dwordx4 v[4:5], v[0:3], off
	s_cbranch_vccnz .LBB0_987
	s_andn2_b64 vcc, exec, s[22:23]
	s_cbranch_vccnz .LBB0_986
	s_barrier
	s_branch .LBB0_986
